# nt hint on the once-touched carried-state / window-cache loads and stores of the phase-3 sample units
# speedup vs baseline: 1.0189x; 1.0124x over previous
.LBB0_372:
	s_ashr_i32 s95, s94, 31
	s_and_b32 s86, s94, -4
	s_lshl_b64 s[6:7], s[94:95], 15
	s_and_b32 s26, s94, 3
	v_or_b32_e32 v150, s6, v106
	s_add_i32 s6, s86, 0x4000
	s_lshl_b32 s89, s26, 2
	s_add_u32 s24, s4, s89
	v_mov_b32_e32 v151, s7
	s_addc_u32 s25, s5, 0
	s_ashr_i32 s7, s6, 31
	s_lshl_b64 s[16:17], s[6:7], 5
	s_add_u32 s16, s24, s16
	v_lshl_add_u64 v[0:1], v[150:151], 2, s[64:65]
	s_addc_u32 s17, s25, s17
	s_add_i32 s18, s86, 0x4001
	v_lshl_add_u64 v[2:3], v[0:1], 0, v[110:111]
	s_ashr_i32 s19, s18, 31
	v_lshl_add_u64 v[4:5], v[0:1], 0, v[112:113]
	global_load_dwordx4 v[92:95], v[2:3], off nt
	global_load_dwordx4 v[88:91], v[4:5], off nt
	global_load_dword v16, v109, s[16:17] offset:16
	s_lshl_b64 s[18:19], s[18:19], 5
	s_add_u32 s18, s24, s18
	s_addc_u32 s19, s25, s19
	s_add_i32 s20, s86, 0x4002
	s_ashr_i32 s21, s20, 31
	s_lshl_b64 s[20:21], s[20:21], 5
	global_load_dword v13, v109, s[18:19] offset:16
	s_add_u32 s20, s24, s20
	s_addc_u32 s21, s25, s21
	global_load_dword v11, v109, s[20:21] offset:16
	s_add_i32 s22, s86, 0x4003
	s_ashr_i32 s23, s22, 31
	s_load_dwordx2 s[28:29], s[0:1], 0x30
	s_lshl_b64 s[22:23], s[22:23], 5
	s_add_u32 s22, s24, s22
	s_addc_u32 s23, s25, s23
	v_add_u32_e32 v8, s6, v105
	global_load_dword v7, v109, s[22:23] offset:16
	s_lshl_b64 s[24:25], s[94:95], 2
	v_ashrrev_i32_e32 v9, 31, v8
	s_waitcnt lgkmcnt(0)
	s_add_u32 s24, s28, s24
	v_lshlrev_b64 v[8:9], 11, v[8:9]
	s_addc_u32 s25, s29, s25
	v_lshl_add_u64 v[8:9], s[74:75], 0, v[8:9]
	s_lshl_b32 s78, s26, 8
	s_waitcnt vmcnt(6)
	v_add_u32_e32 v18, s6, v162
	v_add_u32_e32 v20, s6, v163
	v_lshl_add_u64 v[8:9], v[8:9], 0, s[78:79]
	s_lshl_b32 s26, s26, 9
	s_mov_b32 s27, s79
	v_ashrrev_i32_e32 v19, 31, v18
	v_ashrrev_i32_e32 v21, 31, v20
	v_lshl_add_u64 v[2:3], v[0:1], 0, v[114:115]
	v_lshl_add_u64 v[4:5], v[0:1], 0, v[116:117]
	v_lshl_add_u64 v[8:9], v[8:9], 0, v[108:109]
	v_lshl_add_u64 v[14:15], v[126:127], 0, s[26:27]
	v_lshlrev_b64 v[18:19], 12, v[18:19]
	v_lshlrev_b64 v[20:21], 12, v[20:21]
	v_lshl_add_u64 v[18:19], v[14:15], 0, v[18:19]
	v_lshl_add_u64 v[14:15], v[14:15], 0, v[20:21]
	global_load_ushort v21, v[8:9], off
	global_load_ushort v22, v[8:9], off offset:1024
	global_load_dword v12, v109, s[18:19]
	global_load_dword v17, v109, s[16:17]
	global_load_ushort v23, v[18:19], off
	global_load_ushort v24, v[14:15], off
	global_load_dwordx4 v[84:87], v[2:3], off nt
	global_load_dwordx4 v[72:75], v[4:5], off nt
	v_lshl_add_u64 v[2:3], v[0:1], 0, v[118:119]
	v_lshl_add_u64 v[4:5], v[0:1], 0, v[120:121]
	global_load_dwordx4 v[64:67], v[2:3], off nt
	global_load_dwordx4 v[56:59], v[4:5], off nt
	v_lshl_add_u64 v[2:3], v[0:1], 0, v[122:123]
	v_lshl_add_u64 v[4:5], v[0:1], 0, v[124:125]
	global_load_dwordx4 v[48:51], v[2:3], off nt
	global_load_dwordx4 v[40:43], v[4:5], off nt
	s_nop 0
	global_load_dword v4, v109, s[24:25]
	global_load_dword v5, v109, s[22:23]
	global_load_dword v8, v109, s[20:21]
	s_lshl_b64 s[16:17], s[94:95], 9
	s_add_u32 s72, s66, s16
	s_addc_u32 s73, s67, s17
	v_readlane_b32 s16, v248, 22
	v_mov_b32_e32 v103, v109
	v_readlane_b32 s17, v248, 23
	s_andn2_b64 vcc, exec, s[16:17]
	s_waitcnt vmcnt(18)
	v_mul_f32_e64 v2, |v16|, s33
	v_exp_f32_e32 v19, v2
	s_waitcnt vmcnt(17)
	v_mul_f32_e64 v2, |v13|, s33
	v_add_f32_e32 v20, 1.0, v19
	v_exp_f32_e32 v15, v2
	v_frexp_mant_f32_e32 v2, v20
	v_cmp_gt_f32_e64 s[58:59], s97, v2
	s_waitcnt vmcnt(16)
	v_mul_f32_e64 v2, |v11|, s33
	v_exp_f32_e32 v10, v2
	v_add_f32_e32 v18, 1.0, v15
	v_frexp_mant_f32_e32 v2, v18
	v_cmp_gt_f32_e64 s[48:49], s97, v2
	v_add_f32_e32 v14, 1.0, v10
	v_frexp_mant_f32_e32 v2, v14
	v_cmp_gt_f32_e64 s[38:39], s97, v2
	s_waitcnt vmcnt(15)
	v_mul_f32_e64 v2, |v7|, s33
	v_exp_f32_e32 v6, v2
	v_cmp_neq_f32_e64 s[50:51], s83, v19
	v_cmp_ngt_f32_e64 s[52:53], -1.0, v19
	v_cmp_neq_f32_e64 s[54:55], -1.0, v19
	v_add_f32_e32 v9, 1.0, v6
	v_frexp_mant_f32_e32 v2, v9
	v_cmp_gt_f32_e64 s[26:27], s97, v2
	v_cmp_lt_f32_e64 s[56:57], |v19|, s88
	v_cmp_neq_f32_e64 s[40:41], s83, v15
	v_cmp_ngt_f32_e64 s[42:43], -1.0, v15
	v_cmp_neq_f32_e64 s[44:45], -1.0, v15
	v_cmp_lt_f32_e64 s[46:47], |v15|, s88
	v_cmp_neq_f32_e64 s[28:29], s83, v10
	s_waitcnt vmcnt(14)
	v_lshlrev_b32_e32 v2, 16, v21
	s_waitcnt vmcnt(13)
	v_lshlrev_b32_e32 v3, 16, v22
	ds_write2st64_b32 v167, v2, v3 offset1:8
	v_cmp_ngt_f32_e64 s[30:31], -1.0, v10
	s_waitcnt vmcnt(10)
	v_lshlrev_b32_e32 v2, 16, v23
	s_waitcnt vmcnt(9)
	v_lshlrev_b32_e32 v3, 16, v24
	v_cmp_neq_f32_e64 s[34:35], -1.0, v10
	v_cmp_lt_f32_e64 s[36:37], |v10|, s88
	v_cmp_neq_f32_e64 s[18:19], s83, v6
	v_cmp_ngt_f32_e64 s[20:21], -1.0, v6
	v_cmp_neq_f32_e64 s[22:23], -1.0, v6
	v_cmp_lt_f32_e64 s[24:25], |v6|, s88
	ds_write2st64_b32 v167, v2, v3 offset0:16 offset1:24
	v_lshl_add_u64 v[2:3], s[72:73], 0, v[102:103]
	s_waitcnt lgkmcnt(0)
	s_barrier
	s_cbranch_vccnz .LBB0_383
	v_readlane_b32 s60, v248, 26
	v_readlane_b32 s61, v248, 27
	s_mov_b64 s[16:17], -1
	s_and_b64 vcc, exec, s[60:61]
	s_cbranch_vccz .LBB0_375
	global_load_dword v22, v[2:3], off
	global_load_dword v23, v[2:3], off offset:256
	ds_read_b32 v24, v171
	ds_read_b32 v25, v172
	s_mov_b64 s[16:17], 0
	s_waitcnt vmcnt(0) lgkmcnt(0)
	v_pk_mul_f32 v[22:23], v[22:23], v[24:25]
	s_nop 0
	v_add_f32_e32 v21, v22, v23

.LBB0_405:
	v_max_f32_e32 v2, v16, v16
	v_min_f32_e32 v16, 0, v2
	v_add_f32_e32 v2, -1.0, v20
	s_waitcnt lgkmcnt(0)
	v_sub_f32_e32 v3, v2, v20
	v_add_f32_e32 v3, 1.0, v3
	v_sub_f32_e32 v2, v19, v2
	v_add_f32_e32 v21, v2, v3
	v_cvt_f64_f32_e32 v[2:3], v20
	v_frexp_exp_i32_f64_e32 v2, v[2:3]
	v_subbrev_co_u32_e64 v2, vcc, 0, v2, s[58:59]
	v_sub_u32_e32 v3, 0, v2
	v_ldexp_f32 v20, v20, v3
	v_ldexp_f32 v3, v21, v3
	v_add_f32_e32 v21, -1.0, v20
	v_add_f32_e32 v24, 1.0, v20
	v_add_f32_e32 v22, 1.0, v21
	v_add_f32_e32 v25, -1.0, v24
	v_sub_f32_e32 v22, v20, v22
	v_sub_f32_e32 v20, v20, v25
	v_add_f32_e32 v22, v3, v22
	v_add_f32_e32 v3, v3, v20
	v_add_f32_e32 v20, v24, v3
	v_rcp_f32_e32 v25, v20
	v_add_f32_e32 v23, v21, v22
	v_sub_f32_e32 v21, v23, v21
	v_sub_f32_e32 v21, v22, v21
	v_sub_f32_e32 v22, v20, v24
	v_sub_f32_e32 v3, v3, v22
	v_mul_f32_e32 v22, v23, v25
	v_mul_f32_e32 v24, v20, v22
	v_fma_f32 v26, v22, v20, -v24
	v_fmac_f32_e32 v26, v22, v3
	v_add_f32_e32 v27, v24, v26
	v_sub_f32_e32 v28, v23, v27
	v_sub_f32_e32 v23, v23, v28
	v_sub_f32_e32 v24, v27, v24
	v_sub_f32_e32 v23, v23, v27
	v_add_f32_e32 v21, v21, v23
	v_sub_f32_e32 v23, v24, v26
	v_add_f32_e32 v21, v23, v21
	v_add_f32_e32 v23, v28, v21
	v_mul_f32_e32 v24, v25, v23
	v_mul_f32_e32 v26, v20, v24
	v_fma_f32 v20, v24, v20, -v26
	v_fmac_f32_e32 v20, v24, v3
	v_sub_f32_e32 v3, v28, v23
	v_add_f32_e32 v3, v21, v3
	v_add_f32_e32 v21, v26, v20
	v_sub_f32_e32 v27, v23, v21
	v_sub_f32_e32 v23, v23, v27
	v_sub_f32_e32 v26, v21, v26
	v_sub_f32_e32 v21, v23, v21
	v_add_f32_e32 v3, v3, v21
	v_sub_f32_e32 v20, v26, v20
	v_cvt_f32_i32_e32 v2, v2
	v_add_f32_e32 v3, v20, v3
	v_add_f32_e32 v20, v22, v24
	v_add_f32_e32 v3, v27, v3
	v_sub_f32_e32 v21, v20, v22
	v_mul_f32_e32 v3, v25, v3
	v_sub_f32_e32 v21, v24, v21
	v_add_f32_e32 v3, v21, v3
	v_mul_f32_e32 v24, 0x3f317218, v2
	v_add_f32_e32 v21, v20, v3
	v_fma_f32 v25, v2, s82, -v24
	v_mul_f32_e32 v22, v21, v21
	v_fmac_f32_e32 v25, 0xb102e308, v2
	v_sub_f32_e32 v2, v21, v20
	v_fmamk_f32 v23, v22, 0x3e9b6dac, v183
	v_sub_f32_e32 v2, v3, v2
	v_add_f32_e32 v3, v24, v25
	v_fmaak_f32 v23, v22, v23, 0x3f2aaada
	v_sub_f32_e32 v20, v3, v24
	v_ldexp_f32 v24, v21, 1
	v_mul_f32_e32 v21, v21, v22
	v_mul_f32_e32 v21, v21, v23
	v_add_f32_e32 v22, v24, v21
	v_sub_f32_e32 v23, v22, v24
	v_ldexp_f32 v2, v2, 1
	v_sub_f32_e32 v21, v21, v23
	v_add_f32_e32 v2, v2, v21
	v_add_f32_e32 v21, v22, v2
	v_sub_f32_e32 v22, v21, v22
	v_sub_f32_e32 v2, v2, v22
	v_add_f32_e32 v22, v3, v21
	v_sub_f32_e32 v23, v22, v3
	v_sub_f32_e32 v24, v22, v23
	v_sub_f32_e32 v20, v25, v20
	v_sub_f32_e32 v3, v3, v24
	v_sub_f32_e32 v21, v21, v23
	v_add_f32_e32 v3, v21, v3
	v_add_f32_e32 v21, v20, v2
	v_sub_f32_e32 v23, v21, v20
	v_sub_f32_e32 v24, v21, v23
	v_sub_f32_e32 v20, v20, v24
	v_sub_f32_e32 v2, v2, v23
	v_add_f32_e32 v3, v21, v3
	v_add_f32_e32 v2, v2, v20
	v_add_f32_e32 v20, v22, v3
	v_sub_f32_e32 v21, v20, v22
	v_sub_f32_e32 v3, v3, v21
	v_add_f32_e32 v2, v2, v3
	v_add_f32_e32 v2, v20, v2
	v_cndmask_b32_e64 v2, v187, v2, s[50:51]
	v_cndmask_b32_e64 v2, v188, v2, s[52:53]
	v_cndmask_b32_e64 v2, v189, v2, s[54:55]
	v_cndmask_b32_e64 v2, v2, v19, s[56:57]
	v_sub_f32_e32 v2, v16, v2
	v_add_f32_e32 v16, 0, v2
	v_max_f32_e32 v2, v13, v13
	v_min_f32_e32 v13, 0, v2
	v_add_f32_e32 v2, -1.0, v18
	v_sub_f32_e32 v3, v2, v18
	v_add_f32_e32 v3, 1.0, v3
	v_sub_f32_e32 v2, v15, v2
	v_add_f32_e32 v20, v2, v3
	v_cvt_f64_f32_e32 v[2:3], v18
	v_frexp_exp_i32_f64_e32 v2, v[2:3]
	v_subbrev_co_u32_e64 v2, vcc, 0, v2, s[48:49]
	v_sub_u32_e32 v3, 0, v2
	v_ldexp_f32 v18, v18, v3
	v_ldexp_f32 v3, v20, v3
	v_add_f32_e32 v20, -1.0, v18
	v_add_f32_e32 v23, 1.0, v18
	v_add_f32_e32 v21, 1.0, v20
	v_add_f32_e32 v24, -1.0, v23
	v_sub_f32_e32 v21, v18, v21
	v_sub_f32_e32 v18, v18, v24
	v_add_f32_e32 v21, v3, v21
	v_add_f32_e32 v3, v3, v18
	v_add_f32_e32 v18, v23, v3
	v_rcp_f32_e32 v24, v18
	v_add_f32_e32 v22, v20, v21
	v_sub_f32_e32 v20, v22, v20
	v_sub_f32_e32 v20, v21, v20
	v_sub_f32_e32 v21, v18, v23
	v_sub_f32_e32 v3, v3, v21
	v_mul_f32_e32 v21, v22, v24
	v_mul_f32_e32 v23, v18, v21
	v_fma_f32 v25, v21, v18, -v23
	v_fmac_f32_e32 v25, v21, v3
	v_add_f32_e32 v26, v23, v25
	v_sub_f32_e32 v27, v22, v26
	v_sub_f32_e32 v22, v22, v27
	v_sub_f32_e32 v23, v26, v23
	v_sub_f32_e32 v22, v22, v26
	v_add_f32_e32 v20, v20, v22
	v_sub_f32_e32 v22, v23, v25
	v_add_f32_e32 v20, v22, v20
	v_add_f32_e32 v22, v27, v20
	v_mul_f32_e32 v23, v24, v22
	v_mul_f32_e32 v25, v18, v23
	v_fma_f32 v18, v23, v18, -v25
	v_fmac_f32_e32 v18, v23, v3
	v_sub_f32_e32 v3, v27, v22
	v_add_f32_e32 v3, v20, v3
	v_add_f32_e32 v20, v25, v18
	v_sub_f32_e32 v26, v22, v20
	v_sub_f32_e32 v22, v22, v26
	v_sub_f32_e32 v25, v20, v25
	v_sub_f32_e32 v20, v22, v20
	v_add_f32_e32 v3, v3, v20
	v_sub_f32_e32 v18, v25, v18
	v_cvt_f32_i32_e32 v2, v2
	v_add_f32_e32 v3, v18, v3
	v_add_f32_e32 v18, v21, v23
	v_add_f32_e32 v3, v26, v3
	v_sub_f32_e32 v20, v18, v21
	v_mul_f32_e32 v3, v24, v3
	v_sub_f32_e32 v20, v23, v20
	v_add_f32_e32 v3, v20, v3
	v_mul_f32_e32 v23, 0x3f317218, v2
	v_add_f32_e32 v20, v18, v3
	v_fma_f32 v24, v2, s82, -v23
	v_mul_f32_e32 v21, v20, v20
	v_fmac_f32_e32 v24, 0xb102e308, v2
	v_sub_f32_e32 v2, v20, v18
	v_fmamk_f32 v22, v21, 0x3e9b6dac, v183
	v_sub_f32_e32 v2, v3, v2
	v_add_f32_e32 v3, v23, v24
	v_fmaak_f32 v22, v21, v22, 0x3f2aaada
	v_sub_f32_e32 v18, v3, v23
	v_ldexp_f32 v23, v20, 1
	v_mul_f32_e32 v20, v20, v21
	v_mul_f32_e32 v20, v20, v22
	v_add_f32_e32 v21, v23, v20
	v_sub_f32_e32 v22, v21, v23
	v_ldexp_f32 v2, v2, 1
	v_sub_f32_e32 v20, v20, v22
	v_add_f32_e32 v2, v2, v20
	v_add_f32_e32 v20, v21, v2
	v_sub_f32_e32 v21, v20, v21
	v_sub_f32_e32 v2, v2, v21
	v_add_f32_e32 v21, v3, v20
	v_sub_f32_e32 v22, v21, v3
	v_sub_f32_e32 v23, v21, v22
	v_sub_f32_e32 v18, v24, v18
	v_sub_f32_e32 v3, v3, v23
	v_sub_f32_e32 v20, v20, v22
	v_add_f32_e32 v3, v20, v3
	v_add_f32_e32 v20, v18, v2
	v_sub_f32_e32 v22, v20, v18
	v_sub_f32_e32 v23, v20, v22
	v_sub_f32_e32 v18, v18, v23
	v_sub_f32_e32 v2, v2, v22
	v_add_f32_e32 v3, v20, v3
	v_add_f32_e32 v2, v2, v18
	v_add_f32_e32 v18, v21, v3
	v_sub_f32_e32 v20, v18, v21
	v_sub_f32_e32 v3, v3, v20
	v_add_f32_e32 v2, v2, v3
	v_add_f32_e32 v2, v18, v2
	v_cndmask_b32_e64 v2, v187, v2, s[40:41]
	v_cndmask_b32_e64 v2, v188, v2, s[42:43]
	v_cndmask_b32_e64 v2, v189, v2, s[44:45]
	v_cndmask_b32_e64 v2, v2, v15, s[46:47]
	v_sub_f32_e32 v2, v13, v2
	v_add_f32_e32 v13, v16, v2
	v_max_f32_e32 v2, v11, v11
	v_min_f32_e32 v11, 0, v2
	v_add_f32_e32 v2, -1.0, v14
	v_sub_f32_e32 v3, v2, v14
	v_add_f32_e32 v3, 1.0, v3
	v_sub_f32_e32 v2, v10, v2
	v_add_f32_e32 v15, v2, v3
	v_cvt_f64_f32_e32 v[2:3], v14
	v_frexp_exp_i32_f64_e32 v2, v[2:3]
	v_subbrev_co_u32_e64 v2, vcc, 0, v2, s[38:39]
	v_sub_u32_e32 v3, 0, v2
	v_ldexp_f32 v14, v14, v3
	v_ldexp_f32 v3, v15, v3
	v_add_f32_e32 v15, -1.0, v14
	v_add_f32_e32 v22, 1.0, v14
	v_add_f32_e32 v20, 1.0, v15
	v_add_f32_e32 v23, -1.0, v22
	v_sub_f32_e32 v20, v14, v20
	v_sub_f32_e32 v14, v14, v23
	v_add_f32_e32 v20, v3, v20
	v_add_f32_e32 v3, v3, v14
	v_add_f32_e32 v14, v22, v3
	v_rcp_f32_e32 v23, v14
	v_add_f32_e32 v21, v15, v20
	v_sub_f32_e32 v15, v21, v15
	v_sub_f32_e32 v15, v20, v15
	v_sub_f32_e32 v20, v14, v22
	v_sub_f32_e32 v3, v3, v20
	v_mul_f32_e32 v20, v21, v23
	v_mul_f32_e32 v22, v14, v20
	v_fma_f32 v24, v20, v14, -v22
	v_fmac_f32_e32 v24, v20, v3
	v_add_f32_e32 v25, v22, v24
	v_sub_f32_e32 v26, v21, v25
	v_sub_f32_e32 v21, v21, v26
	v_sub_f32_e32 v22, v25, v22
	v_sub_f32_e32 v21, v21, v25
	v_add_f32_e32 v15, v15, v21
	v_sub_f32_e32 v21, v22, v24
	v_add_f32_e32 v15, v21, v15
	v_add_f32_e32 v21, v26, v15
	v_mul_f32_e32 v22, v23, v21
	v_mul_f32_e32 v24, v14, v22
	v_fma_f32 v14, v22, v14, -v24
	v_fmac_f32_e32 v14, v22, v3
	v_sub_f32_e32 v3, v26, v21
	v_add_f32_e32 v3, v15, v3
	v_add_f32_e32 v15, v24, v14
	v_sub_f32_e32 v25, v21, v15
	v_sub_f32_e32 v21, v21, v25
	v_sub_f32_e32 v24, v15, v24
	v_sub_f32_e32 v15, v21, v15
	v_add_f32_e32 v3, v3, v15
	v_sub_f32_e32 v14, v24, v14
	v_cvt_f32_i32_e32 v2, v2
	v_add_f32_e32 v3, v14, v3
	v_add_f32_e32 v14, v20, v22
	v_add_f32_e32 v3, v25, v3
	v_sub_f32_e32 v15, v14, v20
	v_mul_f32_e32 v3, v23, v3
	v_sub_f32_e32 v15, v22, v15
	v_add_f32_e32 v3, v15, v3
	v_mul_f32_e32 v22, 0x3f317218, v2
	v_add_f32_e32 v15, v14, v3
	v_fma_f32 v23, v2, s82, -v22
	v_mul_f32_e32 v20, v15, v15
	v_fmac_f32_e32 v23, 0xb102e308, v2
	v_sub_f32_e32 v2, v15, v14
	v_fmamk_f32 v21, v20, 0x3e9b6dac, v183
	v_sub_f32_e32 v2, v3, v2
	v_add_f32_e32 v3, v22, v23
	v_fmaak_f32 v21, v20, v21, 0x3f2aaada
	v_sub_f32_e32 v14, v3, v22
	v_ldexp_f32 v22, v15, 1
	v_mul_f32_e32 v15, v15, v20
	v_mul_f32_e32 v15, v15, v21
	v_add_f32_e32 v20, v22, v15
	v_sub_f32_e32 v21, v20, v22
	v_ldexp_f32 v2, v2, 1
	v_sub_f32_e32 v15, v15, v21
	v_add_f32_e32 v2, v2, v15
	v_add_f32_e32 v15, v20, v2
	v_sub_f32_e32 v20, v15, v20
	v_sub_f32_e32 v2, v2, v20
	v_add_f32_e32 v20, v3, v15
	v_sub_f32_e32 v21, v20, v3
	v_sub_f32_e32 v22, v20, v21
	v_sub_f32_e32 v14, v23, v14
	v_sub_f32_e32 v3, v3, v22
	v_sub_f32_e32 v15, v15, v21
	v_add_f32_e32 v3, v15, v3
	v_add_f32_e32 v15, v14, v2
	v_sub_f32_e32 v21, v15, v14
	v_sub_f32_e32 v22, v15, v21
	v_sub_f32_e32 v14, v14, v22
	v_sub_f32_e32 v2, v2, v21
	v_add_f32_e32 v3, v15, v3
	v_add_f32_e32 v2, v2, v14
	v_add_f32_e32 v14, v20, v3
	v_sub_f32_e32 v15, v14, v20
	v_sub_f32_e32 v3, v3, v15
	v_add_f32_e32 v2, v2, v3
	v_add_f32_e32 v2, v14, v2
	v_cndmask_b32_e64 v2, v187, v2, s[28:29]
	v_cndmask_b32_e64 v2, v188, v2, s[30:31]
	v_cndmask_b32_e64 v2, v189, v2, s[34:35]
	v_cndmask_b32_e64 v2, v2, v10, s[36:37]
	v_sub_f32_e32 v2, v11, v2
	v_add_f32_e32 v10, v13, v2
	v_max_f32_e32 v2, v7, v7
	v_min_f32_e32 v7, 0, v2
	v_add_f32_e32 v2, -1.0, v9
	v_sub_f32_e32 v3, v2, v9
	v_add_f32_e32 v3, 1.0, v3
	v_sub_f32_e32 v2, v6, v2
	v_add_f32_e32 v11, v2, v3
	v_cvt_f64_f32_e32 v[2:3], v9
	v_frexp_exp_i32_f64_e32 v2, v[2:3]
	v_subbrev_co_u32_e64 v2, vcc, 0, v2, s[26:27]
	v_sub_u32_e32 v3, 0, v2
	v_ldexp_f32 v9, v9, v3
	v_ldexp_f32 v3, v11, v3
	v_add_f32_e32 v11, -1.0, v9
	v_add_f32_e32 v21, 1.0, v9
	v_add_f32_e32 v14, 1.0, v11
	v_add_f32_e32 v22, -1.0, v21
	v_sub_f32_e32 v14, v9, v14
	v_sub_f32_e32 v9, v9, v22
	v_add_f32_e32 v14, v3, v14
	v_add_f32_e32 v3, v3, v9
	v_add_f32_e32 v9, v21, v3
	v_rcp_f32_e32 v22, v9
	v_add_f32_e32 v15, v11, v14
	v_sub_f32_e32 v11, v15, v11
	v_sub_f32_e32 v11, v14, v11
	v_sub_f32_e32 v14, v9, v21
	v_sub_f32_e32 v3, v3, v14
	v_mul_f32_e32 v14, v15, v22
	v_mul_f32_e32 v21, v9, v14
	v_fma_f32 v23, v14, v9, -v21
	v_fmac_f32_e32 v23, v14, v3
	v_add_f32_e32 v24, v21, v23
	v_sub_f32_e32 v25, v15, v24
	v_sub_f32_e32 v15, v15, v25
	v_sub_f32_e32 v21, v24, v21
	v_sub_f32_e32 v15, v15, v24
	v_add_f32_e32 v11, v11, v15
	v_sub_f32_e32 v15, v21, v23
	v_add_f32_e32 v11, v15, v11
	v_add_f32_e32 v15, v25, v11
	v_mul_f32_e32 v21, v22, v15
	v_mul_f32_e32 v23, v9, v21
	v_fma_f32 v9, v21, v9, -v23
	v_fmac_f32_e32 v9, v21, v3
	v_sub_f32_e32 v3, v25, v15
	v_add_f32_e32 v3, v11, v3
	v_add_f32_e32 v11, v23, v9
	v_sub_f32_e32 v24, v15, v11
	v_sub_f32_e32 v15, v15, v24
	v_sub_f32_e32 v23, v11, v23
	v_sub_f32_e32 v11, v15, v11
	v_add_f32_e32 v3, v3, v11
	v_sub_f32_e32 v9, v23, v9
	v_cvt_f32_i32_e32 v2, v2
	v_add_f32_e32 v3, v9, v3
	v_add_f32_e32 v9, v14, v21
	v_add_f32_e32 v3, v24, v3
	v_sub_f32_e32 v11, v9, v14
	v_mul_f32_e32 v3, v22, v3
	v_sub_f32_e32 v11, v21, v11
	v_add_f32_e32 v3, v11, v3
	v_mul_f32_e32 v21, 0x3f317218, v2
	v_add_f32_e32 v11, v9, v3
	v_fma_f32 v22, v2, s82, -v21
	v_mul_f32_e32 v14, v11, v11
	v_fmac_f32_e32 v22, 0xb102e308, v2
	v_sub_f32_e32 v2, v11, v9
	v_fmamk_f32 v15, v14, 0x3e9b6dac, v183
	v_sub_f32_e32 v2, v3, v2
	v_add_f32_e32 v3, v21, v22
	v_fmaak_f32 v15, v14, v15, 0x3f2aaada
	v_sub_f32_e32 v9, v3, v21
	v_ldexp_f32 v21, v11, 1
	v_mul_f32_e32 v11, v11, v14
	v_mul_f32_e32 v11, v11, v15
	v_add_f32_e32 v14, v21, v11
	v_sub_f32_e32 v15, v14, v21
	v_ldexp_f32 v2, v2, 1
	v_sub_f32_e32 v11, v11, v15
	v_add_f32_e32 v2, v2, v11
	v_add_f32_e32 v11, v14, v2
	v_sub_f32_e32 v14, v11, v14
	v_sub_f32_e32 v2, v2, v14
	v_add_f32_e32 v14, v3, v11
	v_sub_f32_e32 v15, v14, v3
	v_sub_f32_e32 v21, v14, v15
	v_sub_f32_e32 v9, v22, v9
	v_sub_f32_e32 v3, v3, v21
	v_sub_f32_e32 v11, v11, v15
	v_add_f32_e32 v3, v11, v3
	v_add_f32_e32 v11, v9, v2
	v_sub_f32_e32 v15, v11, v9
	v_sub_f32_e32 v21, v11, v15
	v_sub_f32_e32 v9, v9, v21
	v_sub_f32_e32 v2, v2, v15
	v_add_f32_e32 v3, v11, v3
	v_add_f32_e32 v2, v2, v9
	v_add_f32_e32 v9, v14, v3
	v_sub_f32_e32 v11, v9, v14
	v_sub_f32_e32 v3, v3, v11
	v_add_f32_e32 v2, v2, v3
	v_add_f32_e32 v2, v9, v2
	v_cndmask_b32_e64 v2, v187, v2, s[18:19]
	v_sub_f32_e32 v17, v17, v16
	v_cndmask_b32_e64 v2, v188, v2, s[20:21]
	v_max_f32_e32 v19, 0xff800000, v17
	v_sub_f32_e32 v18, v12, v13
	v_cndmask_b32_e64 v2, v189, v2, s[22:23]
	v_max_f32_e32 v12, v19, v18
	s_waitcnt vmcnt(0)
	v_sub_f32_e32 v20, v8, v10
	v_cndmask_b32_e64 v2, v2, v6, s[24:25]
	v_max_f32_e32 v8, v12, v20
	v_sub_f32_e32 v2, v7, v2
	v_max_f32_e32 v3, v4, v4
	v_add_f32_e32 v2, v10, v2
	v_max_f32_e32 v21, v3, v8
	v_sub_f32_e32 v11, v5, v2
	v_max_f32_e32 v5, v3, v19
	v_max_f32_e32 v19, v3, v12
	v_sub_f32_e32 v3, v4, v21
	v_mul_f32_e32 v3, 0x3fb8aa3b, v3
	v_exp_f32_e32 v190, v3
	v_add_f32_e32 v3, v10, v21
	v_max3_f32 v10, v4, v8, v11
	v_add_f32_e32 v103, v2, v10
	v_mul_f32_e32 v2, 0xbfb8aa3b, v103
	v_sub_f32_e32 v6, v4, v5
	v_exp_f32_e32 v23, v2
	v_sub_f32_e32 v2, v17, v10
	v_mul_f32_e32 v6, 0x3fb8aa3b, v6
	v_mul_f32_e32 v2, 0x3fb8aa3b, v2
	v_exp_f32_e32 v194, v6
	v_add_f32_e32 v6, v16, v5
	v_exp_f32_e32 v146, v2
	v_sub_f32_e32 v2, v18, v10
	v_mul_f32_e32 v6, 0xbfb8aa3b, v6
	v_mul_f32_e32 v2, 0x3fb8aa3b, v2
	v_exp_f32_e32 v16, v6
	v_sub_f32_e32 v6, v4, v19
	v_exp_f32_e32 v147, v2
	v_sub_f32_e32 v2, v20, v10
	v_mul_f32_e32 v6, 0x3fb8aa3b, v6
	v_mul_f32_e32 v3, 0xbfb8aa3b, v3
	v_mul_f32_e32 v2, 0x3fb8aa3b, v2
	v_exp_f32_e32 v191, v6
	v_add_f32_e32 v6, v13, v19
	v_exp_f32_e32 v22, v3
	v_sub_f32_e32 v3, v4, v10
	v_exp_f32_e32 v148, v2
	v_sub_f32_e32 v2, v17, v5
	v_mul_f32_e32 v6, 0xbfb8aa3b, v6
	v_mul_f32_e32 v3, 0x3fb8aa3b, v3
	v_mul_f32_e32 v2, 0x3fb8aa3b, v2
	v_exp_f32_e32 v13, v6
	v_exp_f32_e32 v144, v3
	s_barrier
	v_exp_f32_e32 v24, v2
	ds_read_b32 v25, v109 offset:8192
	ds_read_b128 v[2:5], v109 offset:8240
	ds_read_b128 v[6:9], v109 offset:8256
	v_sub_f32_e32 v26, v11, v10
	v_mul_f32_e32 v26, 0x3fb8aa3b, v26
	s_waitcnt lgkmcnt(2)
	v_fma_f32 v27, v24, v25, 0
	v_mul_f32_e32 v195, v24, v25
	s_waitcnt lgkmcnt(0)
	v_fmac_f32_e32 v27, v194, v6
	v_max_f32_e32 v6, v16, v16
	v_max_f32_e64 v6, |v27|, v6
	v_div_scale_f32 v16, s[18:19], v6, v6, 1.0
	v_rcp_f32_e32 v27, v16
	v_exp_f32_e32 v149, v26
	ds_read_b64 v[14:15], v109 offset:8208
	ds_read_b96 v[10:12], v109 offset:8224
	v_mul_f32_e32 v203, v146, v2
	v_fma_f32 v24, -v16, v27, 1.0
	v_fmac_f32_e32 v27, v24, v27
	v_div_scale_f32 v24, vcc, 1.0, v6, 1.0
	v_mul_f32_e32 v25, v24, v27
	v_fma_f32 v26, -v16, v25, v24
	v_fmac_f32_e32 v25, v26, v27
	v_fma_f32 v16, -v16, v25, v24
	v_sub_f32_e32 v24, v17, v19
	v_mul_f32_e32 v24, 0x3fb8aa3b, v24
	v_sub_f32_e32 v19, v18, v19
	v_exp_f32_e32 v24, v24
	v_mul_f32_e32 v19, 0x3fb8aa3b, v19
	v_exp_f32_e32 v19, v19
	v_div_fmas_f32 v16, v16, v27, v25
	s_waitcnt lgkmcnt(1)
	v_fma_f32 v25, v24, v14, 0
	v_div_fixup_f32 v198, v16, v6, 1.0
	v_fmac_f32_e32 v25, v19, v15
	v_fmac_f32_e32 v25, v191, v7
	v_max_f32_e32 v7, v13, v13
	v_max_f32_e64 v7, |v25|, v7
	v_div_scale_f32 v13, s[18:19], v7, v7, 1.0
	v_rcp_f32_e32 v25, v13
	v_mul_f32_e32 v197, v24, v14
	v_mul_f32_e32 v196, v19, v15
	v_fma_f32 v2, v146, v2, 0
	v_fma_f32 v6, -v13, v25, 1.0
	v_fmac_f32_e32 v25, v6, v25
	v_div_scale_f32 v6, vcc, 1.0, v7, 1.0
	v_mul_f32_e32 v14, v6, v25
	v_fma_f32 v15, -v13, v14, v6
	v_fmac_f32_e32 v14, v15, v25
	v_fma_f32 v6, -v13, v14, v6
	v_sub_f32_e32 v13, v17, v21
	v_div_fmas_f32 v6, v6, v25, v14
	v_mul_f32_e32 v13, 0x3fb8aa3b, v13
	v_sub_f32_e32 v14, v18, v21
	v_exp_f32_e32 v13, v13
	v_mul_f32_e32 v14, 0x3fb8aa3b, v14
	v_sub_f32_e32 v15, v20, v21
	v_exp_f32_e32 v14, v14
	v_mul_f32_e32 v15, 0x3fb8aa3b, v15
	v_exp_f32_e32 v15, v15
	v_div_fixup_f32 v199, v6, v7, 1.0
	s_waitcnt lgkmcnt(0)
	v_fma_f32 v6, v13, v10, 0
	v_fmac_f32_e32 v6, v14, v11
	v_fmac_f32_e32 v6, v15, v12
	v_fmac_f32_e32 v6, v190, v8
	v_max_f32_e32 v7, v22, v22
	v_max_f32_e64 v6, |v6|, v7
	v_div_scale_f32 v7, s[18:19], v6, v6, 1.0
	v_rcp_f32_e32 v8, v7
	v_mul_f32_e32 v202, v13, v10
	v_mul_f32_e32 v201, v14, v11
	v_mul_f32_e32 v200, v15, v12
	v_fma_f32 v10, -v7, v8, 1.0
	v_fmac_f32_e32 v8, v10, v8
	v_div_scale_f32 v10, vcc, 1.0, v6, 1.0
	v_mul_f32_e32 v11, v10, v8
	v_fma_f32 v12, -v7, v11, v10
	v_fmac_f32_e32 v11, v12, v8
	v_fmac_f32_e32 v2, v147, v3
	v_fma_f32 v7, -v7, v11, v10
	v_fmac_f32_e32 v2, v148, v4
	v_div_fmas_f32 v7, v7, v8, v11
	v_fmac_f32_e32 v2, v149, v5
	v_div_fixup_f32 v204, v7, v6, 1.0
	v_fmac_f32_e32 v2, v144, v9
	v_max_f32_e32 v6, v23, v23
	v_max_f32_e64 v2, |v2|, v6
	v_div_scale_f32 v6, s[18:19], v2, v2, 1.0
	v_rcp_f32_e32 v7, v6
	v_mul_f32_e32 v207, v147, v3
	v_mul_f32_e32 v206, v148, v4
	v_mul_f32_e32 v205, v149, v5
	v_fma_f32 v3, -v6, v7, 1.0
	v_fmac_f32_e32 v7, v3, v7
	v_div_scale_f32 v3, vcc, 1.0, v2, 1.0
	v_mul_f32_e32 v4, v3, v7
	v_fma_f32 v5, -v6, v4, v3
	v_fmac_f32_e32 v4, v5, v7
	v_fma_f32 v3, -v6, v4, v3
	v_div_fmas_f32 v3, v3, v7, v4
	v_div_fixup_f32 v208, v3, v2, 1.0
	v_lshl_add_u64 v[2:3], v[0:1], 0, v[128:129]
	v_lshl_add_u64 v[4:5], v[0:1], 0, v[130:131]
	global_load_dwordx4 v[80:83], v[2:3], off nt
	global_load_dwordx4 v[76:79], v[4:5], off nt
	v_lshl_add_u64 v[2:3], v[0:1], 0, v[132:133]
	v_lshl_add_u64 v[4:5], v[0:1], 0, v[134:135]
	global_load_dwordx4 v[68:71], v[2:3], off nt
	global_load_dwordx4 v[60:63], v[4:5], off nt
	v_lshl_add_u64 v[2:3], v[0:1], 0, v[136:137]
	v_lshl_add_u64 v[4:5], v[0:1], 0, v[138:139]
	global_load_dwordx4 v[52:55], v[2:3], off nt
	global_load_dwordx4 v[44:47], v[4:5], off nt
	v_lshl_add_u64 v[2:3], v[0:1], 0, v[140:141]
	v_lshl_add_u64 v[0:1], v[0:1], 0, v[142:143]
	global_load_dwordx4 v[36:39], v[2:3], off nt
	global_load_dwordx4 v[8:11], v[0:1], off nt
	ds_read_b128 v[32:35], v169
	ds_read_b128 v[24:27], v169 offset:512
	ds_read_b128 v[28:31], v169 offset:2048
	ds_read_b128 v[20:23], v169 offset:2560
	ds_read_b128 v[16:19], v169 offset:1024
	ds_read_b128 v[12:15], v169 offset:1536
	ds_read_b128 v[4:7], v169 offset:3072
	ds_read_b128 v[0:3], v169 offset:3584
	ds_read2st64_b32 v[152:153], v170 offset0:16 offset1:20
	s_waitcnt lgkmcnt(8)
	v_mul_f32_e32 v145, v93, v33
	v_mul_f32_e32 v154, v95, v35
	v_fmac_f32_e32 v145, v92, v32
	v_fmac_f32_e32 v154, v94, v34
	v_add_f32_e32 v145, v145, v154
	s_waitcnt lgkmcnt(0)
	v_mul_f32_e32 v154, v146, v152
	v_pk_mul_f32 v[210:211], v[30:31], v[154:155] op_sel_hi:[1,0]
	v_pk_mul_f32 v[154:155], v[28:29], v[154:155] op_sel_hi:[1,0]
	v_mul_f32_e32 v209, v93, v25
	v_pk_fma_f32 v[154:155], v[92:93], v[144:145], v[154:155] op_sel_hi:[1,0,1]
	v_mul_f32_e32 v214, v93, v17
	v_mul_f32_e32 v93, v93, v13
	v_fmac_f32_e32 v209, v92, v24
	v_mul_f32_e32 v212, v95, v27
	v_fmac_f32_e32 v214, v92, v16
	v_mul_f32_e32 v215, v95, v19
	v_fmac_f32_e32 v93, v92, v12
	v_mul_f32_e32 v92, v95, v15
	v_fmac_f32_e32 v212, v94, v26
	v_fmac_f32_e32 v215, v94, v18
	v_fmac_f32_e32 v92, v94, v14
	v_pk_fma_f32 v[210:211], v[94:95], v[144:145], v[210:211] op_sel_hi:[1,0,1]
	v_add_f32_e32 v209, v209, v212
	v_mul_f32_e32 v212, v147, v153
	v_add_f32_e32 v215, v214, v215
	v_add_f32_e32 v92, v93, v92
	v_pk_fma_f32 v[210:211], v[22:23], v[212:213], v[210:211] op_sel_hi:[1,0,1]
	v_pk_fma_f32 v[212:213], v[20:21], v[212:213], v[154:155] op_sel_hi:[1,0,1]
	ds_read2st64_b32 v[154:155], v170 offset0:24 offset1:28
	ds_bpermute_b32 v93, v156, v145
	ds_bpermute_b32 v94, v156, v209
	ds_bpermute_b32 v95, v156, v215
	ds_bpermute_b32 v216, v156, v92
	s_waitcnt lgkmcnt(4)
	v_mul_f32_e32 v214, v148, v154
	s_waitcnt lgkmcnt(3)
	v_add_f32_e32 v145, v145, v93
	s_waitcnt lgkmcnt(2)
	v_add_f32_e32 v94, v209, v94
	s_waitcnt lgkmcnt(1)
	v_add_f32_e32 v95, v215, v95
	s_waitcnt lgkmcnt(0)
	v_add_f32_e32 v209, v92, v216
	v_pk_fma_f32 v[218:219], v[4:5], v[214:215], v[212:213] op_sel_hi:[1,0,1]
	ds_bpermute_b32 v212, v157, v145
	ds_bpermute_b32 v213, v157, v94
	ds_bpermute_b32 v215, v157, v95
	ds_bpermute_b32 v216, v157, v209
	v_lshl_add_u64 v[150:151], v[150:151], 2, s[76:77]
	s_waitcnt lgkmcnt(3)
	v_add_f32_e32 v145, v145, v212
	s_waitcnt lgkmcnt(2)
	v_add_f32_e32 v94, v94, v213
	s_waitcnt lgkmcnt(1)
	v_add_f32_e32 v95, v95, v215
	s_waitcnt lgkmcnt(0)
	v_add_f32_e32 v209, v209, v216
	v_pk_fma_f32 v[92:93], v[6:7], v[214:215], v[210:211] op_sel_hi:[1,0,1]
	ds_bpermute_b32 v210, v158, v145
	ds_bpermute_b32 v211, v158, v94
	ds_bpermute_b32 v212, v158, v95
	ds_bpermute_b32 v213, v158, v209
	v_mul_f32_e32 v214, v149, v155
	s_waitcnt lgkmcnt(3)
	v_add_f32_e32 v145, v145, v210
	s_waitcnt lgkmcnt(2)
	v_add_f32_e32 v94, v94, v211
	s_waitcnt lgkmcnt(1)
	v_add_f32_e32 v95, v95, v212
	s_waitcnt lgkmcnt(0)
	v_add_f32_e32 v209, v209, v213
	ds_bpermute_b32 v210, v159, v145
	ds_bpermute_b32 v211, v159, v94
	ds_bpermute_b32 v212, v159, v95
	ds_bpermute_b32 v213, v159, v209
	v_pk_fma_f32 v[216:217], v[2:3], v[214:215], v[92:93] op_sel_hi:[1,0,1]
	s_waitcnt lgkmcnt(3)
	v_add_f32_e32 v92, v145, v210
	s_waitcnt lgkmcnt(2)
	v_add_f32_e32 v93, v94, v211
	s_waitcnt lgkmcnt(1)
	v_add_f32_e32 v94, v95, v212
	s_waitcnt lgkmcnt(0)
	v_add_f32_e32 v145, v209, v213
	ds_bpermute_b32 v95, v160, v92
	ds_bpermute_b32 v210, v160, v93
	ds_bpermute_b32 v211, v160, v94
	ds_bpermute_b32 v212, v160, v145
	v_pk_fma_f32 v[214:215], v[0:1], v[214:215], v[218:219] op_sel_hi:[1,0,1]
	v_lshl_add_u64 v[218:219], v[150:151], 0, v[110:111]
	v_add_u32_e32 v209, 0x50, v170
	global_store_dwordx4 v[218:219], v[214:217], off nt
	s_and_saveexec_b64 s[18:19], s[14:15]
	s_cbranch_execz .LBB0_407
	s_waitcnt lgkmcnt(2)
	v_add_f32_e32 v93, v93, v210
	v_add_f32_e32 v92, v92, v95
	v_mul_f32_e32 v92, v194, v92
	v_mul_f32_e32 v93, v191, v93
	v_fmac_f32_e32 v92, v195, v152
	v_fmac_f32_e32 v93, v197, v152
	v_fmac_f32_e32 v92, 0, v153
	v_fmac_f32_e32 v93, v196, v153
	v_fmac_f32_e32 v92, 0, v154
	v_fmac_f32_e32 v93, 0, v154
	v_fmac_f32_e32 v92, 0, v155
	v_fmac_f32_e32 v93, 0, v155
	s_waitcnt lgkmcnt(0)
	v_add_f32_e32 v145, v145, v212
	v_add_f32_e32 v94, v94, v211
	v_mul_f32_e32 v92, v198, v92
	v_mul_f32_e32 v93, v199, v93
	ds_write2st64_b32 v209, v92, v93 offset0:32 offset1:36
	v_mul_f32_e32 v92, v190, v94
	v_mul_f32_e32 v93, v144, v145
	v_fmac_f32_e32 v92, v202, v152
	v_fmac_f32_e32 v93, v203, v152
	v_fmac_f32_e32 v92, v201, v153
	v_fmac_f32_e32 v93, v207, v153
	v_fmac_f32_e32 v92, v200, v154
	v_fmac_f32_e32 v93, v206, v154
	v_fmac_f32_e32 v92, 0, v155
	v_fmac_f32_e32 v93, v205, v155
	v_mul_f32_e32 v92, v204, v92
	v_mul_f32_e32 v93, v208, v93
	ds_write2st64_b32 v209, v92, v93 offset0:40 offset1:44
.LBB0_407:
	s_or_b64 exec, exec, s[18:19]
	v_add_u32_e32 v155, 64, v170
	s_waitcnt lgkmcnt(3)
	ds_read2st64_b32 v[94:95], v155 offset0:16 offset1:20
	v_mul_f32_e32 v92, v89, v33
	v_mul_f32_e32 v93, v91, v35
	v_fmac_f32_e32 v92, v88, v32
	v_fmac_f32_e32 v93, v90, v34
	v_add_f32_e32 v216, v92, v93
	s_waitcnt lgkmcnt(0)
	v_mul_f32_e32 v92, v146, v94
	v_mul_f32_e32 v154, v89, v25
	v_mul_f32_e32 v212, v91, v27
	v_mov_b32_e32 v145, v144
	v_pk_mul_f32 v[152:153], v[30:31], v[92:93] op_sel_hi:[1,0]
	v_pk_mul_f32 v[210:211], v[28:29], v[92:93] op_sel_hi:[1,0]
	v_mov_b32_e32 v92, v144
	v_mov_b32_e32 v93, v144
	v_fmac_f32_e32 v154, v88, v24
	v_fmac_f32_e32 v212, v90, v26
	v_pk_fma_f32 v[152:153], v[90:91], v[92:93], v[152:153]
	v_pk_fma_f32 v[210:211], v[88:89], v[144:145], v[210:211]
	v_add_f32_e32 v217, v154, v212
	v_mul_f32_e32 v154, v147, v95
	v_pk_fma_f32 v[212:213], v[22:23], v[154:155], v[152:153] op_sel_hi:[1,0,1]
	v_pk_fma_f32 v[210:211], v[20:21], v[154:155], v[210:211] op_sel_hi:[1,0,1]
	v_mul_f32_e32 v154, v89, v17
	v_mul_f32_e32 v89, v89, v13
	v_fmac_f32_e32 v154, v88, v16
	v_mul_f32_e32 v214, v91, v19
	v_fmac_f32_e32 v89, v88, v12
	v_mul_f32_e32 v88, v91, v15
	v_fmac_f32_e32 v214, v90, v18
	v_fmac_f32_e32 v88, v90, v14
	ds_read2st64_b32 v[152:153], v155 offset0:24 offset1:28
	v_add_f32_e32 v218, v154, v214
	v_add_f32_e32 v88, v89, v88
	ds_bpermute_b32 v89, v156, v216
	ds_bpermute_b32 v90, v156, v217
	ds_bpermute_b32 v91, v156, v218
	ds_bpermute_b32 v219, v156, v88
	s_waitcnt lgkmcnt(4)
	v_mul_f32_e32 v154, v148, v152
	v_pk_fma_f32 v[214:215], v[4:5], v[154:155], v[210:211] op_sel_hi:[1,0,1]
	s_waitcnt lgkmcnt(3)
	v_add_f32_e32 v210, v216, v89
	s_waitcnt lgkmcnt(2)
	v_add_f32_e32 v90, v217, v90
	s_waitcnt lgkmcnt(1)
	v_add_f32_e32 v91, v218, v91
	s_waitcnt lgkmcnt(0)
	v_add_f32_e32 v211, v88, v219
	ds_bpermute_b32 v216, v157, v210
	ds_bpermute_b32 v217, v157, v90
	ds_bpermute_b32 v218, v157, v91
	ds_bpermute_b32 v219, v157, v211
	v_pk_fma_f32 v[88:89], v[6:7], v[154:155], v[212:213] op_sel_hi:[1,0,1]
	s_waitcnt lgkmcnt(3)
	v_add_f32_e32 v210, v210, v216
	s_waitcnt lgkmcnt(2)
	v_add_f32_e32 v90, v90, v217
	s_waitcnt lgkmcnt(1)
	v_add_f32_e32 v91, v91, v218
	s_waitcnt lgkmcnt(0)
	v_add_f32_e32 v211, v211, v219
	ds_bpermute_b32 v212, v158, v210
	ds_bpermute_b32 v213, v158, v90
	ds_bpermute_b32 v216, v158, v91
	ds_bpermute_b32 v217, v158, v211
	v_mul_f32_e32 v154, v149, v153
	s_waitcnt lgkmcnt(3)
	v_add_f32_e32 v210, v210, v212
	s_waitcnt lgkmcnt(2)
	v_add_f32_e32 v90, v90, v213
	s_waitcnt lgkmcnt(1)
	v_add_f32_e32 v91, v91, v216
	s_waitcnt lgkmcnt(0)
	v_add_f32_e32 v211, v211, v217
	ds_bpermute_b32 v212, v159, v210
	ds_bpermute_b32 v213, v159, v90
	ds_bpermute_b32 v218, v159, v91
	ds_bpermute_b32 v219, v159, v211
	v_pk_fma_f32 v[216:217], v[2:3], v[154:155], v[88:89] op_sel_hi:[1,0,1]
	s_waitcnt lgkmcnt(3)
	v_add_f32_e32 v88, v210, v212
	s_waitcnt lgkmcnt(2)
	v_add_f32_e32 v89, v90, v213
	s_waitcnt lgkmcnt(1)
	v_add_f32_e32 v90, v91, v218
	s_waitcnt lgkmcnt(0)
	v_add_f32_e32 v210, v211, v219
	ds_bpermute_b32 v91, v160, v88
	ds_bpermute_b32 v211, v160, v89
	ds_bpermute_b32 v212, v160, v90
	ds_bpermute_b32 v213, v160, v210
	v_pk_fma_f32 v[214:215], v[0:1], v[154:155], v[214:215] op_sel_hi:[1,0,1]
	v_lshl_add_u64 v[218:219], v[150:151], 0, v[112:113]
	v_add_u32_e32 v154, 0x90, v170
	global_store_dwordx4 v[218:219], v[214:217], off nt
	s_and_saveexec_b64 s[18:19], s[14:15]
	s_cbranch_execz .LBB0_409
	s_waitcnt lgkmcnt(2)
	v_add_f32_e32 v89, v89, v211
	v_add_f32_e32 v88, v88, v91
	v_mul_f32_e32 v88, v194, v88
	v_mul_f32_e32 v89, v191, v89
	v_fmac_f32_e32 v88, v195, v94
	v_fmac_f32_e32 v89, v197, v94
	v_fmac_f32_e32 v88, 0, v95
	v_fmac_f32_e32 v89, v196, v95
	v_fmac_f32_e32 v88, 0, v152
	v_fmac_f32_e32 v89, 0, v152
	v_fmac_f32_e32 v88, 0, v153
	v_fmac_f32_e32 v89, 0, v153
	s_waitcnt lgkmcnt(0)
	v_add_f32_e32 v210, v210, v213
	v_add_f32_e32 v90, v90, v212
	v_mul_f32_e32 v88, v198, v88
	v_mul_f32_e32 v89, v199, v89
	ds_write2st64_b32 v154, v88, v89 offset0:32 offset1:36
	v_mul_f32_e32 v88, v190, v90
	v_mul_f32_e32 v89, v144, v210
	v_fmac_f32_e32 v88, v202, v94
	v_fmac_f32_e32 v89, v203, v94
	v_fmac_f32_e32 v88, v201, v95
	v_fmac_f32_e32 v89, v207, v95
	v_fmac_f32_e32 v88, v200, v152
	v_fmac_f32_e32 v89, v206, v152
	v_fmac_f32_e32 v88, 0, v153
	v_fmac_f32_e32 v89, v205, v153
	v_mul_f32_e32 v88, v204, v88
	v_mul_f32_e32 v89, v208, v89
	ds_write2st64_b32 v154, v88, v89 offset0:40 offset1:44
.LBB0_409:
	s_or_b64 exec, exec, s[18:19]
	v_add_u32_e32 v94, 0x80, v170
	ds_read2st64_b32 v[88:89], v94 offset0:16 offset1:20
	v_mul_f32_e32 v90, v85, v33
	s_waitcnt lgkmcnt(4)
	v_mul_f32_e32 v91, v87, v35
	v_fmac_f32_e32 v90, v84, v32
	v_fmac_f32_e32 v91, v86, v34
	v_add_f32_e32 v95, v90, v91
	s_waitcnt lgkmcnt(0)
	v_mul_f32_e32 v90, v146, v88
	v_pk_mul_f32 v[152:153], v[30:31], v[90:91] op_sel_hi:[1,0]
	v_pk_mul_f32 v[90:91], v[28:29], v[90:91] op_sel_hi:[1,0]
	v_pk_fma_f32 v[92:93], v[86:87], v[92:93], v[152:153]
	v_pk_fma_f32 v[90:91], v[84:85], v[144:145], v[90:91]
	v_mul_f32_e32 v152, v85, v25
	v_mul_f32_e32 v153, v87, v27
	v_mul_f32_e32 v210, v85, v17
	v_mul_f32_e32 v85, v85, v13
	v_fmac_f32_e32 v152, v84, v24
	v_fmac_f32_e32 v153, v86, v26
	v_fmac_f32_e32 v210, v84, v16
	v_mul_f32_e32 v212, v87, v19
	v_fmac_f32_e32 v85, v84, v12
	v_mul_f32_e32 v84, v87, v15
	v_add_f32_e32 v211, v152, v153
	v_mul_f32_e32 v152, v147, v89
	v_fmac_f32_e32 v212, v86, v18
	v_fmac_f32_e32 v84, v86, v14
	v_pk_fma_f32 v[92:93], v[22:23], v[152:153], v[92:93] op_sel_hi:[1,0,1]
	v_pk_fma_f32 v[152:153], v[20:21], v[152:153], v[90:91] op_sel_hi:[1,0,1]
	ds_read2st64_b32 v[90:91], v94 offset0:24 offset1:28
	v_add_f32_e32 v212, v210, v212
	v_add_f32_e32 v84, v85, v84
	ds_bpermute_b32 v85, v156, v95
	ds_bpermute_b32 v86, v156, v211
	ds_bpermute_b32 v87, v156, v212
	ds_bpermute_b32 v213, v156, v84
	s_waitcnt lgkmcnt(4)
	v_mul_f32_e32 v210, v148, v90
	v_pk_fma_f32 v[214:215], v[4:5], v[210:211], v[152:153] op_sel_hi:[1,0,1]
	s_waitcnt lgkmcnt(3)
	v_add_f32_e32 v95, v95, v85
	s_waitcnt lgkmcnt(2)
	v_add_f32_e32 v86, v211, v86
	s_waitcnt lgkmcnt(1)
	v_add_f32_e32 v87, v212, v87
	s_waitcnt lgkmcnt(0)
	v_add_f32_e32 v152, v84, v213
	ds_bpermute_b32 v153, v157, v95
	ds_bpermute_b32 v211, v157, v86
	ds_bpermute_b32 v212, v157, v87
	ds_bpermute_b32 v213, v157, v152
	s_waitcnt lgkmcnt(2)
	v_pk_fma_f32 v[84:85], v[6:7], v[210:211], v[92:93] op_sel_hi:[1,0,1]
	v_add_f32_e32 v93, v95, v153
	v_add_f32_e32 v86, v86, v211
	s_waitcnt lgkmcnt(1)
	v_add_f32_e32 v87, v87, v212
	s_waitcnt lgkmcnt(0)
	v_add_f32_e32 v95, v152, v213
	ds_bpermute_b32 v152, v158, v93
	ds_bpermute_b32 v153, v158, v86
	ds_bpermute_b32 v210, v158, v87
	ds_bpermute_b32 v211, v158, v95
	v_mul_f32_e32 v92, v149, v91
	s_waitcnt lgkmcnt(3)
	v_add_f32_e32 v93, v93, v152
	s_waitcnt lgkmcnt(2)
	v_add_f32_e32 v86, v86, v153
	s_waitcnt lgkmcnt(1)
	v_add_f32_e32 v87, v87, v210
	s_waitcnt lgkmcnt(0)
	v_add_f32_e32 v95, v95, v211
	ds_bpermute_b32 v152, v159, v93
	ds_bpermute_b32 v153, v159, v86
	ds_bpermute_b32 v210, v159, v87
	ds_bpermute_b32 v211, v159, v95
	v_pk_fma_f32 v[212:213], v[2:3], v[92:93], v[84:85] op_sel_hi:[1,0,1]
	s_waitcnt lgkmcnt(3)
	v_add_f32_e32 v84, v93, v152
	s_waitcnt lgkmcnt(2)
	v_add_f32_e32 v85, v86, v153
	s_waitcnt lgkmcnt(1)
	v_add_f32_e32 v86, v87, v210
	s_waitcnt lgkmcnt(0)
	v_add_f32_e32 v93, v95, v211
	ds_bpermute_b32 v87, v160, v84
	ds_bpermute_b32 v95, v160, v85
	ds_bpermute_b32 v152, v160, v86
	ds_bpermute_b32 v153, v160, v93
	v_pk_fma_f32 v[210:211], v[0:1], v[92:93], v[214:215] op_sel_hi:[1,0,1]
	v_lshl_add_u64 v[214:215], v[150:151], 0, v[114:115]
	v_add_u32_e32 v92, 0xd0, v170
	global_store_dwordx4 v[214:215], v[210:213], off nt
	s_and_saveexec_b64 s[18:19], s[14:15]
	s_cbranch_execz .LBB0_411
	s_waitcnt lgkmcnt(2)
	v_add_f32_e32 v85, v85, v95
	v_add_f32_e32 v84, v84, v87
	v_mul_f32_e32 v84, v194, v84
	v_mul_f32_e32 v85, v191, v85
	v_fmac_f32_e32 v84, v195, v88
	v_fmac_f32_e32 v85, v197, v88
	v_fmac_f32_e32 v84, 0, v89
	v_fmac_f32_e32 v85, v196, v89
	v_fmac_f32_e32 v84, 0, v90
	v_fmac_f32_e32 v85, 0, v90
	v_fmac_f32_e32 v84, 0, v91
	v_fmac_f32_e32 v85, 0, v91
	s_waitcnt lgkmcnt(0)
	v_add_f32_e32 v93, v93, v153
	v_add_f32_e32 v86, v86, v152
	v_mul_f32_e32 v84, v198, v84
	v_mul_f32_e32 v85, v199, v85
	ds_write2st64_b32 v92, v84, v85 offset0:32 offset1:36
	v_mul_f32_e32 v84, v190, v86
	v_mul_f32_e32 v85, v144, v93
	v_fmac_f32_e32 v84, v202, v88
	v_fmac_f32_e32 v85, v203, v88
	v_fmac_f32_e32 v84, v201, v89
	v_fmac_f32_e32 v85, v207, v89
	v_fmac_f32_e32 v84, v200, v90
	v_fmac_f32_e32 v85, v206, v90
	v_fmac_f32_e32 v84, 0, v91
	v_fmac_f32_e32 v85, v205, v91
	v_mul_f32_e32 v84, v204, v84
	v_mul_f32_e32 v85, v208, v85
	ds_write2st64_b32 v92, v84, v85 offset0:40 offset1:44
.LBB0_411:
	s_or_b64 exec, exec, s[18:19]
	v_add_u32_e32 v91, 0xc0, v170
	s_waitcnt lgkmcnt(3)
	ds_read2st64_b32 v[86:87], v91 offset0:16 offset1:20
	v_mul_f32_e32 v84, v73, v33
	v_mul_f32_e32 v85, v75, v35
	v_fmac_f32_e32 v84, v72, v32
	v_fmac_f32_e32 v85, v74, v34
	v_add_f32_e32 v93, v84, v85
	s_waitcnt lgkmcnt(0)
	v_mul_f32_e32 v84, v146, v86
	v_mul_f32_e32 v90, v73, v25
	v_mul_f32_e32 v95, v75, v27
	v_pk_mul_f32 v[88:89], v[30:31], v[84:85] op_sel_hi:[1,0]
	v_pk_mul_f32 v[152:153], v[28:29], v[84:85] op_sel_hi:[1,0]
	v_mov_b32_e32 v84, v144
	v_mov_b32_e32 v85, v144
	v_fmac_f32_e32 v90, v72, v24
	v_fmac_f32_e32 v95, v74, v26
	v_pk_fma_f32 v[88:89], v[74:75], v[84:85], v[88:89]
	v_pk_fma_f32 v[152:153], v[72:73], v[144:145], v[152:153]
	v_add_f32_e32 v95, v90, v95
	v_mul_f32_e32 v90, v147, v87
	v_pk_fma_f32 v[210:211], v[22:23], v[90:91], v[88:89] op_sel_hi:[1,0,1]
	v_pk_fma_f32 v[152:153], v[20:21], v[90:91], v[152:153] op_sel_hi:[1,0,1]
	v_mul_f32_e32 v90, v73, v17
	v_mul_f32_e32 v73, v73, v13
	v_fmac_f32_e32 v90, v72, v16
	v_mul_f32_e32 v212, v75, v19
	v_fmac_f32_e32 v73, v72, v12
	v_mul_f32_e32 v72, v75, v15
	v_fmac_f32_e32 v212, v74, v18
	v_fmac_f32_e32 v72, v74, v14
	v_add_f32_e32 v212, v90, v212
	v_add_f32_e32 v72, v73, v72
	ds_read2st64_b32 v[88:89], v91 offset0:24 offset1:28
	ds_bpermute_b32 v73, v156, v93
	ds_bpermute_b32 v74, v156, v95
	ds_bpermute_b32 v75, v156, v212
	ds_bpermute_b32 v213, v156, v72
	s_waitcnt lgkmcnt(4)
	v_mul_f32_e32 v90, v148, v88
	s_waitcnt lgkmcnt(3)
	v_add_f32_e32 v93, v93, v73
	s_waitcnt lgkmcnt(2)
	v_add_f32_e32 v74, v95, v74
	s_waitcnt lgkmcnt(1)
	v_add_f32_e32 v75, v212, v75
	s_waitcnt lgkmcnt(0)
	v_add_f32_e32 v95, v72, v213
	v_pk_fma_f32 v[214:215], v[4:5], v[90:91], v[152:153] op_sel_hi:[1,0,1]
	ds_bpermute_b32 v152, v157, v93
	ds_bpermute_b32 v153, v157, v74
	ds_bpermute_b32 v212, v157, v75
	ds_bpermute_b32 v213, v157, v95
	v_pk_fma_f32 v[72:73], v[6:7], v[90:91], v[210:211] op_sel_hi:[1,0,1]
	s_waitcnt lgkmcnt(3)
	v_add_f32_e32 v93, v93, v152
	s_waitcnt lgkmcnt(2)
	v_add_f32_e32 v74, v74, v153
	s_waitcnt lgkmcnt(1)
	v_add_f32_e32 v75, v75, v212
	s_waitcnt lgkmcnt(0)
	v_add_f32_e32 v95, v95, v213
	ds_bpermute_b32 v152, v158, v93
	ds_bpermute_b32 v153, v158, v74
	ds_bpermute_b32 v210, v158, v75
	ds_bpermute_b32 v211, v158, v95
	v_mul_f32_e32 v90, v149, v89
	s_waitcnt lgkmcnt(3)
	v_add_f32_e32 v93, v93, v152
	s_waitcnt lgkmcnt(2)
	v_add_f32_e32 v74, v74, v153
	s_waitcnt lgkmcnt(1)
	v_add_f32_e32 v75, v75, v210
	s_waitcnt lgkmcnt(0)
	v_add_f32_e32 v95, v95, v211
	ds_bpermute_b32 v152, v159, v93
	ds_bpermute_b32 v153, v159, v74
	ds_bpermute_b32 v210, v159, v75
	ds_bpermute_b32 v211, v159, v95
	v_pk_fma_f32 v[212:213], v[2:3], v[90:91], v[72:73] op_sel_hi:[1,0,1]
	s_waitcnt lgkmcnt(3)
	v_add_f32_e32 v72, v93, v152
	s_waitcnt lgkmcnt(2)
	v_add_f32_e32 v73, v74, v153
	s_waitcnt lgkmcnt(1)
	v_add_f32_e32 v74, v75, v210
	s_waitcnt lgkmcnt(0)
	v_add_f32_e32 v93, v95, v211
	ds_bpermute_b32 v75, v160, v72
	ds_bpermute_b32 v95, v160, v73
	ds_bpermute_b32 v152, v160, v74
	ds_bpermute_b32 v153, v160, v93
	v_pk_fma_f32 v[210:211], v[0:1], v[90:91], v[214:215] op_sel_hi:[1,0,1]
	v_lshl_add_u64 v[214:215], v[150:151], 0, v[116:117]
	v_add_u32_e32 v90, 16, v170
	global_store_dwordx4 v[214:215], v[210:213], off nt
	s_and_saveexec_b64 s[18:19], s[14:15]
	s_cbranch_execz .LBB0_413
	s_waitcnt lgkmcnt(2)
	v_add_f32_e32 v73, v73, v95
	v_add_f32_e32 v72, v72, v75
	v_mul_f32_e32 v72, v194, v72
	v_mul_f32_e32 v73, v191, v73
	v_fmac_f32_e32 v72, v195, v86
	v_fmac_f32_e32 v73, v197, v86
	v_fmac_f32_e32 v72, 0, v87
	v_fmac_f32_e32 v73, v196, v87
	v_fmac_f32_e32 v72, 0, v88
	v_fmac_f32_e32 v73, 0, v88
	v_fmac_f32_e32 v72, 0, v89
	v_fmac_f32_e32 v73, 0, v89
	s_waitcnt lgkmcnt(0)
	v_add_f32_e32 v93, v93, v153
	v_add_f32_e32 v74, v74, v152
	v_mul_f32_e32 v72, v198, v72
	v_mul_f32_e32 v73, v199, v73
	ds_write2st64_b32 v90, v72, v73 offset0:33 offset1:37
	v_mul_f32_e32 v72, v190, v74
	v_mul_f32_e32 v73, v144, v93
	v_fmac_f32_e32 v72, v202, v86
	v_fmac_f32_e32 v73, v203, v86
	v_fmac_f32_e32 v72, v201, v87
	v_fmac_f32_e32 v73, v207, v87
	v_fmac_f32_e32 v72, v200, v88
	v_fmac_f32_e32 v73, v206, v88
	v_fmac_f32_e32 v72, 0, v89
	v_fmac_f32_e32 v73, v205, v89
	v_mul_f32_e32 v72, v204, v72
	v_mul_f32_e32 v73, v208, v73
	ds_write2st64_b32 v90, v72, v73 offset0:41 offset1:45
.LBB0_413:
	s_or_b64 exec, exec, s[18:19]
	ds_read2st64_b32 v[72:73], v170 offset0:17 offset1:21
	v_mul_f32_e32 v74, v65, v33
	s_waitcnt lgkmcnt(4)
	v_mul_f32_e32 v75, v67, v35
	v_fmac_f32_e32 v74, v64, v32
	v_fmac_f32_e32 v75, v66, v34
	v_add_f32_e32 v88, v74, v75
	s_waitcnt lgkmcnt(0)
	v_mul_f32_e32 v74, v146, v72
	v_pk_mul_f32 v[86:87], v[30:31], v[74:75] op_sel_hi:[1,0]
	v_pk_mul_f32 v[74:75], v[28:29], v[74:75] op_sel_hi:[1,0]
	v_pk_fma_f32 v[84:85], v[66:67], v[84:85], v[86:87]
	v_mul_f32_e32 v86, v65, v25
	v_mul_f32_e32 v87, v67, v27
	v_fmac_f32_e32 v86, v64, v24
	v_fmac_f32_e32 v87, v66, v26
	v_pk_fma_f32 v[74:75], v[64:65], v[144:145], v[74:75]
	v_add_f32_e32 v89, v86, v87
	v_mul_f32_e32 v86, v147, v73
	v_pk_fma_f32 v[84:85], v[22:23], v[86:87], v[84:85] op_sel_hi:[1,0,1]
	v_pk_fma_f32 v[86:87], v[20:21], v[86:87], v[74:75] op_sel_hi:[1,0,1]
	v_mul_f32_e32 v74, v65, v17
	v_mul_f32_e32 v65, v65, v13
	v_fmac_f32_e32 v74, v64, v16
	v_mul_f32_e32 v75, v67, v19
	v_fmac_f32_e32 v65, v64, v12
	v_mul_f32_e32 v64, v67, v15
	v_fmac_f32_e32 v75, v66, v18
	v_fmac_f32_e32 v64, v66, v14
	v_add_f32_e32 v93, v74, v75
	v_add_f32_e32 v65, v65, v64
	ds_bpermute_b32 v66, v156, v88
	ds_bpermute_b32 v67, v156, v89
	ds_bpermute_b32 v95, v156, v93
	ds_bpermute_b32 v152, v156, v65
	ds_read2st64_b32 v[74:75], v170 offset0:25 offset1:29
	s_waitcnt lgkmcnt(4)
	v_add_f32_e32 v66, v88, v66
	s_waitcnt lgkmcnt(3)
	v_add_f32_e32 v67, v89, v67
	s_waitcnt lgkmcnt(2)
	v_add_f32_e32 v93, v93, v95
	s_waitcnt lgkmcnt(1)
	v_add_f32_e32 v65, v65, v152
	ds_bpermute_b32 v95, v157, v66
	ds_bpermute_b32 v152, v157, v67
	ds_bpermute_b32 v153, v157, v93
	ds_bpermute_b32 v210, v157, v65
	s_waitcnt lgkmcnt(4)
	v_mul_f32_e32 v64, v148, v74
	v_pk_fma_f32 v[88:89], v[4:5], v[64:65], v[86:87] op_sel_hi:[1,0,1]
	s_waitcnt lgkmcnt(3)
	v_add_f32_e32 v66, v66, v95
	s_waitcnt lgkmcnt(2)
	v_add_f32_e32 v67, v67, v152
	s_waitcnt lgkmcnt(1)
	v_add_f32_e32 v86, v93, v153
	s_waitcnt lgkmcnt(0)
	v_add_f32_e32 v65, v65, v210
	ds_bpermute_b32 v87, v158, v66
	ds_bpermute_b32 v93, v158, v67
	ds_bpermute_b32 v95, v158, v86
	ds_bpermute_b32 v210, v158, v65
	v_pk_fma_f32 v[152:153], v[6:7], v[64:65], v[84:85] op_sel_hi:[1,0,1]
	s_waitcnt lgkmcnt(3)
	v_add_f32_e32 v64, v66, v87
	s_waitcnt lgkmcnt(2)
	v_add_f32_e32 v66, v67, v93
	s_waitcnt lgkmcnt(1)
	v_add_f32_e32 v67, v86, v95
	s_waitcnt lgkmcnt(0)
	v_add_f32_e32 v84, v65, v210
	ds_bpermute_b32 v65, v159, v64
	ds_bpermute_b32 v85, v159, v66
	ds_bpermute_b32 v86, v159, v67
	ds_bpermute_b32 v87, v159, v84
	v_mul_f32_e32 v210, v149, v75
	s_waitcnt lgkmcnt(3)
	v_add_f32_e32 v64, v64, v65
	s_waitcnt lgkmcnt(2)
	v_add_f32_e32 v65, v66, v85
	s_waitcnt lgkmcnt(1)
	v_add_f32_e32 v66, v67, v86
	s_waitcnt lgkmcnt(0)
	v_add_f32_e32 v84, v84, v87
	ds_bpermute_b32 v67, v160, v64
	ds_bpermute_b32 v85, v160, v65
	ds_bpermute_b32 v86, v160, v66
	ds_bpermute_b32 v87, v160, v84
	v_pk_fma_f32 v[212:213], v[2:3], v[210:211], v[152:153] op_sel_hi:[1,0,1]
	v_pk_fma_f32 v[210:211], v[0:1], v[210:211], v[88:89] op_sel_hi:[1,0,1]
	v_lshl_add_u64 v[88:89], v[150:151], 0, v[118:119]
	global_store_dwordx4 v[88:89], v[210:213], off nt
	s_and_saveexec_b64 s[18:19], s[14:15]
	s_cbranch_execz .LBB0_415
	s_waitcnt lgkmcnt(2)
	v_add_f32_e32 v65, v65, v85
	v_add_f32_e32 v64, v64, v67
	v_mul_f32_e32 v64, v194, v64
	v_mul_f32_e32 v65, v191, v65
	v_fmac_f32_e32 v64, v195, v72
	v_fmac_f32_e32 v65, v197, v72
	v_fmac_f32_e32 v64, 0, v73
	v_fmac_f32_e32 v65, v196, v73
	v_fmac_f32_e32 v64, 0, v74
	v_fmac_f32_e32 v65, 0, v74
	v_fmac_f32_e32 v64, 0, v75
	v_fmac_f32_e32 v65, 0, v75
	s_waitcnt lgkmcnt(0)
	v_add_f32_e32 v84, v84, v87
	v_add_f32_e32 v66, v66, v86
	v_mul_f32_e32 v64, v198, v64
	v_mul_f32_e32 v65, v199, v65
	ds_write2st64_b32 v209, v64, v65 offset0:33 offset1:37
	v_mul_f32_e32 v64, v190, v66
	v_mul_f32_e32 v65, v144, v84
	v_fmac_f32_e32 v64, v202, v72
	v_fmac_f32_e32 v65, v203, v72
	v_fmac_f32_e32 v64, v201, v73
	v_fmac_f32_e32 v65, v207, v73
	v_fmac_f32_e32 v64, v200, v74
	v_fmac_f32_e32 v65, v206, v74
	v_fmac_f32_e32 v64, 0, v75
	v_fmac_f32_e32 v65, v205, v75
	v_mul_f32_e32 v64, v204, v64
	v_mul_f32_e32 v65, v208, v65
	ds_write2st64_b32 v209, v64, v65 offset0:41 offset1:45
.LBB0_415:
	s_or_b64 exec, exec, s[18:19]
	s_waitcnt lgkmcnt(3)
	ds_read2st64_b32 v[66:67], v155 offset0:17 offset1:21
	v_mul_f32_e32 v64, v57, v33
	v_mul_f32_e32 v65, v59, v35
	v_fmac_f32_e32 v64, v56, v32
	v_fmac_f32_e32 v65, v58, v34
	s_waitcnt lgkmcnt(3)
	v_add_f32_e32 v85, v64, v65
	s_waitcnt lgkmcnt(0)
	v_mul_f32_e32 v64, v146, v66
	v_mul_f32_e32 v84, v57, v25
	v_mul_f32_e32 v86, v59, v27
	v_pk_mul_f32 v[72:73], v[30:31], v[64:65] op_sel_hi:[1,0]
	v_pk_mul_f32 v[74:75], v[28:29], v[64:65] op_sel_hi:[1,0]
	v_mov_b32_e32 v64, v144
	v_mov_b32_e32 v65, v144
	v_fmac_f32_e32 v84, v56, v24
	v_fmac_f32_e32 v86, v58, v26
	v_pk_fma_f32 v[72:73], v[58:59], v[64:65], v[72:73]
	v_add_f32_e32 v88, v84, v86
	v_mul_f32_e32 v84, v147, v67
	v_pk_fma_f32 v[74:75], v[56:57], v[144:145], v[74:75]
	v_pk_fma_f32 v[86:87], v[22:23], v[84:85], v[72:73] op_sel_hi:[1,0,1]
	v_mul_f32_e32 v72, v57, v17
	v_mul_f32_e32 v57, v57, v13
	v_fmac_f32_e32 v72, v56, v16
	v_mul_f32_e32 v73, v59, v19
	v_fmac_f32_e32 v57, v56, v12
	v_mul_f32_e32 v56, v59, v15
	v_fmac_f32_e32 v73, v58, v18
	v_fmac_f32_e32 v56, v58, v14
	v_pk_fma_f32 v[74:75], v[20:21], v[84:85], v[74:75] op_sel_hi:[1,0,1]
	v_add_f32_e32 v84, v72, v73
	v_add_f32_e32 v57, v57, v56
	ds_bpermute_b32 v58, v156, v85
	ds_bpermute_b32 v59, v156, v88
	ds_bpermute_b32 v89, v156, v84
	ds_bpermute_b32 v93, v156, v57
	ds_read2st64_b32 v[72:73], v155 offset0:25 offset1:29
	s_waitcnt lgkmcnt(4)
	v_add_f32_e32 v58, v85, v58
	s_waitcnt lgkmcnt(3)
	v_add_f32_e32 v59, v88, v59
	s_waitcnt lgkmcnt(2)
	v_add_f32_e32 v84, v84, v89
	s_waitcnt lgkmcnt(1)
	v_add_f32_e32 v57, v57, v93
	ds_bpermute_b32 v85, v157, v58
	ds_bpermute_b32 v88, v157, v59
	ds_bpermute_b32 v89, v157, v84
	ds_bpermute_b32 v93, v157, v57
	s_waitcnt lgkmcnt(4)
	v_mul_f32_e32 v56, v148, v72
	v_pk_fma_f32 v[152:153], v[4:5], v[56:57], v[74:75] op_sel_hi:[1,0,1]
	s_waitcnt lgkmcnt(3)
	v_add_f32_e32 v58, v58, v85
	s_waitcnt lgkmcnt(2)
	v_add_f32_e32 v59, v59, v88
	s_waitcnt lgkmcnt(1)
	v_add_f32_e32 v74, v84, v89
	s_waitcnt lgkmcnt(0)
	v_add_f32_e32 v57, v57, v93
	ds_bpermute_b32 v75, v158, v58
	ds_bpermute_b32 v84, v158, v59
	ds_bpermute_b32 v85, v158, v74
	ds_bpermute_b32 v88, v158, v57
	v_pk_fma_f32 v[86:87], v[6:7], v[56:57], v[86:87] op_sel_hi:[1,0,1]
	s_waitcnt lgkmcnt(3)
	v_add_f32_e32 v56, v58, v75
	s_waitcnt lgkmcnt(2)
	v_add_f32_e32 v58, v59, v84
	s_waitcnt lgkmcnt(1)
	v_add_f32_e32 v59, v74, v85
	s_waitcnt lgkmcnt(0)
	v_add_f32_e32 v74, v57, v88
	ds_bpermute_b32 v57, v159, v56
	ds_bpermute_b32 v75, v159, v58
	ds_bpermute_b32 v84, v159, v59
	ds_bpermute_b32 v85, v159, v74
	v_mul_f32_e32 v210, v149, v73
	s_waitcnt lgkmcnt(3)
	v_add_f32_e32 v56, v56, v57
	s_waitcnt lgkmcnt(2)
	v_add_f32_e32 v57, v58, v75
	s_waitcnt lgkmcnt(1)
	v_add_f32_e32 v58, v59, v84
	s_waitcnt lgkmcnt(0)
	v_add_f32_e32 v74, v74, v85
	ds_bpermute_b32 v59, v160, v56
	ds_bpermute_b32 v75, v160, v57
	ds_bpermute_b32 v84, v160, v58
	ds_bpermute_b32 v85, v160, v74
	v_pk_fma_f32 v[88:89], v[2:3], v[210:211], v[86:87] op_sel_hi:[1,0,1]
	v_pk_fma_f32 v[86:87], v[0:1], v[210:211], v[152:153] op_sel_hi:[1,0,1]
	v_lshl_add_u64 v[152:153], v[150:151], 0, v[120:121]
	global_store_dwordx4 v[152:153], v[86:89], off nt
	s_and_saveexec_b64 s[18:19], s[14:15]
	s_cbranch_execz .LBB0_417
	s_waitcnt lgkmcnt(2)
	v_add_f32_e32 v57, v57, v75
	v_add_f32_e32 v56, v56, v59
	v_mul_f32_e32 v56, v194, v56
	v_mul_f32_e32 v57, v191, v57
	v_fmac_f32_e32 v56, v195, v66
	v_fmac_f32_e32 v57, v197, v66
	v_fmac_f32_e32 v56, 0, v67
	v_fmac_f32_e32 v57, v196, v67
	v_fmac_f32_e32 v56, 0, v72
	v_fmac_f32_e32 v57, 0, v72
	v_fmac_f32_e32 v56, 0, v73
	v_fmac_f32_e32 v57, 0, v73
	s_waitcnt lgkmcnt(0)
	v_add_f32_e32 v74, v74, v85
	v_add_f32_e32 v58, v58, v84
	v_mul_f32_e32 v56, v198, v56
	v_mul_f32_e32 v57, v199, v57
	ds_write2st64_b32 v154, v56, v57 offset0:33 offset1:37
	v_mul_f32_e32 v56, v190, v58
	v_mul_f32_e32 v57, v144, v74
	v_fmac_f32_e32 v56, v202, v66
	v_fmac_f32_e32 v57, v203, v66
	v_fmac_f32_e32 v56, v201, v67
	v_fmac_f32_e32 v57, v207, v67
	v_fmac_f32_e32 v56, v200, v72
	v_fmac_f32_e32 v57, v206, v72
	v_fmac_f32_e32 v56, 0, v73
	v_fmac_f32_e32 v57, v205, v73
	v_mul_f32_e32 v56, v204, v56
	v_mul_f32_e32 v57, v208, v57
	ds_write2st64_b32 v154, v56, v57 offset0:41 offset1:45
.LBB0_417:
	s_or_b64 exec, exec, s[18:19]
	ds_read2st64_b32 v[56:57], v94 offset0:17 offset1:21
	v_mul_f32_e32 v58, v49, v33
	s_waitcnt lgkmcnt(4)
	v_mul_f32_e32 v59, v51, v35
	v_fmac_f32_e32 v58, v48, v32
	v_fmac_f32_e32 v59, v50, v34
	v_add_f32_e32 v72, v58, v59
	s_waitcnt lgkmcnt(0)
	v_mul_f32_e32 v58, v146, v56
	v_pk_mul_f32 v[66:67], v[30:31], v[58:59] op_sel_hi:[1,0]
	v_pk_mul_f32 v[58:59], v[28:29], v[58:59] op_sel_hi:[1,0]
	v_pk_fma_f32 v[64:65], v[50:51], v[64:65], v[66:67]
	v_mul_f32_e32 v66, v49, v25
	v_mul_f32_e32 v67, v51, v27
	v_fmac_f32_e32 v66, v48, v24
	v_fmac_f32_e32 v67, v50, v26
	v_pk_fma_f32 v[58:59], v[48:49], v[144:145], v[58:59]
	v_add_f32_e32 v73, v66, v67
	v_mul_f32_e32 v66, v147, v57
	v_pk_fma_f32 v[64:65], v[22:23], v[66:67], v[64:65] op_sel_hi:[1,0,1]
	v_pk_fma_f32 v[66:67], v[20:21], v[66:67], v[58:59] op_sel_hi:[1,0,1]
	v_mul_f32_e32 v58, v49, v17
	v_mul_f32_e32 v49, v49, v13
	v_fmac_f32_e32 v58, v48, v16
	v_mul_f32_e32 v59, v51, v19
	v_fmac_f32_e32 v49, v48, v12
	v_mul_f32_e32 v48, v51, v15
	v_fmac_f32_e32 v59, v50, v18
	v_fmac_f32_e32 v48, v50, v14
	v_add_f32_e32 v74, v58, v59
	v_add_f32_e32 v49, v49, v48
	ds_bpermute_b32 v50, v156, v72
	ds_bpermute_b32 v51, v156, v73
	ds_bpermute_b32 v75, v156, v74
	ds_bpermute_b32 v84, v156, v49
	ds_read2st64_b32 v[58:59], v94 offset0:25 offset1:29
	s_waitcnt lgkmcnt(4)
	v_add_f32_e32 v50, v72, v50
	s_waitcnt lgkmcnt(3)
	v_add_f32_e32 v51, v73, v51
	s_waitcnt lgkmcnt(2)
	v_add_f32_e32 v74, v74, v75
	s_waitcnt lgkmcnt(1)
	v_add_f32_e32 v49, v49, v84
	ds_bpermute_b32 v75, v157, v50
	ds_bpermute_b32 v84, v157, v51
	ds_bpermute_b32 v85, v157, v74
	ds_bpermute_b32 v86, v157, v49
	s_waitcnt lgkmcnt(4)
	v_mul_f32_e32 v48, v148, v58
	v_pk_fma_f32 v[72:73], v[4:5], v[48:49], v[66:67] op_sel_hi:[1,0,1]
	s_waitcnt lgkmcnt(3)
	v_add_f32_e32 v50, v50, v75
	s_waitcnt lgkmcnt(2)
	v_add_f32_e32 v51, v51, v84
	s_waitcnt lgkmcnt(1)
	v_add_f32_e32 v66, v74, v85
	s_waitcnt lgkmcnt(0)
	v_add_f32_e32 v49, v49, v86
	ds_bpermute_b32 v67, v158, v50
	ds_bpermute_b32 v84, v158, v51
	ds_bpermute_b32 v85, v158, v66
	ds_bpermute_b32 v86, v158, v49
	v_pk_fma_f32 v[74:75], v[6:7], v[48:49], v[64:65] op_sel_hi:[1,0,1]
	s_waitcnt lgkmcnt(3)
	v_add_f32_e32 v48, v50, v67
	s_waitcnt lgkmcnt(2)
	v_add_f32_e32 v50, v51, v84
	s_waitcnt lgkmcnt(1)
	v_add_f32_e32 v51, v66, v85
	s_waitcnt lgkmcnt(0)
	v_add_f32_e32 v64, v49, v86
	ds_bpermute_b32 v49, v159, v48
	ds_bpermute_b32 v65, v159, v50
	ds_bpermute_b32 v66, v159, v51
	ds_bpermute_b32 v67, v159, v64
	v_mul_f32_e32 v84, v149, v59
	s_waitcnt lgkmcnt(3)
	v_add_f32_e32 v48, v48, v49
	s_waitcnt lgkmcnt(2)
	v_add_f32_e32 v49, v50, v65
	s_waitcnt lgkmcnt(1)
	v_add_f32_e32 v50, v51, v66
	s_waitcnt lgkmcnt(0)
	v_add_f32_e32 v64, v64, v67
	ds_bpermute_b32 v51, v160, v48
	ds_bpermute_b32 v65, v160, v49
	ds_bpermute_b32 v66, v160, v50
	ds_bpermute_b32 v67, v160, v64
	v_pk_fma_f32 v[74:75], v[2:3], v[84:85], v[74:75] op_sel_hi:[1,0,1]
	v_pk_fma_f32 v[72:73], v[0:1], v[84:85], v[72:73] op_sel_hi:[1,0,1]
	v_lshl_add_u64 v[84:85], v[150:151], 0, v[122:123]
	global_store_dwordx4 v[84:85], v[72:75], off nt
	s_and_saveexec_b64 s[18:19], s[14:15]
	s_cbranch_execz .LBB0_419
	s_waitcnt lgkmcnt(2)
	v_add_f32_e32 v49, v49, v65
	v_add_f32_e32 v48, v48, v51
	v_mul_f32_e32 v48, v194, v48
	v_mul_f32_e32 v49, v191, v49
	v_fmac_f32_e32 v48, v195, v56
	v_fmac_f32_e32 v49, v197, v56
	v_fmac_f32_e32 v48, 0, v57
	v_fmac_f32_e32 v49, v196, v57
	v_fmac_f32_e32 v48, 0, v58
	v_fmac_f32_e32 v49, 0, v58
	v_fmac_f32_e32 v48, 0, v59
	v_fmac_f32_e32 v49, 0, v59
	s_waitcnt lgkmcnt(0)
	v_add_f32_e32 v64, v64, v67
	v_add_f32_e32 v50, v50, v66
	v_mul_f32_e32 v48, v198, v48
	v_mul_f32_e32 v49, v199, v49
	ds_write2st64_b32 v92, v48, v49 offset0:33 offset1:37
	v_mul_f32_e32 v48, v190, v50
	v_mul_f32_e32 v49, v144, v64
	v_fmac_f32_e32 v48, v202, v56
	v_fmac_f32_e32 v49, v203, v56
	v_fmac_f32_e32 v48, v201, v57
	v_fmac_f32_e32 v49, v207, v57
	v_fmac_f32_e32 v48, v200, v58
	v_fmac_f32_e32 v49, v206, v58
	v_fmac_f32_e32 v48, 0, v59
	v_fmac_f32_e32 v49, v205, v59
	v_mul_f32_e32 v48, v204, v48
	v_mul_f32_e32 v49, v208, v49
	ds_write2st64_b32 v92, v48, v49 offset0:41 offset1:45
.LBB0_419:
	s_or_b64 exec, exec, s[18:19]
	s_waitcnt lgkmcnt(3)
	ds_read2st64_b32 v[50:51], v91 offset0:17 offset1:21
	v_mul_f32_e32 v48, v41, v33
	v_mul_f32_e32 v49, v43, v35
	v_fmac_f32_e32 v48, v40, v32
	v_fmac_f32_e32 v49, v42, v34
	s_waitcnt lgkmcnt(3)
	v_add_f32_e32 v65, v48, v49
	s_waitcnt lgkmcnt(0)
	v_mul_f32_e32 v48, v146, v50
	v_mul_f32_e32 v64, v41, v25
	v_mul_f32_e32 v66, v43, v27
	v_pk_mul_f32 v[56:57], v[30:31], v[48:49] op_sel_hi:[1,0]
	v_pk_mul_f32 v[58:59], v[28:29], v[48:49] op_sel_hi:[1,0]
	v_mov_b32_e32 v48, v144
	v_mov_b32_e32 v49, v144
	v_fmac_f32_e32 v64, v40, v24
	v_fmac_f32_e32 v66, v42, v26
	v_pk_fma_f32 v[56:57], v[42:43], v[48:49], v[56:57]
	v_add_f32_e32 v72, v64, v66
	v_mul_f32_e32 v64, v147, v51
	v_pk_fma_f32 v[58:59], v[40:41], v[144:145], v[58:59]
	v_pk_fma_f32 v[66:67], v[22:23], v[64:65], v[56:57] op_sel_hi:[1,0,1]
	v_mul_f32_e32 v56, v41, v17
	v_mul_f32_e32 v41, v41, v13
	v_fmac_f32_e32 v56, v40, v16
	v_mul_f32_e32 v57, v43, v19
	v_fmac_f32_e32 v41, v40, v12
	v_mul_f32_e32 v40, v43, v15
	v_fmac_f32_e32 v57, v42, v18
	v_fmac_f32_e32 v40, v42, v14
	v_pk_fma_f32 v[58:59], v[20:21], v[64:65], v[58:59] op_sel_hi:[1,0,1]
	v_add_f32_e32 v64, v56, v57
	v_add_f32_e32 v41, v41, v40
	ds_bpermute_b32 v42, v156, v65
	ds_bpermute_b32 v43, v156, v72
	ds_bpermute_b32 v73, v156, v64
	ds_bpermute_b32 v74, v156, v41
	ds_read2st64_b32 v[56:57], v91 offset0:25 offset1:29
	s_waitcnt lgkmcnt(4)
	v_add_f32_e32 v42, v65, v42
	s_waitcnt lgkmcnt(3)
	v_add_f32_e32 v43, v72, v43
	s_waitcnt lgkmcnt(2)
	v_add_f32_e32 v64, v64, v73
	s_waitcnt lgkmcnt(1)
	v_add_f32_e32 v41, v41, v74
	ds_bpermute_b32 v65, v157, v42
	ds_bpermute_b32 v74, v157, v43
	ds_bpermute_b32 v75, v157, v64
	ds_bpermute_b32 v84, v157, v41
	s_waitcnt lgkmcnt(4)
	v_mul_f32_e32 v40, v148, v56
	v_pk_fma_f32 v[72:73], v[4:5], v[40:41], v[58:59] op_sel_hi:[1,0,1]
	s_waitcnt lgkmcnt(3)
	v_add_f32_e32 v42, v42, v65
	s_waitcnt lgkmcnt(2)
	v_add_f32_e32 v43, v43, v74
	s_waitcnt lgkmcnt(1)
	v_add_f32_e32 v58, v64, v75
	s_waitcnt lgkmcnt(0)
	v_add_f32_e32 v41, v41, v84
	ds_bpermute_b32 v59, v158, v42
	ds_bpermute_b32 v64, v158, v43
	ds_bpermute_b32 v65, v158, v58
	ds_bpermute_b32 v74, v158, v41
	v_pk_fma_f32 v[66:67], v[6:7], v[40:41], v[66:67] op_sel_hi:[1,0,1]
	s_waitcnt lgkmcnt(3)
	v_add_f32_e32 v40, v42, v59
	s_waitcnt lgkmcnt(2)
	v_add_f32_e32 v42, v43, v64
	s_waitcnt lgkmcnt(1)
	v_add_f32_e32 v43, v58, v65
	s_waitcnt lgkmcnt(0)
	v_add_f32_e32 v58, v41, v74
	ds_bpermute_b32 v41, v159, v40
	ds_bpermute_b32 v59, v159, v42
	ds_bpermute_b32 v64, v159, v43
	ds_bpermute_b32 v65, v159, v58
	v_mul_f32_e32 v84, v149, v57
	s_waitcnt lgkmcnt(3)
	v_add_f32_e32 v40, v40, v41
	s_waitcnt lgkmcnt(2)
	v_add_f32_e32 v41, v42, v59
	s_waitcnt lgkmcnt(1)
	v_add_f32_e32 v42, v43, v64
	s_waitcnt lgkmcnt(0)
	v_add_f32_e32 v58, v58, v65
	ds_bpermute_b32 v43, v160, v40
	ds_bpermute_b32 v59, v160, v41
	ds_bpermute_b32 v64, v160, v42
	ds_bpermute_b32 v65, v160, v58
	v_pk_fma_f32 v[74:75], v[2:3], v[84:85], v[66:67] op_sel_hi:[1,0,1]
	v_pk_fma_f32 v[72:73], v[0:1], v[84:85], v[72:73] op_sel_hi:[1,0,1]
	v_lshl_add_u64 v[66:67], v[150:151], 0, v[124:125]
	global_store_dwordx4 v[66:67], v[72:75], off nt
	s_and_saveexec_b64 s[18:19], s[14:15]
	s_cbranch_execz .LBB0_421
	s_waitcnt lgkmcnt(2)
	v_add_f32_e32 v41, v41, v59
	v_add_f32_e32 v40, v40, v43
	v_mul_f32_e32 v40, v194, v40
	v_mul_f32_e32 v41, v191, v41
	v_fmac_f32_e32 v40, v195, v50
	v_fmac_f32_e32 v41, v197, v50
	v_fmac_f32_e32 v40, 0, v51
	v_fmac_f32_e32 v41, v196, v51
	v_fmac_f32_e32 v40, 0, v56
	v_fmac_f32_e32 v41, 0, v56
	v_fmac_f32_e32 v40, 0, v57
	v_fmac_f32_e32 v41, 0, v57
	s_waitcnt lgkmcnt(0)
	v_add_f32_e32 v58, v58, v65
	v_add_f32_e32 v42, v42, v64
	v_mul_f32_e32 v40, v198, v40
	v_mul_f32_e32 v41, v199, v41
	ds_write2st64_b32 v90, v40, v41 offset0:34 offset1:38
	v_mul_f32_e32 v40, v190, v42
	v_mul_f32_e32 v41, v144, v58
	v_fmac_f32_e32 v40, v202, v50
	v_fmac_f32_e32 v41, v203, v50
	v_fmac_f32_e32 v40, v201, v51
	v_fmac_f32_e32 v41, v207, v51
	v_fmac_f32_e32 v40, v200, v56
	v_fmac_f32_e32 v41, v206, v56
	v_fmac_f32_e32 v40, 0, v57
	v_fmac_f32_e32 v41, v205, v57
	v_mul_f32_e32 v40, v204, v40
	v_mul_f32_e32 v41, v208, v41
	ds_write2st64_b32 v90, v40, v41 offset0:42 offset1:46
.LBB0_421:
	s_or_b64 exec, exec, s[18:19]
	ds_read2st64_b32 v[40:41], v170 offset0:18 offset1:22
	s_waitcnt vmcnt(15)
	v_mul_f32_e32 v42, v81, v33
	s_waitcnt lgkmcnt(4)
	v_mul_f32_e32 v43, v83, v35
	v_fmac_f32_e32 v42, v80, v32
	v_fmac_f32_e32 v43, v82, v34
	v_add_f32_e32 v57, v42, v43
	s_waitcnt lgkmcnt(0)
	v_mul_f32_e32 v42, v146, v40
	v_pk_mul_f32 v[50:51], v[30:31], v[42:43] op_sel_hi:[1,0]
	v_pk_mul_f32 v[42:43], v[28:29], v[42:43] op_sel_hi:[1,0]
	v_pk_fma_f32 v[48:49], v[48:49], v[82:83], v[50:51]
	v_mul_f32_e32 v50, v81, v25
	v_mul_f32_e32 v51, v83, v27
	v_fmac_f32_e32 v50, v80, v24
	v_fmac_f32_e32 v51, v82, v26
	v_pk_fma_f32 v[42:43], v[144:145], v[80:81], v[42:43]
	v_add_f32_e32 v58, v50, v51
	v_mul_f32_e32 v50, v147, v41
	v_pk_fma_f32 v[48:49], v[22:23], v[50:51], v[48:49] op_sel_hi:[1,0,1]
	v_pk_fma_f32 v[50:51], v[20:21], v[50:51], v[42:43] op_sel_hi:[1,0,1]
	v_mul_f32_e32 v42, v81, v17
	v_mul_f32_e32 v43, v83, v19
	v_mul_f32_e32 v56, v81, v13
	v_mul_f32_e32 v64, v83, v15
	v_fmac_f32_e32 v42, v80, v16
	v_fmac_f32_e32 v43, v82, v18
	v_fmac_f32_e32 v56, v80, v12
	v_fmac_f32_e32 v64, v82, v14
	v_add_f32_e32 v59, v42, v43
	v_add_f32_e32 v64, v56, v64
	ds_bpermute_b32 v65, v156, v57
	ds_bpermute_b32 v66, v156, v58
	ds_bpermute_b32 v67, v156, v59
	ds_bpermute_b32 v72, v156, v64
	ds_read2st64_b32 v[42:43], v170 offset0:26 offset1:30
	s_waitcnt lgkmcnt(4)
	v_add_f32_e32 v57, v57, v65
	s_waitcnt lgkmcnt(3)
	v_add_f32_e32 v58, v58, v66
	s_waitcnt lgkmcnt(2)
	v_add_f32_e32 v59, v59, v67
	s_waitcnt lgkmcnt(1)
	v_add_f32_e32 v66, v64, v72
	ds_bpermute_b32 v67, v157, v57
	ds_bpermute_b32 v72, v157, v58
	ds_bpermute_b32 v73, v157, v59
	ds_bpermute_b32 v74, v157, v66
	s_waitcnt lgkmcnt(4)
	v_mul_f32_e32 v56, v148, v42
	v_pk_fma_f32 v[64:65], v[4:5], v[56:57], v[50:51] op_sel_hi:[1,0,1]
	s_waitcnt lgkmcnt(3)
	v_add_f32_e32 v50, v57, v67
	s_waitcnt lgkmcnt(2)
	v_add_f32_e32 v51, v58, v72
	s_waitcnt lgkmcnt(1)
	v_add_f32_e32 v57, v59, v73
	s_waitcnt lgkmcnt(0)
	v_add_f32_e32 v58, v66, v74
	ds_bpermute_b32 v59, v158, v50
	ds_bpermute_b32 v72, v158, v51
	ds_bpermute_b32 v73, v158, v57
	ds_bpermute_b32 v74, v158, v58
	v_pk_fma_f32 v[66:67], v[6:7], v[56:57], v[48:49] op_sel_hi:[1,0,1]
	s_waitcnt lgkmcnt(3)
	v_add_f32_e32 v48, v50, v59
	s_waitcnt lgkmcnt(2)
	v_add_f32_e32 v49, v51, v72
	s_waitcnt lgkmcnt(1)
	v_add_f32_e32 v50, v57, v73
	s_waitcnt lgkmcnt(0)
	v_add_f32_e32 v51, v58, v74
	ds_bpermute_b32 v56, v159, v48
	ds_bpermute_b32 v57, v159, v49
	ds_bpermute_b32 v58, v159, v50
	ds_bpermute_b32 v59, v159, v51
	v_mul_f32_e32 v72, v149, v43
	s_waitcnt lgkmcnt(3)
	v_add_f32_e32 v48, v48, v56
	s_waitcnt lgkmcnt(2)
	v_add_f32_e32 v49, v49, v57
	s_waitcnt lgkmcnt(1)
	v_add_f32_e32 v50, v50, v58
	s_waitcnt lgkmcnt(0)
	v_add_f32_e32 v56, v51, v59
	ds_bpermute_b32 v51, v160, v48
	ds_bpermute_b32 v57, v160, v49
	ds_bpermute_b32 v58, v160, v50
	ds_bpermute_b32 v59, v160, v56
	v_pk_fma_f32 v[66:67], v[2:3], v[72:73], v[66:67] op_sel_hi:[1,0,1]
	v_pk_fma_f32 v[64:65], v[0:1], v[72:73], v[64:65] op_sel_hi:[1,0,1]
	v_lshl_add_u64 v[72:73], v[150:151], 0, v[128:129]
	global_store_dwordx4 v[72:73], v[64:67], off nt
	s_and_saveexec_b64 s[18:19], s[14:15]
	s_cbranch_execz .LBB0_423
	s_waitcnt lgkmcnt(2)
	v_add_f32_e32 v49, v49, v57
	v_add_f32_e32 v48, v48, v51
	v_mul_f32_e32 v48, v194, v48
	v_mul_f32_e32 v49, v191, v49
	v_fmac_f32_e32 v48, v195, v40
	v_fmac_f32_e32 v49, v197, v40
	v_fmac_f32_e32 v48, 0, v41
	v_fmac_f32_e32 v49, v196, v41
	v_fmac_f32_e32 v48, 0, v42
	v_fmac_f32_e32 v49, 0, v42
	v_fmac_f32_e32 v48, 0, v43
	v_fmac_f32_e32 v49, 0, v43
	s_waitcnt lgkmcnt(0)
	v_add_f32_e32 v56, v56, v59
	v_add_f32_e32 v50, v50, v58
	v_mul_f32_e32 v48, v198, v48
	v_mul_f32_e32 v49, v199, v49
	ds_write2st64_b32 v209, v48, v49 offset0:34 offset1:38
	v_mul_f32_e32 v48, v190, v50
	v_mul_f32_e32 v49, v144, v56
	v_fmac_f32_e32 v48, v202, v40
	v_fmac_f32_e32 v49, v203, v40
	v_fmac_f32_e32 v48, v201, v41
	v_fmac_f32_e32 v49, v207, v41
	v_fmac_f32_e32 v48, v200, v42
	v_fmac_f32_e32 v49, v206, v42
	v_fmac_f32_e32 v48, 0, v43
	v_fmac_f32_e32 v49, v205, v43
	v_mul_f32_e32 v48, v204, v48
	v_mul_f32_e32 v40, v208, v49
	ds_write2st64_b32 v209, v48, v40 offset0:42 offset1:46
.LBB0_423:
	s_or_b64 exec, exec, s[18:19]
	ds_read2st64_b32 v[42:43], v155 offset0:18 offset1:22
	s_waitcnt vmcnt(15)
	v_mul_f32_e32 v40, v77, v33
	v_mul_f32_e32 v41, v79, v35
	v_fmac_f32_e32 v40, v76, v32
	v_fmac_f32_e32 v41, v78, v34
	s_waitcnt lgkmcnt(3)
	v_add_f32_e32 v57, v40, v41
	s_waitcnt lgkmcnt(0)
	v_mul_f32_e32 v40, v146, v42
	v_mul_f32_e32 v56, v77, v25
	v_mul_f32_e32 v58, v79, v27
	v_pk_mul_f32 v[48:49], v[30:31], v[40:41] op_sel_hi:[1,0]
	v_pk_mul_f32 v[50:51], v[28:29], v[40:41] op_sel_hi:[1,0]
	v_mov_b32_e32 v40, v144
	v_mov_b32_e32 v41, v144
	v_fmac_f32_e32 v56, v76, v24
	v_fmac_f32_e32 v58, v78, v26
	v_pk_fma_f32 v[48:49], v[40:41], v[78:79], v[48:49]
	v_pk_fma_f32 v[50:51], v[144:145], v[76:77], v[50:51]
	v_add_f32_e32 v64, v56, v58
	v_mul_f32_e32 v56, v147, v43
	v_pk_fma_f32 v[58:59], v[22:23], v[56:57], v[48:49] op_sel_hi:[1,0,1]
	v_pk_fma_f32 v[50:51], v[20:21], v[56:57], v[50:51] op_sel_hi:[1,0,1]
	v_mul_f32_e32 v48, v77, v17
	v_mul_f32_e32 v49, v79, v19
	v_mul_f32_e32 v56, v77, v13
	v_mul_f32_e32 v66, v79, v15
	v_fmac_f32_e32 v48, v76, v16
	v_fmac_f32_e32 v49, v78, v18
	v_fmac_f32_e32 v56, v76, v12
	v_fmac_f32_e32 v66, v78, v14
	v_add_f32_e32 v65, v48, v49
	v_add_f32_e32 v66, v56, v66
	ds_bpermute_b32 v67, v156, v57
	ds_bpermute_b32 v72, v156, v64
	ds_bpermute_b32 v73, v156, v65
	ds_bpermute_b32 v74, v156, v66
	ds_read2st64_b32 v[48:49], v155 offset0:26 offset1:30
	s_waitcnt lgkmcnt(4)
	v_add_f32_e32 v57, v57, v67
	s_waitcnt lgkmcnt(3)
	v_add_f32_e32 v64, v64, v72
	s_waitcnt lgkmcnt(2)
	v_add_f32_e32 v65, v65, v73
	s_waitcnt lgkmcnt(1)
	v_add_f32_e32 v72, v66, v74
	ds_bpermute_b32 v73, v157, v57
	ds_bpermute_b32 v74, v157, v64
	ds_bpermute_b32 v75, v157, v65
	ds_bpermute_b32 v76, v157, v72
	s_waitcnt lgkmcnt(4)
	v_mul_f32_e32 v56, v148, v48
	v_pk_fma_f32 v[66:67], v[4:5], v[56:57], v[50:51] op_sel_hi:[1,0,1]
	s_waitcnt lgkmcnt(3)
	v_add_f32_e32 v50, v57, v73
	s_waitcnt lgkmcnt(2)
	v_add_f32_e32 v51, v64, v74
	s_waitcnt lgkmcnt(1)
	v_add_f32_e32 v57, v65, v75
	s_waitcnt lgkmcnt(0)
	v_add_f32_e32 v64, v72, v76
	ds_bpermute_b32 v65, v158, v50
	ds_bpermute_b32 v74, v158, v51
	ds_bpermute_b32 v75, v158, v57
	ds_bpermute_b32 v76, v158, v64
	v_pk_fma_f32 v[72:73], v[6:7], v[56:57], v[58:59] op_sel_hi:[1,0,1]
	s_waitcnt lgkmcnt(3)
	v_add_f32_e32 v50, v50, v65
	s_waitcnt lgkmcnt(2)
	v_add_f32_e32 v51, v51, v74
	s_waitcnt lgkmcnt(1)
	v_add_f32_e32 v56, v57, v75
	s_waitcnt lgkmcnt(0)
	v_add_f32_e32 v57, v64, v76
	ds_bpermute_b32 v58, v159, v50
	ds_bpermute_b32 v59, v159, v51
	ds_bpermute_b32 v64, v159, v56
	ds_bpermute_b32 v65, v159, v57
	v_mul_f32_e32 v76, v149, v49
	s_waitcnt lgkmcnt(3)
	v_add_f32_e32 v50, v50, v58
	s_waitcnt lgkmcnt(2)
	v_add_f32_e32 v51, v51, v59
	s_waitcnt lgkmcnt(1)
	v_add_f32_e32 v56, v56, v64
	s_waitcnt lgkmcnt(0)
	v_add_f32_e32 v58, v57, v65
	ds_bpermute_b32 v57, v160, v50
	ds_bpermute_b32 v59, v160, v51
	ds_bpermute_b32 v64, v160, v56
	ds_bpermute_b32 v65, v160, v58
	v_pk_fma_f32 v[74:75], v[2:3], v[76:77], v[72:73] op_sel_hi:[1,0,1]
	v_pk_fma_f32 v[72:73], v[0:1], v[76:77], v[66:67] op_sel_hi:[1,0,1]
	v_lshl_add_u64 v[66:67], v[150:151], 0, v[130:131]
	global_store_dwordx4 v[66:67], v[72:75], off nt
	s_and_saveexec_b64 s[18:19], s[14:15]
	s_cbranch_execz .LBB0_425
	s_waitcnt lgkmcnt(2)
	v_add_f32_e32 v51, v51, v59
	v_add_f32_e32 v50, v50, v57
	v_mul_f32_e32 v50, v194, v50
	v_mul_f32_e32 v51, v191, v51
	v_fmac_f32_e32 v50, v195, v42
	v_fmac_f32_e32 v51, v197, v42
	v_fmac_f32_e32 v50, 0, v43
	v_fmac_f32_e32 v51, v196, v43
	v_fmac_f32_e32 v50, 0, v48
	v_fmac_f32_e32 v51, 0, v48
	v_fmac_f32_e32 v50, 0, v49
	v_fmac_f32_e32 v51, 0, v49
	s_waitcnt lgkmcnt(0)
	v_add_f32_e32 v58, v58, v65
	v_add_f32_e32 v56, v56, v64
	v_mul_f32_e32 v50, v198, v50
	v_mul_f32_e32 v51, v199, v51
	ds_write2st64_b32 v154, v50, v51 offset0:34 offset1:38
	v_mul_f32_e32 v50, v190, v56
	v_mul_f32_e32 v51, v144, v58
	v_fmac_f32_e32 v50, v202, v42
	v_fmac_f32_e32 v51, v203, v42
	v_fmac_f32_e32 v50, v201, v43
	v_fmac_f32_e32 v51, v207, v43
	v_fmac_f32_e32 v50, v200, v48
	v_fmac_f32_e32 v51, v206, v48
	v_fmac_f32_e32 v50, 0, v49
	v_fmac_f32_e32 v51, v205, v49
	v_mul_f32_e32 v50, v204, v50
	v_mul_f32_e32 v42, v208, v51
	ds_write2st64_b32 v154, v50, v42 offset0:42 offset1:46
.LBB0_425:
	s_or_b64 exec, exec, s[18:19]
	ds_read2st64_b32 v[42:43], v94 offset0:18 offset1:22
	s_waitcnt vmcnt(15)
	v_mul_f32_e32 v48, v69, v33
	v_mul_f32_e32 v49, v71, v35
	v_fmac_f32_e32 v48, v68, v32
	v_fmac_f32_e32 v49, v70, v34
	v_add_f32_e32 v58, v48, v49
	s_waitcnt lgkmcnt(0)
	v_mul_f32_e32 v48, v146, v42
	v_pk_mul_f32 v[50:51], v[30:31], v[48:49] op_sel_hi:[1,0]
	v_pk_mul_f32 v[48:49], v[28:29], v[48:49] op_sel_hi:[1,0]
	v_pk_fma_f32 v[40:41], v[40:41], v[70:71], v[50:51]
	v_mul_f32_e32 v50, v69, v25
	v_mul_f32_e32 v51, v71, v27
	v_fmac_f32_e32 v50, v68, v24
	v_fmac_f32_e32 v51, v70, v26
	v_pk_fma_f32 v[48:49], v[144:145], v[68:69], v[48:49]
	v_add_f32_e32 v51, v50, v51
	v_mul_f32_e32 v50, v147, v43
	v_pk_fma_f32 v[56:57], v[22:23], v[50:51], v[40:41] op_sel_hi:[1,0,1]
	v_pk_fma_f32 v[48:49], v[20:21], v[50:51], v[48:49] op_sel_hi:[1,0,1]
	v_mul_f32_e32 v40, v69, v17
	v_mul_f32_e32 v41, v71, v19
	v_mul_f32_e32 v50, v69, v13
	v_mul_f32_e32 v64, v71, v15
	v_fmac_f32_e32 v40, v68, v16
	v_fmac_f32_e32 v41, v70, v18
	v_fmac_f32_e32 v50, v68, v12
	v_fmac_f32_e32 v64, v70, v14
	v_add_f32_e32 v59, v40, v41
	v_add_f32_e32 v64, v50, v64
	ds_bpermute_b32 v65, v156, v58
	ds_bpermute_b32 v66, v156, v51
	ds_bpermute_b32 v67, v156, v59
	ds_bpermute_b32 v68, v156, v64
	ds_read2st64_b32 v[40:41], v94 offset0:26 offset1:30
	s_waitcnt lgkmcnt(4)
	v_add_f32_e32 v58, v58, v65
	s_waitcnt lgkmcnt(3)
	v_add_f32_e32 v51, v51, v66
	s_waitcnt lgkmcnt(2)
	v_add_f32_e32 v59, v59, v67
	s_waitcnt lgkmcnt(1)
	v_add_f32_e32 v66, v64, v68
	ds_bpermute_b32 v67, v157, v58
	ds_bpermute_b32 v68, v157, v51
	ds_bpermute_b32 v69, v157, v59
	ds_bpermute_b32 v70, v157, v66
	s_waitcnt lgkmcnt(4)
	v_mul_f32_e32 v50, v148, v40
	v_pk_fma_f32 v[64:65], v[4:5], v[50:51], v[48:49] op_sel_hi:[1,0,1]
	s_waitcnt lgkmcnt(3)
	v_add_f32_e32 v48, v58, v67
	s_waitcnt lgkmcnt(2)
	v_add_f32_e32 v49, v51, v68
	s_waitcnt lgkmcnt(1)
	v_add_f32_e32 v51, v59, v69
	s_waitcnt lgkmcnt(0)
	v_add_f32_e32 v58, v66, v70
	ds_bpermute_b32 v59, v158, v48
	ds_bpermute_b32 v68, v158, v49
	ds_bpermute_b32 v69, v158, v51
	ds_bpermute_b32 v70, v158, v58
	v_pk_fma_f32 v[66:67], v[6:7], v[50:51], v[56:57] op_sel_hi:[1,0,1]
	s_waitcnt lgkmcnt(3)
	v_add_f32_e32 v48, v48, v59
	s_waitcnt lgkmcnt(2)
	v_add_f32_e32 v49, v49, v68
	s_waitcnt lgkmcnt(1)
	v_add_f32_e32 v50, v51, v69
	s_waitcnt lgkmcnt(0)
	v_add_f32_e32 v51, v58, v70
	ds_bpermute_b32 v56, v159, v48
	ds_bpermute_b32 v57, v159, v49
	ds_bpermute_b32 v58, v159, v50
	ds_bpermute_b32 v59, v159, v51
	v_mul_f32_e32 v68, v149, v41
	s_waitcnt lgkmcnt(3)
	v_add_f32_e32 v48, v48, v56
	s_waitcnt lgkmcnt(2)
	v_add_f32_e32 v49, v49, v57
	s_waitcnt lgkmcnt(1)
	v_add_f32_e32 v50, v50, v58
	s_waitcnt lgkmcnt(0)
	v_add_f32_e32 v56, v51, v59
	ds_bpermute_b32 v51, v160, v48
	ds_bpermute_b32 v57, v160, v49
	ds_bpermute_b32 v58, v160, v50
	ds_bpermute_b32 v59, v160, v56
	v_pk_fma_f32 v[66:67], v[2:3], v[68:69], v[66:67] op_sel_hi:[1,0,1]
	v_pk_fma_f32 v[64:65], v[0:1], v[68:69], v[64:65] op_sel_hi:[1,0,1]
	v_lshl_add_u64 v[68:69], v[150:151], 0, v[132:133]
	global_store_dwordx4 v[68:69], v[64:67], off nt
	s_and_saveexec_b64 s[18:19], s[14:15]
	s_cbranch_execz .LBB0_427
	s_waitcnt lgkmcnt(2)
	v_add_f32_e32 v49, v49, v57
	v_add_f32_e32 v48, v48, v51
	v_mul_f32_e32 v48, v194, v48
	v_mul_f32_e32 v49, v191, v49
	v_fmac_f32_e32 v48, v195, v42
	v_fmac_f32_e32 v49, v197, v42
	v_fmac_f32_e32 v48, 0, v43
	v_fmac_f32_e32 v49, v196, v43
	v_fmac_f32_e32 v48, 0, v40
	v_fmac_f32_e32 v49, 0, v40
	v_fmac_f32_e32 v48, 0, v41
	v_fmac_f32_e32 v49, 0, v41
	s_waitcnt lgkmcnt(0)
	v_add_f32_e32 v56, v56, v59
	v_add_f32_e32 v50, v50, v58
	v_mul_f32_e32 v48, v198, v48
	v_mul_f32_e32 v49, v199, v49
	ds_write2st64_b32 v92, v48, v49 offset0:34 offset1:38
	v_mul_f32_e32 v48, v190, v50
	v_mul_f32_e32 v49, v144, v56
	v_fmac_f32_e32 v48, v202, v42
	v_fmac_f32_e32 v49, v203, v42
	v_fmac_f32_e32 v48, v201, v43
	v_fmac_f32_e32 v49, v207, v43
	v_fmac_f32_e32 v48, v200, v40
	v_fmac_f32_e32 v49, v206, v40
	v_fmac_f32_e32 v48, 0, v41
	v_fmac_f32_e32 v49, v205, v41
	v_mul_f32_e32 v48, v204, v48
	v_mul_f32_e32 v40, v208, v49
	ds_write2st64_b32 v92, v48, v40 offset0:42 offset1:46
.LBB0_427:
	s_or_b64 exec, exec, s[18:19]
	ds_read2st64_b32 v[42:43], v91 offset0:18 offset1:22
	s_waitcnt vmcnt(15)
	v_mul_f32_e32 v40, v61, v33
	v_mul_f32_e32 v41, v63, v35
	v_fmac_f32_e32 v40, v60, v32
	v_fmac_f32_e32 v41, v62, v34
	s_waitcnt lgkmcnt(3)
	v_add_f32_e32 v57, v40, v41
	s_waitcnt lgkmcnt(0)
	v_mul_f32_e32 v40, v146, v42
	v_mul_f32_e32 v56, v61, v25
	v_mul_f32_e32 v58, v63, v27
	v_pk_mul_f32 v[48:49], v[30:31], v[40:41] op_sel_hi:[1,0]
	v_pk_mul_f32 v[50:51], v[28:29], v[40:41] op_sel_hi:[1,0]
	v_mov_b32_e32 v40, v144
	v_mov_b32_e32 v41, v144
	v_fmac_f32_e32 v56, v60, v24
	v_fmac_f32_e32 v58, v62, v26
	v_pk_fma_f32 v[48:49], v[40:41], v[62:63], v[48:49]
	v_pk_fma_f32 v[50:51], v[144:145], v[60:61], v[50:51]
	v_add_f32_e32 v64, v56, v58
	v_mul_f32_e32 v56, v147, v43
	v_pk_fma_f32 v[58:59], v[22:23], v[56:57], v[48:49] op_sel_hi:[1,0,1]
	v_pk_fma_f32 v[50:51], v[20:21], v[56:57], v[50:51] op_sel_hi:[1,0,1]
	v_mul_f32_e32 v48, v61, v17
	v_mul_f32_e32 v56, v61, v13
	v_fmac_f32_e32 v48, v60, v16
	v_mul_f32_e32 v49, v63, v19
	v_fmac_f32_e32 v56, v60, v12
	v_mul_f32_e32 v60, v63, v15
	v_fmac_f32_e32 v49, v62, v18
	v_fmac_f32_e32 v60, v62, v14
	v_add_f32_e32 v65, v48, v49
	v_add_f32_e32 v60, v56, v60
	ds_bpermute_b32 v61, v156, v57
	ds_bpermute_b32 v62, v156, v64
	ds_bpermute_b32 v63, v156, v65
	ds_bpermute_b32 v66, v156, v60
	ds_read2st64_b32 v[48:49], v91 offset0:26 offset1:30
	s_waitcnt lgkmcnt(4)
	v_add_f32_e32 v57, v57, v61
	s_waitcnt lgkmcnt(3)
	v_add_f32_e32 v61, v64, v62
	s_waitcnt lgkmcnt(2)
	v_add_f32_e32 v64, v65, v63
	s_waitcnt lgkmcnt(1)
	v_add_f32_e32 v60, v60, v66
	ds_bpermute_b32 v65, v157, v57
	ds_bpermute_b32 v66, v157, v61
	ds_bpermute_b32 v67, v157, v64
	ds_bpermute_b32 v68, v157, v60
	s_waitcnt lgkmcnt(4)
	v_mul_f32_e32 v56, v148, v48
	v_pk_fma_f32 v[62:63], v[4:5], v[56:57], v[50:51] op_sel_hi:[1,0,1]
	s_waitcnt lgkmcnt(3)
	v_add_f32_e32 v50, v57, v65
	s_waitcnt lgkmcnt(2)
	v_add_f32_e32 v51, v61, v66
	s_waitcnt lgkmcnt(1)
	v_add_f32_e32 v57, v64, v67
	s_waitcnt lgkmcnt(0)
	v_add_f32_e32 v60, v60, v68
	ds_bpermute_b32 v61, v158, v50
	ds_bpermute_b32 v66, v158, v51
	ds_bpermute_b32 v67, v158, v57
	ds_bpermute_b32 v68, v158, v60
	v_pk_fma_f32 v[64:65], v[6:7], v[56:57], v[58:59] op_sel_hi:[1,0,1]
	s_waitcnt lgkmcnt(3)
	v_add_f32_e32 v50, v50, v61
	s_waitcnt lgkmcnt(2)
	v_add_f32_e32 v51, v51, v66
	s_waitcnt lgkmcnt(1)
	v_add_f32_e32 v56, v57, v67
	s_waitcnt lgkmcnt(0)
	v_add_f32_e32 v57, v60, v68
	ds_bpermute_b32 v58, v159, v50
	ds_bpermute_b32 v59, v159, v51
	ds_bpermute_b32 v60, v159, v56
	ds_bpermute_b32 v61, v159, v57
	v_mul_f32_e32 v66, v149, v49
	s_waitcnt lgkmcnt(3)
	v_add_f32_e32 v50, v50, v58
	s_waitcnt lgkmcnt(2)
	v_add_f32_e32 v51, v51, v59
	s_waitcnt lgkmcnt(1)
	v_add_f32_e32 v56, v56, v60
	s_waitcnt lgkmcnt(0)
	v_add_f32_e32 v58, v57, v61
	ds_bpermute_b32 v57, v160, v50
	ds_bpermute_b32 v59, v160, v51
	ds_bpermute_b32 v60, v160, v56
	ds_bpermute_b32 v61, v160, v58
	v_pk_fma_f32 v[64:65], v[2:3], v[66:67], v[64:65] op_sel_hi:[1,0,1]
	v_pk_fma_f32 v[62:63], v[0:1], v[66:67], v[62:63] op_sel_hi:[1,0,1]
	v_lshl_add_u64 v[66:67], v[150:151], 0, v[134:135]
	global_store_dwordx4 v[66:67], v[62:65], off nt
	s_and_saveexec_b64 s[18:19], s[14:15]
	s_cbranch_execz .LBB0_429
	s_waitcnt lgkmcnt(2)
	v_add_f32_e32 v51, v51, v59
	v_add_f32_e32 v50, v50, v57
	v_mul_f32_e32 v50, v194, v50
	v_mul_f32_e32 v51, v191, v51
	v_fmac_f32_e32 v50, v195, v42
	v_fmac_f32_e32 v51, v197, v42
	v_fmac_f32_e32 v50, 0, v43
	v_fmac_f32_e32 v51, v196, v43
	v_fmac_f32_e32 v50, 0, v48
	v_fmac_f32_e32 v51, 0, v48
	v_fmac_f32_e32 v50, 0, v49
	v_fmac_f32_e32 v51, 0, v49
	s_waitcnt lgkmcnt(0)
	v_add_f32_e32 v58, v58, v61
	v_add_f32_e32 v56, v56, v60
	v_mul_f32_e32 v50, v198, v50
	v_mul_f32_e32 v51, v199, v51
	ds_write2st64_b32 v90, v50, v51 offset0:35 offset1:39
	v_mul_f32_e32 v50, v190, v56
	v_mul_f32_e32 v51, v144, v58
	v_fmac_f32_e32 v50, v202, v42
	v_fmac_f32_e32 v51, v203, v42
	v_fmac_f32_e32 v50, v201, v43
	v_fmac_f32_e32 v51, v207, v43
	v_fmac_f32_e32 v50, v200, v48
	v_fmac_f32_e32 v51, v206, v48
	v_fmac_f32_e32 v50, 0, v49
	v_fmac_f32_e32 v51, v205, v49
	v_mul_f32_e32 v50, v204, v50
	v_mul_f32_e32 v42, v208, v51
	ds_write2st64_b32 v90, v50, v42 offset0:43 offset1:47
.LBB0_429:
	s_or_b64 exec, exec, s[18:19]
	ds_read2st64_b32 v[42:43], v170 offset0:19 offset1:23
	s_waitcnt vmcnt(15)
	v_mul_f32_e32 v48, v53, v33
	v_mul_f32_e32 v49, v55, v35
	v_fmac_f32_e32 v48, v52, v32
	v_fmac_f32_e32 v49, v54, v34
	v_add_f32_e32 v58, v48, v49
	s_waitcnt lgkmcnt(0)
	v_mul_f32_e32 v48, v146, v42
	v_pk_mul_f32 v[50:51], v[30:31], v[48:49] op_sel_hi:[1,0]
	v_pk_mul_f32 v[48:49], v[28:29], v[48:49] op_sel_hi:[1,0]
	v_pk_fma_f32 v[40:41], v[40:41], v[54:55], v[50:51]
	v_mul_f32_e32 v50, v53, v25
	v_mul_f32_e32 v51, v55, v27
	v_fmac_f32_e32 v50, v52, v24
	v_fmac_f32_e32 v51, v54, v26
	v_pk_fma_f32 v[48:49], v[144:145], v[52:53], v[48:49]
	v_add_f32_e32 v51, v50, v51
	v_mul_f32_e32 v50, v147, v43
	v_pk_fma_f32 v[56:57], v[22:23], v[50:51], v[40:41] op_sel_hi:[1,0,1]
	v_pk_fma_f32 v[48:49], v[20:21], v[50:51], v[48:49] op_sel_hi:[1,0,1]
	v_mul_f32_e32 v40, v53, v17
	v_mul_f32_e32 v50, v53, v13
	v_fmac_f32_e32 v40, v52, v16
	v_mul_f32_e32 v41, v55, v19
	v_fmac_f32_e32 v50, v52, v12
	v_mul_f32_e32 v52, v55, v15
	v_fmac_f32_e32 v41, v54, v18
	v_fmac_f32_e32 v52, v54, v14
	v_add_f32_e32 v59, v40, v41
	v_add_f32_e32 v52, v50, v52
	ds_bpermute_b32 v53, v156, v58
	ds_bpermute_b32 v54, v156, v51
	ds_bpermute_b32 v55, v156, v59
	ds_bpermute_b32 v60, v156, v52
	ds_read2st64_b32 v[40:41], v170 offset0:27 offset1:31
	s_waitcnt lgkmcnt(4)
	v_add_f32_e32 v53, v58, v53
	s_waitcnt lgkmcnt(3)
	v_add_f32_e32 v51, v51, v54
	s_waitcnt lgkmcnt(2)
	v_add_f32_e32 v54, v59, v55
	s_waitcnt lgkmcnt(1)
	v_add_f32_e32 v52, v52, v60
	ds_bpermute_b32 v55, v157, v53
	ds_bpermute_b32 v58, v157, v51
	ds_bpermute_b32 v59, v157, v54
	ds_bpermute_b32 v62, v157, v52
	s_waitcnt lgkmcnt(4)
	v_mul_f32_e32 v50, v148, v40
	v_pk_fma_f32 v[60:61], v[4:5], v[50:51], v[48:49] op_sel_hi:[1,0,1]
	s_waitcnt lgkmcnt(3)
	v_add_f32_e32 v48, v53, v55
	s_waitcnt lgkmcnt(2)
	v_add_f32_e32 v49, v51, v58
	s_waitcnt lgkmcnt(1)
	v_add_f32_e32 v51, v54, v59
	s_waitcnt lgkmcnt(0)
	v_add_f32_e32 v52, v52, v62
	ds_bpermute_b32 v53, v158, v48
	ds_bpermute_b32 v54, v158, v49
	ds_bpermute_b32 v55, v158, v51
	ds_bpermute_b32 v58, v158, v52
	v_pk_fma_f32 v[56:57], v[6:7], v[50:51], v[56:57] op_sel_hi:[1,0,1]
	s_waitcnt lgkmcnt(3)
	v_add_f32_e32 v48, v48, v53
	s_waitcnt lgkmcnt(2)
	v_add_f32_e32 v49, v49, v54
	s_waitcnt lgkmcnt(1)
	v_add_f32_e32 v50, v51, v55
	s_waitcnt lgkmcnt(0)
	v_add_f32_e32 v51, v52, v58
	ds_bpermute_b32 v52, v159, v48
	ds_bpermute_b32 v53, v159, v49
	ds_bpermute_b32 v54, v159, v50
	ds_bpermute_b32 v55, v159, v51
	v_mul_f32_e32 v62, v149, v41
	s_waitcnt lgkmcnt(3)
	v_add_f32_e32 v48, v48, v52
	s_waitcnt lgkmcnt(2)
	v_add_f32_e32 v49, v49, v53
	s_waitcnt lgkmcnt(1)
	v_add_f32_e32 v50, v50, v54
	s_waitcnt lgkmcnt(0)
	v_add_f32_e32 v52, v51, v55
	ds_bpermute_b32 v51, v160, v48
	ds_bpermute_b32 v53, v160, v49
	ds_bpermute_b32 v54, v160, v50
	ds_bpermute_b32 v55, v160, v52
	v_pk_fma_f32 v[58:59], v[2:3], v[62:63], v[56:57] op_sel_hi:[1,0,1]
	v_pk_fma_f32 v[56:57], v[0:1], v[62:63], v[60:61] op_sel_hi:[1,0,1]
	v_lshl_add_u64 v[60:61], v[150:151], 0, v[136:137]
	global_store_dwordx4 v[60:61], v[56:59], off nt
	s_and_saveexec_b64 s[18:19], s[14:15]
	s_cbranch_execz .LBB0_431
	s_waitcnt lgkmcnt(2)
	v_add_f32_e32 v49, v49, v53
	v_add_f32_e32 v48, v48, v51
	v_mul_f32_e32 v48, v194, v48
	v_mul_f32_e32 v49, v191, v49
	v_fmac_f32_e32 v48, v195, v42
	v_fmac_f32_e32 v49, v197, v42
	v_fmac_f32_e32 v48, 0, v43
	v_fmac_f32_e32 v49, v196, v43
	v_fmac_f32_e32 v48, 0, v40
	v_fmac_f32_e32 v49, 0, v40
	v_fmac_f32_e32 v48, 0, v41
	v_fmac_f32_e32 v49, 0, v41
	s_waitcnt lgkmcnt(0)
	v_add_f32_e32 v52, v52, v55
	v_add_f32_e32 v50, v50, v54
	v_mul_f32_e32 v48, v198, v48
	v_mul_f32_e32 v49, v199, v49
	ds_write2st64_b32 v209, v48, v49 offset0:35 offset1:39
	v_mul_f32_e32 v48, v190, v50
	v_mul_f32_e32 v49, v144, v52
	v_fmac_f32_e32 v48, v202, v42
	v_fmac_f32_e32 v49, v203, v42
	v_fmac_f32_e32 v48, v201, v43
	v_fmac_f32_e32 v49, v207, v43
	v_fmac_f32_e32 v48, v200, v40
	v_fmac_f32_e32 v49, v206, v40
	v_fmac_f32_e32 v48, 0, v41
	v_fmac_f32_e32 v49, v205, v41
	v_mul_f32_e32 v48, v204, v48
	v_mul_f32_e32 v40, v208, v49
	ds_write2st64_b32 v209, v48, v40 offset0:43 offset1:47
.LBB0_431:
	s_or_b64 exec, exec, s[18:19]
	ds_read2st64_b32 v[42:43], v155 offset0:19 offset1:23
	s_waitcnt vmcnt(15)
	v_mul_f32_e32 v40, v45, v33
	v_mul_f32_e32 v41, v47, v35
	v_fmac_f32_e32 v40, v44, v32
	v_fmac_f32_e32 v41, v46, v34
	s_waitcnt lgkmcnt(3)
	v_add_f32_e32 v53, v40, v41
	s_waitcnt lgkmcnt(0)
	v_mul_f32_e32 v40, v146, v42
	v_mul_f32_e32 v52, v45, v25
	v_mul_f32_e32 v54, v47, v27
	v_pk_mul_f32 v[48:49], v[30:31], v[40:41] op_sel_hi:[1,0]
	v_pk_mul_f32 v[50:51], v[28:29], v[40:41] op_sel_hi:[1,0]
	v_mov_b32_e32 v40, v144
	v_mov_b32_e32 v41, v144
	v_fmac_f32_e32 v52, v44, v24
	v_fmac_f32_e32 v54, v46, v26
	v_pk_fma_f32 v[48:49], v[40:41], v[46:47], v[48:49]
	v_add_f32_e32 v56, v52, v54
	v_mul_f32_e32 v52, v147, v43
	v_pk_fma_f32 v[50:51], v[144:145], v[44:45], v[50:51]
	v_pk_fma_f32 v[54:55], v[22:23], v[52:53], v[48:49] op_sel_hi:[1,0,1]
	v_mul_f32_e32 v48, v45, v17
	v_mul_f32_e32 v45, v45, v13
	v_fmac_f32_e32 v48, v44, v16
	v_mul_f32_e32 v49, v47, v19
	v_fmac_f32_e32 v45, v44, v12
	v_mul_f32_e32 v44, v47, v15
	v_fmac_f32_e32 v49, v46, v18
	v_fmac_f32_e32 v44, v46, v14
	v_pk_fma_f32 v[50:51], v[20:21], v[52:53], v[50:51] op_sel_hi:[1,0,1]
	v_add_f32_e32 v52, v48, v49
	v_add_f32_e32 v45, v45, v44
	ds_bpermute_b32 v46, v156, v53
	ds_bpermute_b32 v47, v156, v56
	ds_bpermute_b32 v57, v156, v52
	ds_bpermute_b32 v58, v156, v45
	ds_read2st64_b32 v[48:49], v155 offset0:27 offset1:31
	s_waitcnt lgkmcnt(4)
	v_add_f32_e32 v46, v53, v46
	s_waitcnt lgkmcnt(3)
	v_add_f32_e32 v47, v56, v47
	s_waitcnt lgkmcnt(2)
	v_add_f32_e32 v52, v52, v57
	s_waitcnt lgkmcnt(1)
	v_add_f32_e32 v45, v45, v58
	ds_bpermute_b32 v53, v157, v46
	ds_bpermute_b32 v56, v157, v47
	ds_bpermute_b32 v57, v157, v52
	ds_bpermute_b32 v60, v157, v45
	s_waitcnt lgkmcnt(4)
	v_mul_f32_e32 v44, v148, v48
	v_pk_fma_f32 v[58:59], v[4:5], v[44:45], v[50:51] op_sel_hi:[1,0,1]
	s_waitcnt lgkmcnt(3)
	v_add_f32_e32 v46, v46, v53
	s_waitcnt lgkmcnt(2)
	v_add_f32_e32 v47, v47, v56
	s_waitcnt lgkmcnt(1)
	v_add_f32_e32 v50, v52, v57
	s_waitcnt lgkmcnt(0)
	v_add_f32_e32 v45, v45, v60
	ds_bpermute_b32 v51, v158, v46
	ds_bpermute_b32 v52, v158, v47
	ds_bpermute_b32 v53, v158, v50
	ds_bpermute_b32 v56, v158, v45
	v_pk_fma_f32 v[54:55], v[6:7], v[44:45], v[54:55] op_sel_hi:[1,0,1]
	s_waitcnt lgkmcnt(3)
	v_add_f32_e32 v44, v46, v51
	s_waitcnt lgkmcnt(2)
	v_add_f32_e32 v46, v47, v52
	s_waitcnt lgkmcnt(1)
	v_add_f32_e32 v47, v50, v53
	s_waitcnt lgkmcnt(0)
	v_add_f32_e32 v50, v45, v56
	ds_bpermute_b32 v45, v159, v44
	ds_bpermute_b32 v51, v159, v46
	ds_bpermute_b32 v52, v159, v47
	ds_bpermute_b32 v53, v159, v50
	v_mul_f32_e32 v60, v149, v49
	s_waitcnt lgkmcnt(3)
	v_add_f32_e32 v44, v44, v45
	s_waitcnt lgkmcnt(2)
	v_add_f32_e32 v45, v46, v51
	s_waitcnt lgkmcnt(1)
	v_add_f32_e32 v46, v47, v52
	s_waitcnt lgkmcnt(0)
	v_add_f32_e32 v50, v50, v53
	ds_bpermute_b32 v47, v160, v44
	ds_bpermute_b32 v51, v160, v45
	ds_bpermute_b32 v52, v160, v46
	ds_bpermute_b32 v53, v160, v50
	v_pk_fma_f32 v[56:57], v[2:3], v[60:61], v[54:55] op_sel_hi:[1,0,1]
	v_pk_fma_f32 v[54:55], v[0:1], v[60:61], v[58:59] op_sel_hi:[1,0,1]
	v_lshl_add_u64 v[58:59], v[150:151], 0, v[138:139]
	global_store_dwordx4 v[58:59], v[54:57], off nt
	s_and_saveexec_b64 s[18:19], s[14:15]
	s_cbranch_execz .LBB0_433
	s_waitcnt lgkmcnt(2)
	v_add_f32_e32 v45, v45, v51
	v_add_f32_e32 v44, v44, v47
	v_mul_f32_e32 v44, v194, v44
	v_mul_f32_e32 v45, v191, v45
	v_fmac_f32_e32 v44, v195, v42
	v_fmac_f32_e32 v45, v197, v42
	v_fmac_f32_e32 v44, 0, v43
	v_fmac_f32_e32 v45, v196, v43
	v_fmac_f32_e32 v44, 0, v48
	v_fmac_f32_e32 v45, 0, v48
	v_fmac_f32_e32 v44, 0, v49
	v_fmac_f32_e32 v45, 0, v49
	s_waitcnt lgkmcnt(0)
	v_add_f32_e32 v50, v50, v53
	v_add_f32_e32 v46, v46, v52
	v_mul_f32_e32 v44, v198, v44
	v_mul_f32_e32 v45, v199, v45
	ds_write2st64_b32 v154, v44, v45 offset0:35 offset1:39
	v_mul_f32_e32 v44, v190, v46
	v_mul_f32_e32 v45, v144, v50
	v_fmac_f32_e32 v44, v202, v42
	v_fmac_f32_e32 v45, v203, v42
	v_fmac_f32_e32 v44, v201, v43
	v_fmac_f32_e32 v45, v207, v43
	v_fmac_f32_e32 v44, v200, v48
	v_fmac_f32_e32 v45, v206, v48
	v_fmac_f32_e32 v44, 0, v49
	v_fmac_f32_e32 v45, v205, v49
	v_mul_f32_e32 v44, v204, v44
	v_mul_f32_e32 v42, v208, v45
	ds_write2st64_b32 v154, v44, v42 offset0:43 offset1:47
.LBB0_433:
	s_or_b64 exec, exec, s[18:19]
	ds_read2st64_b32 v[42:43], v94 offset0:19 offset1:23
	s_waitcnt vmcnt(15)
	v_mul_f32_e32 v44, v37, v33
	v_mul_f32_e32 v45, v39, v35
	v_fmac_f32_e32 v44, v36, v32
	v_fmac_f32_e32 v45, v38, v34
	v_add_f32_e32 v50, v44, v45
	s_waitcnt lgkmcnt(0)
	v_mul_f32_e32 v44, v146, v42
	v_pk_mul_f32 v[46:47], v[30:31], v[44:45] op_sel_hi:[1,0]
	v_pk_mul_f32 v[44:45], v[28:29], v[44:45] op_sel_hi:[1,0]
	v_pk_fma_f32 v[40:41], v[40:41], v[38:39], v[46:47]
	v_mul_f32_e32 v46, v37, v25
	v_mul_f32_e32 v47, v39, v27
	v_fmac_f32_e32 v46, v36, v24
	v_fmac_f32_e32 v47, v38, v26
	v_add_f32_e32 v47, v46, v47
	v_mul_f32_e32 v46, v147, v43
	v_pk_fma_f32 v[44:45], v[144:145], v[36:37], v[44:45]
	v_pk_fma_f32 v[48:49], v[22:23], v[46:47], v[40:41] op_sel_hi:[1,0,1]
	v_mul_f32_e32 v40, v37, v17
	v_mul_f32_e32 v37, v37, v13
	v_fmac_f32_e32 v40, v36, v16
	v_mul_f32_e32 v41, v39, v19
	v_fmac_f32_e32 v37, v36, v12
	v_mul_f32_e32 v36, v39, v15
	v_fmac_f32_e32 v41, v38, v18
	v_fmac_f32_e32 v36, v38, v14
	v_pk_fma_f32 v[44:45], v[20:21], v[46:47], v[44:45] op_sel_hi:[1,0,1]
	v_add_f32_e32 v46, v40, v41
	v_add_f32_e32 v37, v37, v36
	ds_bpermute_b32 v38, v156, v50
	ds_bpermute_b32 v39, v156, v47
	ds_bpermute_b32 v51, v156, v46
	ds_bpermute_b32 v52, v156, v37
	ds_read2st64_b32 v[40:41], v94 offset0:27 offset1:31
	s_waitcnt lgkmcnt(4)
	v_add_f32_e32 v38, v50, v38
	s_waitcnt lgkmcnt(3)
	v_add_f32_e32 v39, v47, v39
	s_waitcnt lgkmcnt(2)
	v_add_f32_e32 v46, v46, v51
	s_waitcnt lgkmcnt(1)
	v_add_f32_e32 v37, v37, v52
	ds_bpermute_b32 v47, v157, v38
	ds_bpermute_b32 v50, v157, v39
	ds_bpermute_b32 v51, v157, v46
	ds_bpermute_b32 v54, v157, v37
	s_waitcnt lgkmcnt(4)
	v_mul_f32_e32 v36, v148, v40
	v_pk_fma_f32 v[52:53], v[4:5], v[36:37], v[44:45] op_sel_hi:[1,0,1]
	s_waitcnt lgkmcnt(3)
	v_add_f32_e32 v38, v38, v47
	s_waitcnt lgkmcnt(2)
	v_add_f32_e32 v39, v39, v50
	s_waitcnt lgkmcnt(1)
	v_add_f32_e32 v44, v46, v51
	s_waitcnt lgkmcnt(0)
	v_add_f32_e32 v37, v37, v54
	ds_bpermute_b32 v45, v158, v38
	ds_bpermute_b32 v46, v158, v39
	ds_bpermute_b32 v47, v158, v44
	ds_bpermute_b32 v50, v158, v37
	v_pk_fma_f32 v[48:49], v[6:7], v[36:37], v[48:49] op_sel_hi:[1,0,1]
	s_waitcnt lgkmcnt(3)
	v_add_f32_e32 v36, v38, v45
	s_waitcnt lgkmcnt(2)
	v_add_f32_e32 v38, v39, v46
	s_waitcnt lgkmcnt(1)
	v_add_f32_e32 v39, v44, v47
	s_waitcnt lgkmcnt(0)
	v_add_f32_e32 v44, v37, v50
	ds_bpermute_b32 v37, v159, v36
	ds_bpermute_b32 v45, v159, v38
	ds_bpermute_b32 v46, v159, v39
	ds_bpermute_b32 v47, v159, v44
	v_mul_f32_e32 v54, v149, v41
	s_waitcnt lgkmcnt(3)
	v_add_f32_e32 v36, v36, v37
	s_waitcnt lgkmcnt(2)
	v_add_f32_e32 v37, v38, v45
	s_waitcnt lgkmcnt(1)
	v_add_f32_e32 v38, v39, v46
	s_waitcnt lgkmcnt(0)
	v_add_f32_e32 v44, v44, v47
	ds_bpermute_b32 v39, v160, v36
	ds_bpermute_b32 v45, v160, v37
	ds_bpermute_b32 v46, v160, v38
	ds_bpermute_b32 v47, v160, v44
	v_pk_fma_f32 v[50:51], v[2:3], v[54:55], v[48:49] op_sel_hi:[1,0,1]
	v_pk_fma_f32 v[48:49], v[0:1], v[54:55], v[52:53] op_sel_hi:[1,0,1]
	v_lshl_add_u64 v[52:53], v[150:151], 0, v[140:141]
	global_store_dwordx4 v[52:53], v[48:51], off nt
	s_and_saveexec_b64 s[18:19], s[14:15]
	s_cbranch_execz .LBB0_435
	s_waitcnt lgkmcnt(2)
	v_add_f32_e32 v37, v37, v45
	v_add_f32_e32 v36, v36, v39
	v_mul_f32_e32 v36, v194, v36
	v_mul_f32_e32 v37, v191, v37
	v_fmac_f32_e32 v36, v195, v42
	v_fmac_f32_e32 v37, v197, v42
	v_fmac_f32_e32 v36, 0, v43
	v_fmac_f32_e32 v37, v196, v43
	v_fmac_f32_e32 v36, 0, v40
	v_fmac_f32_e32 v37, 0, v40
	v_fmac_f32_e32 v36, 0, v41
	v_fmac_f32_e32 v37, 0, v41
	s_waitcnt lgkmcnt(0)
	v_add_f32_e32 v44, v44, v47
	v_add_f32_e32 v38, v38, v46
	v_mul_f32_e32 v36, v198, v36
	v_mul_f32_e32 v37, v199, v37
	ds_write2st64_b32 v92, v36, v37 offset0:35 offset1:39
	v_mul_f32_e32 v36, v190, v38
	v_mul_f32_e32 v37, v144, v44
	v_fmac_f32_e32 v36, v202, v42
	v_fmac_f32_e32 v37, v203, v42
	v_fmac_f32_e32 v36, v201, v43
	v_fmac_f32_e32 v37, v207, v43
	v_fmac_f32_e32 v36, v200, v40
	v_fmac_f32_e32 v37, v206, v40
	v_fmac_f32_e32 v36, 0, v41
	v_fmac_f32_e32 v37, v205, v41
	v_mul_f32_e32 v36, v204, v36
	v_mul_f32_e32 v37, v208, v37
	ds_write2st64_b32 v92, v36, v37 offset0:43 offset1:47
.LBB0_435:
	s_or_b64 exec, exec, s[18:19]
	ds_read2st64_b32 v[36:37], v91 offset0:19 offset1:23
	s_waitcnt vmcnt(15)
	v_mul_f32_e32 v33, v9, v33
	v_fmac_f32_e32 v33, v8, v32
	v_mul_f32_e32 v32, v11, v35
	v_fmac_f32_e32 v32, v10, v34
	v_add_f32_e32 v34, v33, v32
	s_waitcnt lgkmcnt(0)
	v_mul_f32_e32 v32, v146, v36
	v_pk_mul_f32 v[28:29], v[28:29], v[32:33] op_sel_hi:[1,0]
	v_mul_f32_e32 v25, v9, v25
	v_pk_fma_f32 v[28:29], v[144:145], v[8:9], v[28:29]
	v_mul_f32_e32 v17, v9, v17
	v_mul_f32_e32 v9, v9, v13
	v_fmac_f32_e32 v25, v8, v24
	v_mul_f32_e32 v24, v11, v27
	v_fmac_f32_e32 v17, v8, v16
	v_mul_f32_e32 v16, v11, v19
	v_fmac_f32_e32 v9, v8, v12
	v_mul_f32_e32 v8, v11, v15
	v_fmac_f32_e32 v24, v10, v26
	v_fmac_f32_e32 v16, v10, v18
	v_fmac_f32_e32 v8, v10, v14
	v_pk_mul_f32 v[30:31], v[30:31], v[32:33] op_sel_hi:[1,0]
	v_mov_b32_e32 v32, v144
	v_mov_b32_e32 v33, v144
	v_add_f32_e32 v25, v25, v24
	v_add_f32_e32 v18, v17, v16
	v_add_f32_e32 v9, v9, v8
	v_pk_fma_f32 v[30:31], v[32:33], v[10:11], v[30:31]
	ds_bpermute_b32 v10, v156, v34
	ds_bpermute_b32 v11, v156, v25
	ds_bpermute_b32 v12, v156, v18
	ds_bpermute_b32 v13, v156, v9
	v_mul_f32_e32 v24, v147, v37
	ds_read2st64_b32 v[16:17], v91 offset0:27 offset1:31
	s_waitcnt lgkmcnt(4)
	v_add_f32_e32 v10, v34, v10
	s_waitcnt lgkmcnt(3)
	v_add_f32_e32 v11, v25, v11
	s_waitcnt lgkmcnt(2)
	v_add_f32_e32 v14, v18, v12
	s_waitcnt lgkmcnt(1)
	v_add_f32_e32 v9, v9, v13
	v_pk_fma_f32 v[22:23], v[22:23], v[24:25], v[30:31] op_sel_hi:[1,0,1]
	v_pk_fma_f32 v[20:21], v[20:21], v[24:25], v[28:29] op_sel_hi:[1,0,1]
	ds_bpermute_b32 v15, v157, v10
	ds_bpermute_b32 v18, v157, v11
	ds_bpermute_b32 v19, v157, v14
	ds_bpermute_b32 v24, v157, v9
	s_waitcnt lgkmcnt(4)
	v_mul_f32_e32 v8, v148, v16
	v_pk_fma_f32 v[12:13], v[4:5], v[8:9], v[20:21] op_sel_hi:[1,0,1]
	s_waitcnt lgkmcnt(3)
	v_add_f32_e32 v4, v10, v15
	s_waitcnt lgkmcnt(2)
	v_add_f32_e32 v5, v11, v18
	s_waitcnt lgkmcnt(1)
	v_add_f32_e32 v10, v14, v19
	s_waitcnt lgkmcnt(0)
	v_add_f32_e32 v9, v9, v24
	ds_bpermute_b32 v11, v158, v4
	ds_bpermute_b32 v18, v158, v5
	ds_bpermute_b32 v19, v158, v10
	ds_bpermute_b32 v20, v158, v9
	v_pk_fma_f32 v[14:15], v[6:7], v[8:9], v[22:23] op_sel_hi:[1,0,1]
	s_waitcnt lgkmcnt(3)
	v_add_f32_e32 v4, v4, v11
	s_waitcnt lgkmcnt(2)
	v_add_f32_e32 v5, v5, v18
	s_waitcnt lgkmcnt(1)
	v_add_f32_e32 v6, v10, v19
	s_waitcnt lgkmcnt(0)
	v_add_f32_e32 v7, v9, v20
	ds_bpermute_b32 v8, v159, v4
	ds_bpermute_b32 v9, v159, v5
	ds_bpermute_b32 v10, v159, v6
	ds_bpermute_b32 v11, v159, v7
	v_mul_f32_e32 v18, v149, v17
	s_waitcnt lgkmcnt(3)
	v_add_f32_e32 v4, v4, v8
	s_waitcnt lgkmcnt(2)
	v_add_f32_e32 v5, v5, v9
	s_waitcnt lgkmcnt(1)
	v_add_f32_e32 v6, v6, v10
	s_waitcnt lgkmcnt(0)
	v_add_f32_e32 v8, v7, v11
	ds_bpermute_b32 v7, v160, v4
	ds_bpermute_b32 v9, v160, v5
	ds_bpermute_b32 v10, v160, v6
	ds_bpermute_b32 v11, v160, v8
	v_pk_fma_f32 v[2:3], v[2:3], v[18:19], v[14:15] op_sel_hi:[1,0,1]
	v_pk_fma_f32 v[0:1], v[0:1], v[18:19], v[12:13] op_sel_hi:[1,0,1]
	v_lshl_add_u64 v[12:13], v[150:151], 0, v[142:143]
	global_store_dwordx4 v[12:13], v[0:3], off nt
	s_and_saveexec_b64 s[18:19], s[14:15]
	s_cbranch_execnz .LBB0_441
	s_or_b64 exec, exec, s[18:19]
	s_and_saveexec_b64 s[18:19], s[10:11]
	s_cbranch_execnz .LBB0_442

.LBB0_445:
	s_lshl_b32 s46, s57, 5
	s_and_b32 s44, s57, 3
	s_and_b32 s30, s46, 0xffffff80
	s_lshl_b32 s45, s44, 6
	v_add_u32_e32 v0, s30, v50
	v_or_b32_e32 v40, s45, v49
	v_ashrrev_i32_e32 v1, 31, v0
	v_lshlrev_b64 v[0:1], 10, v[0:1]
	v_lshlrev_b32_e32 v6, 2, v40
	v_or_b32_e32 v0, v0, v6
	s_waitcnt lgkmcnt(0)
	v_lshl_add_u64 v[2:3], s[36:37], 0, v[0:1]
	v_lshl_add_u64 v[0:1], s[38:39], 0, v[0:1]
	global_load_dwordx4 v[28:31], v[0:1], off nt
	v_add_u32_e32 v0, s30, v51
	v_ashrrev_i32_e32 v1, 31, v0
	v_lshlrev_b64 v[0:1], 10, v[0:1]
	v_or_b32_e32 v0, v0, v6
	global_load_dwordx4 v[24:27], v[2:3], off nt
	v_lshl_add_u64 v[2:3], s[36:37], 0, v[0:1]
	v_lshl_add_u64 v[0:1], s[38:39], 0, v[0:1]
	global_load_dwordx4 v[20:23], v[0:1], off nt
	v_add_u32_e32 v0, s30, v52
	v_ashrrev_i32_e32 v1, 31, v0
	v_lshlrev_b64 v[0:1], 10, v[0:1]
	v_or_b32_e32 v0, v0, v6
	global_load_dwordx4 v[16:19], v[2:3], off nt
	v_lshl_add_u64 v[2:3], s[36:37], 0, v[0:1]
	v_lshl_add_u64 v[0:1], s[38:39], 0, v[0:1]
	global_load_dwordx4 v[12:15], v[0:1], off nt
	v_add_u32_e32 v0, s30, v53
	v_ashrrev_i32_e32 v1, 31, v0
	v_lshlrev_b64 v[4:5], 10, v[0:1]
	v_or_b32_e32 v4, v4, v6
	v_lshl_add_u64 v[0:1], s[36:37], 0, v[4:5]
	v_lshl_add_u64 v[4:5], s[38:39], 0, v[4:5]
	global_load_dwordx4 v[8:11], v[2:3], off nt
	s_add_i32 s30, s30, -4
	global_load_dwordx4 v[0:3], v[0:1], off nt
	s_nop 0
	global_load_dwordx4 v[4:7], v[4:5], off nt
	s_waitcnt vmcnt(6)
	ds_write_b128 v32, v[24:27]
	ds_write_b128 v32, v[28:31] offset:35904
	s_and_saveexec_b64 s[42:43], s[16:17]
	s_cbranch_execz .LBB0_447
	v_add_u32_e32 v64, s30, v50
	v_ashrrev_i32_e32 v65, 31, v64
	v_lshlrev_b64 v[64:65], 10, v[64:65]
	v_lshl_or_b32 v64, v40, 2, v64
	v_lshl_add_u64 v[66:67], s[34:35], 0, v[64:65]
	global_store_dwordx4 v[66:67], v[24:27], off nt
	s_nop 1
	v_lshl_add_u64 v[24:25], s[40:41], 0, v[64:65]
	global_store_dwordx4 v[24:25], v[28:31], off nt
.LBB0_447:
	s_or_b64 exec, exec, s[42:43]
	s_waitcnt vmcnt(4)
	ds_write_b128 v34, v[16:19]
	ds_write_b128 v34, v[20:23] offset:35904
	s_and_saveexec_b64 s[42:43], s[18:19]
	s_cbranch_execz .LBB0_449
	v_add_u32_e32 v24, s30, v51
	v_ashrrev_i32_e32 v25, 31, v24
	v_lshlrev_b64 v[24:25], 10, v[24:25]
	v_lshl_or_b32 v24, v40, 2, v24
	v_lshl_add_u64 v[26:27], s[34:35], 0, v[24:25]
	global_store_dwordx4 v[26:27], v[16:19], off nt
	s_nop 1
	v_lshl_add_u64 v[16:17], s[40:41], 0, v[24:25]
	global_store_dwordx4 v[16:17], v[20:23], off nt
.LBB0_449:
	s_or_b64 exec, exec, s[42:43]
	s_waitcnt vmcnt(2)
	ds_write_b128 v36, v[8:11]
	ds_write_b128 v36, v[12:15] offset:35904
	s_and_saveexec_b64 s[42:43], s[20:21]
	s_cbranch_execz .LBB0_451
	v_add_u32_e32 v16, s30, v52
	v_ashrrev_i32_e32 v17, 31, v16
	v_lshlrev_b64 v[16:17], 10, v[16:17]
	v_lshl_or_b32 v16, v40, 2, v16
	v_lshl_add_u64 v[18:19], s[34:35], 0, v[16:17]
	global_store_dwordx4 v[18:19], v[8:11], off nt
	s_nop 1
	v_lshl_add_u64 v[8:9], s[40:41], 0, v[16:17]
	global_store_dwordx4 v[8:9], v[12:15], off nt
.LBB0_451:
	s_or_b64 exec, exec, s[42:43]
	s_waitcnt vmcnt(1)
	ds_write_b128 v38, v[0:3]
	s_waitcnt vmcnt(0)
	ds_write_b128 v38, v[4:7] offset:35904
	s_and_saveexec_b64 s[42:43], s[22:23]
	s_cbranch_execz .LBB0_453
	v_add_u32_e32 v8, s30, v53
	v_ashrrev_i32_e32 v9, 31, v8
	v_lshlrev_b64 v[8:9], 10, v[8:9]
	v_lshl_or_b32 v8, v40, 2, v8
	v_lshl_add_u64 v[10:11], s[34:35], 0, v[8:9]
	global_store_dwordx4 v[10:11], v[0:3], off nt
	s_nop 1
	v_lshl_add_u64 v[0:1], s[40:41], 0, v[8:9]
	global_store_dwordx4 v[0:1], v[4:7], off nt

.LBB0_516:
	s_ashr_i32 s89, s88, 31
	s_and_b32 s90, s88, -4
	s_lshl_b64 s[6:7], s[88:89], 15
	s_and_b32 s26, s88, 3
	v_or_b32_e32 v150, s6, v104
	s_add_i32 s6, s90, 0x4000
	s_lshl_b32 s77, s26, 2
	v_mov_b32_e32 v151, s7
	s_add_u32 s24, s91, s77
	v_readlane_b32 s7, v248, 22
	s_addc_u32 s25, s7, 0
	s_ashr_i32 s7, s6, 31
	s_lshl_b64 s[16:17], s[6:7], 5
	s_add_u32 s16, s24, s16
	v_lshl_add_u64 v[0:1], v[150:151], 2, s[64:65]
	s_addc_u32 s17, s25, s17
	s_add_i32 s18, s90, 0x4001
	v_lshl_add_u64 v[2:3], v[0:1], 0, v[108:109]
	s_ashr_i32 s19, s18, 31
	v_lshl_add_u64 v[4:5], v[0:1], 0, v[110:111]
	global_load_dwordx4 v[92:95], v[2:3], off nt
	global_load_dwordx4 v[88:91], v[4:5], off nt
	global_load_dword v16, v107, s[16:17] offset:16
	s_lshl_b64 s[18:19], s[18:19], 5
	s_add_u32 s18, s24, s18
	s_addc_u32 s19, s25, s19
	s_add_i32 s20, s90, 0x4002
	s_ashr_i32 s21, s20, 31
	s_lshl_b64 s[20:21], s[20:21], 5
	global_load_dword v13, v107, s[18:19] offset:16
	s_add_u32 s20, s24, s20
	s_addc_u32 s21, s25, s21
	global_load_dword v11, v107, s[20:21] offset:16
	s_add_i32 s22, s90, 0x4003
	s_ashr_i32 s23, s22, 31
	s_load_dwordx2 s[28:29], s[0:1], 0x30
	s_lshl_b64 s[22:23], s[22:23], 5
	s_add_u32 s22, s24, s22
	s_addc_u32 s23, s25, s23
	v_add_u32_e32 v8, s6, v103
	global_load_dword v7, v107, s[22:23] offset:16
	s_lshl_b64 s[24:25], s[88:89], 2
	v_ashrrev_i32_e32 v9, 31, v8
	s_waitcnt lgkmcnt(0)
	s_add_u32 s24, s28, s24
	v_lshlrev_b64 v[8:9], 11, v[8:9]
	s_addc_u32 s25, s29, s25
	v_lshl_add_u64 v[8:9], s[72:73], 0, v[8:9]
	s_lshl_b32 s74, s26, 8
	s_waitcnt vmcnt(6)
	v_add_u32_e32 v18, s6, v161
	v_add_u32_e32 v20, s6, v162
	v_lshl_add_u64 v[8:9], v[8:9], 0, s[74:75]
	s_lshl_b32 s26, s26, 9
	s_mov_b32 s27, s75
	v_ashrrev_i32_e32 v19, 31, v18
	v_ashrrev_i32_e32 v21, 31, v20
	v_lshl_add_u64 v[2:3], v[0:1], 0, v[112:113]
	v_lshl_add_u64 v[4:5], v[0:1], 0, v[114:115]
	v_lshl_add_u64 v[8:9], v[8:9], 0, v[106:107]
	v_lshl_add_u64 v[14:15], v[124:125], 0, s[26:27]
	v_lshlrev_b64 v[18:19], 12, v[18:19]
	v_lshlrev_b64 v[20:21], 12, v[20:21]
	v_lshl_add_u64 v[18:19], v[14:15], 0, v[18:19]
	v_lshl_add_u64 v[14:15], v[14:15], 0, v[20:21]
	global_load_ushort v21, v[8:9], off
	global_load_ushort v22, v[8:9], off offset:1024
	global_load_dword v12, v107, s[18:19]
	global_load_dword v17, v107, s[16:17]
	global_load_ushort v23, v[18:19], off
	global_load_ushort v24, v[14:15], off
	global_load_dwordx4 v[84:87], v[2:3], off nt
	global_load_dwordx4 v[76:79], v[4:5], off nt
	v_lshl_add_u64 v[2:3], v[0:1], 0, v[116:117]
	v_lshl_add_u64 v[4:5], v[0:1], 0, v[118:119]
	global_load_dwordx4 v[68:71], v[2:3], off nt
	global_load_dwordx4 v[60:63], v[4:5], off nt
	v_lshl_add_u64 v[2:3], v[0:1], 0, v[120:121]
	v_lshl_add_u64 v[4:5], v[0:1], 0, v[122:123]
	global_load_dwordx4 v[52:55], v[2:3], off nt
	global_load_dwordx4 v[44:47], v[4:5], off nt
	s_nop 0
	global_load_dword v4, v107, s[24:25]
	global_load_dword v5, v107, s[22:23]
	global_load_dword v8, v107, s[20:21]
	s_lshl_b64 s[16:17], s[88:89], 9
	s_add_u32 s94, s66, s16
	s_addc_u32 s95, s67, s17
	v_readlane_b32 s16, v248, 24
	v_mov_b32_e32 v101, v107
	v_readlane_b32 s17, v248, 25
	s_andn2_b64 vcc, exec, s[16:17]
	s_waitcnt vmcnt(18)
	v_mul_f32_e64 v2, |v16|, s70
	v_exp_f32_e32 v19, v2
	s_waitcnt vmcnt(17)
	v_mul_f32_e64 v2, |v13|, s70
	v_add_f32_e32 v20, 1.0, v19
	v_exp_f32_e32 v15, v2
	v_frexp_mant_f32_e32 v2, v20
	v_cmp_gt_f32_e64 s[58:59], s71, v2
	s_waitcnt vmcnt(16)
	v_mul_f32_e64 v2, |v11|, s70
	v_exp_f32_e32 v10, v2
	v_add_f32_e32 v18, 1.0, v15
	v_frexp_mant_f32_e32 v2, v18
	v_cmp_gt_f32_e64 s[48:49], s71, v2
	v_add_f32_e32 v14, 1.0, v10
	v_frexp_mant_f32_e32 v2, v14
	v_cmp_gt_f32_e64 s[38:39], s71, v2
	s_waitcnt vmcnt(15)
	v_mul_f32_e64 v2, |v7|, s70
	v_exp_f32_e32 v6, v2
	v_cmp_neq_f32_e64 s[50:51], s97, v19
	v_cmp_ngt_f32_e64 s[52:53], -1.0, v19
	v_cmp_neq_f32_e64 s[54:55], -1.0, v19
	v_add_f32_e32 v9, 1.0, v6
	v_frexp_mant_f32_e32 v2, v9
	v_cmp_gt_f32_e64 s[26:27], s71, v2
	v_cmp_lt_f32_e64 s[56:57], |v19|, s76
	v_cmp_neq_f32_e64 s[40:41], s97, v15
	v_cmp_ngt_f32_e64 s[42:43], -1.0, v15
	v_cmp_neq_f32_e64 s[44:45], -1.0, v15
	v_cmp_lt_f32_e64 s[46:47], |v15|, s76
	v_cmp_neq_f32_e64 s[28:29], s97, v10
	s_waitcnt vmcnt(14)
	v_lshlrev_b32_e32 v2, 16, v21
	s_waitcnt vmcnt(13)
	v_lshlrev_b32_e32 v3, 16, v22
	ds_write2st64_b32 v166, v2, v3 offset1:8
	v_cmp_ngt_f32_e64 s[30:31], -1.0, v10
	s_waitcnt vmcnt(10)
	v_lshlrev_b32_e32 v2, 16, v23
	s_waitcnt vmcnt(9)
	v_lshlrev_b32_e32 v3, 16, v24
	v_cmp_neq_f32_e64 s[34:35], -1.0, v10
	v_cmp_lt_f32_e64 s[36:37], |v10|, s76
	v_cmp_neq_f32_e64 s[18:19], s97, v6
	v_cmp_ngt_f32_e64 s[20:21], -1.0, v6
	v_cmp_neq_f32_e64 s[22:23], -1.0, v6
	v_cmp_lt_f32_e64 s[24:25], |v6|, s76
	ds_write2st64_b32 v166, v2, v3 offset0:16 offset1:24
	v_lshl_add_u64 v[2:3], s[94:95], 0, v[100:101]
	s_waitcnt lgkmcnt(0)
	s_barrier
	s_cbranch_vccz .LBB0_519
	s_andn2_b64 vcc, exec, s[78:79]
	s_cbranch_vccz .LBB0_529

.LBB0_549:
	v_max_f32_e32 v2, v16, v16
	v_min_f32_e32 v16, 0, v2
	v_add_f32_e32 v2, -1.0, v20
	s_waitcnt lgkmcnt(0)
	v_sub_f32_e32 v3, v2, v20
	v_add_f32_e32 v3, 1.0, v3
	v_sub_f32_e32 v2, v19, v2
	v_add_f32_e32 v21, v2, v3
	v_cvt_f64_f32_e32 v[2:3], v20
	v_frexp_exp_i32_f64_e32 v2, v[2:3]
	v_subbrev_co_u32_e64 v2, vcc, 0, v2, s[58:59]
	v_sub_u32_e32 v3, 0, v2
	v_ldexp_f32 v20, v20, v3
	v_ldexp_f32 v3, v21, v3
	v_add_f32_e32 v21, -1.0, v20
	v_add_f32_e32 v24, 1.0, v20
	v_add_f32_e32 v22, 1.0, v21
	v_add_f32_e32 v25, -1.0, v24
	v_sub_f32_e32 v22, v20, v22
	v_sub_f32_e32 v20, v20, v25
	v_add_f32_e32 v22, v3, v22
	v_add_f32_e32 v3, v3, v20
	v_add_f32_e32 v20, v24, v3
	v_rcp_f32_e32 v25, v20
	v_add_f32_e32 v23, v21, v22
	v_sub_f32_e32 v21, v23, v21
	v_sub_f32_e32 v21, v22, v21
	v_sub_f32_e32 v22, v20, v24
	v_sub_f32_e32 v3, v3, v22
	v_mul_f32_e32 v22, v23, v25
	v_mul_f32_e32 v24, v20, v22
	v_fma_f32 v26, v22, v20, -v24
	v_fmac_f32_e32 v26, v22, v3
	v_add_f32_e32 v27, v24, v26
	v_sub_f32_e32 v28, v23, v27
	v_sub_f32_e32 v23, v23, v28
	v_sub_f32_e32 v24, v27, v24
	v_sub_f32_e32 v23, v23, v27
	v_add_f32_e32 v21, v21, v23
	v_sub_f32_e32 v23, v24, v26
	v_add_f32_e32 v21, v23, v21
	v_add_f32_e32 v23, v28, v21
	v_mul_f32_e32 v24, v25, v23
	v_mul_f32_e32 v26, v20, v24
	v_fma_f32 v20, v24, v20, -v26
	v_fmac_f32_e32 v20, v24, v3
	v_sub_f32_e32 v3, v28, v23
	v_add_f32_e32 v3, v21, v3
	v_add_f32_e32 v21, v26, v20
	v_sub_f32_e32 v27, v23, v21
	v_sub_f32_e32 v23, v23, v27
	v_sub_f32_e32 v26, v21, v26
	v_sub_f32_e32 v21, v23, v21
	v_add_f32_e32 v3, v3, v21
	v_sub_f32_e32 v20, v26, v20
	v_cvt_f32_i32_e32 v2, v2
	v_add_f32_e32 v3, v20, v3
	v_add_f32_e32 v20, v22, v24
	v_add_f32_e32 v3, v27, v3
	v_sub_f32_e32 v21, v20, v22
	v_mul_f32_e32 v3, v25, v3
	v_sub_f32_e32 v21, v24, v21
	v_add_f32_e32 v3, v21, v3
	v_mul_f32_e32 v24, 0x3f317218, v2
	v_add_f32_e32 v21, v20, v3
	v_fma_f32 v25, v2, s33, -v24
	v_mul_f32_e32 v22, v21, v21
	v_fmac_f32_e32 v25, 0xb102e308, v2
	v_sub_f32_e32 v2, v21, v20
	v_fmamk_f32 v23, v22, 0x3e9b6dac, v182
	v_sub_f32_e32 v2, v3, v2
	v_add_f32_e32 v3, v24, v25
	v_fmaak_f32 v23, v22, v23, 0x3f2aaada
	v_sub_f32_e32 v20, v3, v24
	v_ldexp_f32 v24, v21, 1
	v_mul_f32_e32 v21, v21, v22
	v_mul_f32_e32 v21, v21, v23
	v_add_f32_e32 v22, v24, v21
	v_sub_f32_e32 v23, v22, v24
	v_ldexp_f32 v2, v2, 1
	v_sub_f32_e32 v21, v21, v23
	v_add_f32_e32 v2, v2, v21
	v_add_f32_e32 v21, v22, v2
	v_sub_f32_e32 v22, v21, v22
	v_sub_f32_e32 v2, v2, v22
	v_add_f32_e32 v22, v3, v21
	v_sub_f32_e32 v23, v22, v3
	v_sub_f32_e32 v24, v22, v23
	v_sub_f32_e32 v20, v25, v20
	v_sub_f32_e32 v3, v3, v24
	v_sub_f32_e32 v21, v21, v23
	v_add_f32_e32 v3, v21, v3
	v_add_f32_e32 v21, v20, v2
	v_sub_f32_e32 v23, v21, v20
	v_sub_f32_e32 v24, v21, v23
	v_sub_f32_e32 v20, v20, v24
	v_sub_f32_e32 v2, v2, v23
	v_add_f32_e32 v3, v21, v3
	v_add_f32_e32 v2, v2, v20
	v_add_f32_e32 v20, v22, v3
	v_sub_f32_e32 v21, v20, v22
	v_sub_f32_e32 v3, v3, v21
	v_add_f32_e32 v2, v2, v3
	v_add_f32_e32 v2, v20, v2
	v_cndmask_b32_e64 v2, v185, v2, s[50:51]
	v_cndmask_b32_e64 v2, v186, v2, s[52:53]
	v_cndmask_b32_e64 v2, v187, v2, s[54:55]
	v_cndmask_b32_e64 v2, v2, v19, s[56:57]
	v_sub_f32_e32 v2, v16, v2
	v_add_f32_e32 v16, 0, v2
	v_max_f32_e32 v2, v13, v13
	v_min_f32_e32 v13, 0, v2
	v_add_f32_e32 v2, -1.0, v18
	v_sub_f32_e32 v3, v2, v18
	v_add_f32_e32 v3, 1.0, v3
	v_sub_f32_e32 v2, v15, v2
	v_add_f32_e32 v20, v2, v3
	v_cvt_f64_f32_e32 v[2:3], v18
	v_frexp_exp_i32_f64_e32 v2, v[2:3]
	v_subbrev_co_u32_e64 v2, vcc, 0, v2, s[48:49]
	v_sub_u32_e32 v3, 0, v2
	v_ldexp_f32 v18, v18, v3
	v_ldexp_f32 v3, v20, v3
	v_add_f32_e32 v20, -1.0, v18
	v_add_f32_e32 v23, 1.0, v18
	v_add_f32_e32 v21, 1.0, v20
	v_add_f32_e32 v24, -1.0, v23
	v_sub_f32_e32 v21, v18, v21
	v_sub_f32_e32 v18, v18, v24
	v_add_f32_e32 v21, v3, v21
	v_add_f32_e32 v3, v3, v18
	v_add_f32_e32 v18, v23, v3
	v_rcp_f32_e32 v24, v18
	v_add_f32_e32 v22, v20, v21
	v_sub_f32_e32 v20, v22, v20
	v_sub_f32_e32 v20, v21, v20
	v_sub_f32_e32 v21, v18, v23
	v_sub_f32_e32 v3, v3, v21
	v_mul_f32_e32 v21, v22, v24
	v_mul_f32_e32 v23, v18, v21
	v_fma_f32 v25, v21, v18, -v23
	v_fmac_f32_e32 v25, v21, v3
	v_add_f32_e32 v26, v23, v25
	v_sub_f32_e32 v27, v22, v26
	v_sub_f32_e32 v22, v22, v27
	v_sub_f32_e32 v23, v26, v23
	v_sub_f32_e32 v22, v22, v26
	v_add_f32_e32 v20, v20, v22
	v_sub_f32_e32 v22, v23, v25
	v_add_f32_e32 v20, v22, v20
	v_add_f32_e32 v22, v27, v20
	v_mul_f32_e32 v23, v24, v22
	v_mul_f32_e32 v25, v18, v23
	v_fma_f32 v18, v23, v18, -v25
	v_fmac_f32_e32 v18, v23, v3
	v_sub_f32_e32 v3, v27, v22
	v_add_f32_e32 v3, v20, v3
	v_add_f32_e32 v20, v25, v18
	v_sub_f32_e32 v26, v22, v20
	v_sub_f32_e32 v22, v22, v26
	v_sub_f32_e32 v25, v20, v25
	v_sub_f32_e32 v20, v22, v20
	v_add_f32_e32 v3, v3, v20
	v_sub_f32_e32 v18, v25, v18
	v_cvt_f32_i32_e32 v2, v2
	v_add_f32_e32 v3, v18, v3
	v_add_f32_e32 v18, v21, v23
	v_add_f32_e32 v3, v26, v3
	v_sub_f32_e32 v20, v18, v21
	v_mul_f32_e32 v3, v24, v3
	v_sub_f32_e32 v20, v23, v20
	v_add_f32_e32 v3, v20, v3
	v_mul_f32_e32 v23, 0x3f317218, v2
	v_add_f32_e32 v20, v18, v3
	v_fma_f32 v24, v2, s33, -v23
	v_mul_f32_e32 v21, v20, v20
	v_fmac_f32_e32 v24, 0xb102e308, v2
	v_sub_f32_e32 v2, v20, v18
	v_fmamk_f32 v22, v21, 0x3e9b6dac, v182
	v_sub_f32_e32 v2, v3, v2
	v_add_f32_e32 v3, v23, v24
	v_fmaak_f32 v22, v21, v22, 0x3f2aaada
	v_sub_f32_e32 v18, v3, v23
	v_ldexp_f32 v23, v20, 1
	v_mul_f32_e32 v20, v20, v21
	v_mul_f32_e32 v20, v20, v22
	v_add_f32_e32 v21, v23, v20
	v_sub_f32_e32 v22, v21, v23
	v_ldexp_f32 v2, v2, 1
	v_sub_f32_e32 v20, v20, v22
	v_add_f32_e32 v2, v2, v20
	v_add_f32_e32 v20, v21, v2
	v_sub_f32_e32 v21, v20, v21
	v_sub_f32_e32 v2, v2, v21
	v_add_f32_e32 v21, v3, v20
	v_sub_f32_e32 v22, v21, v3
	v_sub_f32_e32 v23, v21, v22
	v_sub_f32_e32 v18, v24, v18
	v_sub_f32_e32 v3, v3, v23
	v_sub_f32_e32 v20, v20, v22
	v_add_f32_e32 v3, v20, v3
	v_add_f32_e32 v20, v18, v2
	v_sub_f32_e32 v22, v20, v18
	v_sub_f32_e32 v23, v20, v22
	v_sub_f32_e32 v18, v18, v23
	v_sub_f32_e32 v2, v2, v22
	v_add_f32_e32 v3, v20, v3
	v_add_f32_e32 v2, v2, v18
	v_add_f32_e32 v18, v21, v3
	v_sub_f32_e32 v20, v18, v21
	v_sub_f32_e32 v3, v3, v20
	v_add_f32_e32 v2, v2, v3
	v_add_f32_e32 v2, v18, v2
	v_cndmask_b32_e64 v2, v185, v2, s[40:41]
	v_cndmask_b32_e64 v2, v186, v2, s[42:43]
	v_cndmask_b32_e64 v2, v187, v2, s[44:45]
	v_cndmask_b32_e64 v2, v2, v15, s[46:47]
	v_sub_f32_e32 v2, v13, v2
	v_add_f32_e32 v13, v16, v2
	v_max_f32_e32 v2, v11, v11
	v_min_f32_e32 v11, 0, v2
	v_add_f32_e32 v2, -1.0, v14
	v_sub_f32_e32 v3, v2, v14
	v_add_f32_e32 v3, 1.0, v3
	v_sub_f32_e32 v2, v10, v2
	v_add_f32_e32 v15, v2, v3
	v_cvt_f64_f32_e32 v[2:3], v14
	v_frexp_exp_i32_f64_e32 v2, v[2:3]
	v_subbrev_co_u32_e64 v2, vcc, 0, v2, s[38:39]
	v_sub_u32_e32 v3, 0, v2
	v_ldexp_f32 v14, v14, v3
	v_ldexp_f32 v3, v15, v3
	v_add_f32_e32 v15, -1.0, v14
	v_add_f32_e32 v22, 1.0, v14
	v_add_f32_e32 v20, 1.0, v15
	v_add_f32_e32 v23, -1.0, v22
	v_sub_f32_e32 v20, v14, v20
	v_sub_f32_e32 v14, v14, v23
	v_add_f32_e32 v20, v3, v20
	v_add_f32_e32 v3, v3, v14
	v_add_f32_e32 v14, v22, v3
	v_rcp_f32_e32 v23, v14
	v_add_f32_e32 v21, v15, v20
	v_sub_f32_e32 v15, v21, v15
	v_sub_f32_e32 v15, v20, v15
	v_sub_f32_e32 v20, v14, v22
	v_sub_f32_e32 v3, v3, v20
	v_mul_f32_e32 v20, v21, v23
	v_mul_f32_e32 v22, v14, v20
	v_fma_f32 v24, v20, v14, -v22
	v_fmac_f32_e32 v24, v20, v3
	v_add_f32_e32 v25, v22, v24
	v_sub_f32_e32 v26, v21, v25
	v_sub_f32_e32 v21, v21, v26
	v_sub_f32_e32 v22, v25, v22
	v_sub_f32_e32 v21, v21, v25
	v_add_f32_e32 v15, v15, v21
	v_sub_f32_e32 v21, v22, v24
	v_add_f32_e32 v15, v21, v15
	v_add_f32_e32 v21, v26, v15
	v_mul_f32_e32 v22, v23, v21
	v_mul_f32_e32 v24, v14, v22
	v_fma_f32 v14, v22, v14, -v24
	v_fmac_f32_e32 v14, v22, v3
	v_sub_f32_e32 v3, v26, v21
	v_add_f32_e32 v3, v15, v3
	v_add_f32_e32 v15, v24, v14
	v_sub_f32_e32 v25, v21, v15
	v_sub_f32_e32 v21, v21, v25
	v_sub_f32_e32 v24, v15, v24
	v_sub_f32_e32 v15, v21, v15
	v_add_f32_e32 v3, v3, v15
	v_sub_f32_e32 v14, v24, v14
	v_cvt_f32_i32_e32 v2, v2
	v_add_f32_e32 v3, v14, v3
	v_add_f32_e32 v14, v20, v22
	v_add_f32_e32 v3, v25, v3
	v_sub_f32_e32 v15, v14, v20
	v_mul_f32_e32 v3, v23, v3
	v_sub_f32_e32 v15, v22, v15
	v_add_f32_e32 v3, v15, v3
	v_mul_f32_e32 v22, 0x3f317218, v2
	v_add_f32_e32 v15, v14, v3
	v_fma_f32 v23, v2, s33, -v22
	v_mul_f32_e32 v20, v15, v15
	v_fmac_f32_e32 v23, 0xb102e308, v2
	v_sub_f32_e32 v2, v15, v14
	v_fmamk_f32 v21, v20, 0x3e9b6dac, v182
	v_sub_f32_e32 v2, v3, v2
	v_add_f32_e32 v3, v22, v23
	v_fmaak_f32 v21, v20, v21, 0x3f2aaada
	v_sub_f32_e32 v14, v3, v22
	v_ldexp_f32 v22, v15, 1
	v_mul_f32_e32 v15, v15, v20
	v_mul_f32_e32 v15, v15, v21
	v_add_f32_e32 v20, v22, v15
	v_sub_f32_e32 v21, v20, v22
	v_ldexp_f32 v2, v2, 1
	v_sub_f32_e32 v15, v15, v21
	v_add_f32_e32 v2, v2, v15
	v_add_f32_e32 v15, v20, v2
	v_sub_f32_e32 v20, v15, v20
	v_sub_f32_e32 v2, v2, v20
	v_add_f32_e32 v20, v3, v15
	v_sub_f32_e32 v21, v20, v3
	v_sub_f32_e32 v22, v20, v21
	v_sub_f32_e32 v14, v23, v14
	v_sub_f32_e32 v3, v3, v22
	v_sub_f32_e32 v15, v15, v21
	v_add_f32_e32 v3, v15, v3
	v_add_f32_e32 v15, v14, v2
	v_sub_f32_e32 v21, v15, v14
	v_sub_f32_e32 v22, v15, v21
	v_sub_f32_e32 v14, v14, v22
	v_sub_f32_e32 v2, v2, v21
	v_add_f32_e32 v3, v15, v3
	v_add_f32_e32 v2, v2, v14
	v_add_f32_e32 v14, v20, v3
	v_sub_f32_e32 v15, v14, v20
	v_sub_f32_e32 v3, v3, v15
	v_add_f32_e32 v2, v2, v3
	v_add_f32_e32 v2, v14, v2
	v_cndmask_b32_e64 v2, v185, v2, s[28:29]
	v_cndmask_b32_e64 v2, v186, v2, s[30:31]
	v_cndmask_b32_e64 v2, v187, v2, s[34:35]
	v_cndmask_b32_e64 v2, v2, v10, s[36:37]
	v_sub_f32_e32 v2, v11, v2
	v_add_f32_e32 v10, v13, v2
	v_max_f32_e32 v2, v7, v7
	v_min_f32_e32 v7, 0, v2
	v_add_f32_e32 v2, -1.0, v9
	v_sub_f32_e32 v3, v2, v9
	v_add_f32_e32 v3, 1.0, v3
	v_sub_f32_e32 v2, v6, v2
	v_add_f32_e32 v11, v2, v3
	v_cvt_f64_f32_e32 v[2:3], v9
	v_frexp_exp_i32_f64_e32 v2, v[2:3]
	v_subbrev_co_u32_e64 v2, vcc, 0, v2, s[26:27]
	v_sub_u32_e32 v3, 0, v2
	v_ldexp_f32 v9, v9, v3
	v_ldexp_f32 v3, v11, v3
	v_add_f32_e32 v11, -1.0, v9
	v_add_f32_e32 v21, 1.0, v9
	v_add_f32_e32 v14, 1.0, v11
	v_add_f32_e32 v22, -1.0, v21
	v_sub_f32_e32 v14, v9, v14
	v_sub_f32_e32 v9, v9, v22
	v_add_f32_e32 v14, v3, v14
	v_add_f32_e32 v3, v3, v9
	v_add_f32_e32 v9, v21, v3
	v_rcp_f32_e32 v22, v9
	v_add_f32_e32 v15, v11, v14
	v_sub_f32_e32 v11, v15, v11
	v_sub_f32_e32 v11, v14, v11
	v_sub_f32_e32 v14, v9, v21
	v_sub_f32_e32 v3, v3, v14
	v_mul_f32_e32 v14, v15, v22
	v_mul_f32_e32 v21, v9, v14
	v_fma_f32 v23, v14, v9, -v21
	v_fmac_f32_e32 v23, v14, v3
	v_add_f32_e32 v24, v21, v23
	v_sub_f32_e32 v25, v15, v24
	v_sub_f32_e32 v15, v15, v25
	v_sub_f32_e32 v21, v24, v21
	v_sub_f32_e32 v15, v15, v24
	v_add_f32_e32 v11, v11, v15
	v_sub_f32_e32 v15, v21, v23
	v_add_f32_e32 v11, v15, v11
	v_add_f32_e32 v15, v25, v11
	v_mul_f32_e32 v21, v22, v15
	v_mul_f32_e32 v23, v9, v21
	v_fma_f32 v9, v21, v9, -v23
	v_fmac_f32_e32 v9, v21, v3
	v_sub_f32_e32 v3, v25, v15
	v_add_f32_e32 v3, v11, v3
	v_add_f32_e32 v11, v23, v9
	v_sub_f32_e32 v24, v15, v11
	v_sub_f32_e32 v15, v15, v24
	v_sub_f32_e32 v23, v11, v23
	v_sub_f32_e32 v11, v15, v11
	v_add_f32_e32 v3, v3, v11
	v_sub_f32_e32 v9, v23, v9
	v_cvt_f32_i32_e32 v2, v2
	v_add_f32_e32 v3, v9, v3
	v_add_f32_e32 v9, v14, v21
	v_add_f32_e32 v3, v24, v3
	v_sub_f32_e32 v11, v9, v14
	v_mul_f32_e32 v3, v22, v3
	v_sub_f32_e32 v11, v21, v11
	v_add_f32_e32 v3, v11, v3
	v_mul_f32_e32 v21, 0x3f317218, v2
	v_add_f32_e32 v11, v9, v3
	v_fma_f32 v22, v2, s33, -v21
	v_mul_f32_e32 v14, v11, v11
	v_fmac_f32_e32 v22, 0xb102e308, v2
	v_sub_f32_e32 v2, v11, v9
	v_fmamk_f32 v15, v14, 0x3e9b6dac, v182
	v_sub_f32_e32 v2, v3, v2
	v_add_f32_e32 v3, v21, v22
	v_fmaak_f32 v15, v14, v15, 0x3f2aaada
	v_sub_f32_e32 v9, v3, v21
	v_ldexp_f32 v21, v11, 1
	v_mul_f32_e32 v11, v11, v14
	v_mul_f32_e32 v11, v11, v15
	v_add_f32_e32 v14, v21, v11
	v_sub_f32_e32 v15, v14, v21
	v_ldexp_f32 v2, v2, 1
	v_sub_f32_e32 v11, v11, v15
	v_add_f32_e32 v2, v2, v11
	v_add_f32_e32 v11, v14, v2
	v_sub_f32_e32 v14, v11, v14
	v_sub_f32_e32 v2, v2, v14
	v_add_f32_e32 v14, v3, v11
	v_sub_f32_e32 v15, v14, v3
	v_sub_f32_e32 v21, v14, v15
	v_sub_f32_e32 v9, v22, v9
	v_sub_f32_e32 v3, v3, v21
	v_sub_f32_e32 v11, v11, v15
	v_add_f32_e32 v3, v11, v3
	v_add_f32_e32 v11, v9, v2
	v_sub_f32_e32 v15, v11, v9
	v_sub_f32_e32 v21, v11, v15
	v_sub_f32_e32 v9, v9, v21
	v_sub_f32_e32 v2, v2, v15
	v_add_f32_e32 v3, v11, v3
	v_add_f32_e32 v2, v2, v9
	v_add_f32_e32 v9, v14, v3
	v_sub_f32_e32 v11, v9, v14
	v_sub_f32_e32 v3, v3, v11
	v_add_f32_e32 v2, v2, v3
	v_add_f32_e32 v2, v9, v2
	v_cndmask_b32_e64 v2, v185, v2, s[18:19]
	v_sub_f32_e32 v17, v17, v16
	v_cndmask_b32_e64 v2, v186, v2, s[20:21]
	v_max_f32_e32 v19, 0xff800000, v17
	v_sub_f32_e32 v18, v12, v13
	v_cndmask_b32_e64 v2, v187, v2, s[22:23]
	v_max_f32_e32 v12, v19, v18
	s_waitcnt vmcnt(0)
	v_sub_f32_e32 v20, v8, v10
	v_cndmask_b32_e64 v2, v2, v6, s[24:25]
	v_max_f32_e32 v8, v12, v20
	v_sub_f32_e32 v2, v7, v2
	v_max_f32_e32 v3, v4, v4
	v_add_f32_e32 v2, v10, v2
	v_max_f32_e32 v21, v3, v8
	v_sub_f32_e32 v11, v5, v2
	v_max_f32_e32 v5, v3, v19
	v_max_f32_e32 v19, v3, v12
	v_sub_f32_e32 v3, v4, v21
	v_mul_f32_e32 v3, 0x3fb8aa3b, v3
	v_exp_f32_e32 v188, v3
	v_add_f32_e32 v3, v10, v21
	v_max3_f32 v10, v4, v8, v11
	v_add_f32_e32 v101, v2, v10
	v_mul_f32_e32 v2, 0xbfb8aa3b, v101
	v_sub_f32_e32 v6, v4, v5
	v_exp_f32_e32 v23, v2
	v_sub_f32_e32 v2, v17, v10
	v_mul_f32_e32 v6, 0x3fb8aa3b, v6
	v_mul_f32_e32 v2, 0x3fb8aa3b, v2
	v_exp_f32_e32 v190, v6
	v_add_f32_e32 v6, v16, v5
	v_exp_f32_e32 v146, v2
	v_sub_f32_e32 v2, v18, v10
	v_mul_f32_e32 v6, 0xbfb8aa3b, v6
	v_mul_f32_e32 v2, 0x3fb8aa3b, v2
	v_exp_f32_e32 v16, v6
	v_sub_f32_e32 v6, v4, v19
	v_exp_f32_e32 v147, v2
	v_sub_f32_e32 v2, v20, v10
	v_mul_f32_e32 v6, 0x3fb8aa3b, v6
	v_mul_f32_e32 v3, 0xbfb8aa3b, v3
	v_mul_f32_e32 v2, 0x3fb8aa3b, v2
	v_exp_f32_e32 v189, v6
	v_add_f32_e32 v6, v13, v19
	v_exp_f32_e32 v22, v3
	v_sub_f32_e32 v3, v4, v10
	v_exp_f32_e32 v148, v2
	v_sub_f32_e32 v2, v17, v5
	v_mul_f32_e32 v6, 0xbfb8aa3b, v6
	v_mul_f32_e32 v3, 0x3fb8aa3b, v3
	v_mul_f32_e32 v2, 0x3fb8aa3b, v2
	v_exp_f32_e32 v13, v6
	v_exp_f32_e32 v144, v3
	s_barrier
	v_exp_f32_e32 v24, v2
	ds_read_b32 v25, v107 offset:8192
	ds_read_b128 v[2:5], v107 offset:8240
	ds_read_b128 v[6:9], v107 offset:8256
	v_sub_f32_e32 v26, v11, v10
	v_mul_f32_e32 v26, 0x3fb8aa3b, v26
	s_waitcnt lgkmcnt(2)
	v_fma_f32 v27, v24, v25, 0
	v_mul_f32_e32 v191, v24, v25
	s_waitcnt lgkmcnt(0)
	v_fmac_f32_e32 v27, v190, v6
	v_max_f32_e32 v6, v16, v16
	v_max_f32_e64 v6, |v27|, v6
	v_div_scale_f32 v16, s[18:19], v6, v6, 1.0
	v_rcp_f32_e32 v27, v16
	v_exp_f32_e32 v149, v26
	ds_read_b64 v[14:15], v107 offset:8208
	ds_read_b96 v[10:12], v107 offset:8224
	v_mul_f32_e32 v201, v146, v2
	v_fma_f32 v24, -v16, v27, 1.0
	v_fmac_f32_e32 v27, v24, v27
	v_div_scale_f32 v24, vcc, 1.0, v6, 1.0
	v_mul_f32_e32 v25, v24, v27
	v_fma_f32 v26, -v16, v25, v24
	v_fmac_f32_e32 v25, v26, v27
	v_fma_f32 v16, -v16, v25, v24
	v_sub_f32_e32 v24, v17, v19
	v_mul_f32_e32 v24, 0x3fb8aa3b, v24
	v_sub_f32_e32 v19, v18, v19
	v_exp_f32_e32 v24, v24
	v_mul_f32_e32 v19, 0x3fb8aa3b, v19
	v_exp_f32_e32 v19, v19
	v_div_fmas_f32 v16, v16, v27, v25
	s_waitcnt lgkmcnt(1)
	v_fma_f32 v25, v24, v14, 0
	v_div_fixup_f32 v196, v16, v6, 1.0
	v_fmac_f32_e32 v25, v19, v15
	v_fmac_f32_e32 v25, v189, v7
	v_max_f32_e32 v7, v13, v13
	v_max_f32_e64 v7, |v25|, v7
	v_div_scale_f32 v13, s[18:19], v7, v7, 1.0
	v_rcp_f32_e32 v25, v13
	v_mul_f32_e32 v195, v24, v14
	v_mul_f32_e32 v194, v19, v15
	v_fma_f32 v2, v146, v2, 0
	v_fma_f32 v6, -v13, v25, 1.0
	v_fmac_f32_e32 v25, v6, v25
	v_div_scale_f32 v6, vcc, 1.0, v7, 1.0
	v_mul_f32_e32 v14, v6, v25
	v_fma_f32 v15, -v13, v14, v6
	v_fmac_f32_e32 v14, v15, v25
	v_fma_f32 v6, -v13, v14, v6
	v_sub_f32_e32 v13, v17, v21
	v_div_fmas_f32 v6, v6, v25, v14
	v_mul_f32_e32 v13, 0x3fb8aa3b, v13
	v_sub_f32_e32 v14, v18, v21
	v_exp_f32_e32 v13, v13
	v_mul_f32_e32 v14, 0x3fb8aa3b, v14
	v_sub_f32_e32 v15, v20, v21
	v_exp_f32_e32 v14, v14
	v_mul_f32_e32 v15, 0x3fb8aa3b, v15
	v_exp_f32_e32 v15, v15
	v_div_fixup_f32 v197, v6, v7, 1.0
	s_waitcnt lgkmcnt(0)
	v_fma_f32 v6, v13, v10, 0
	v_fmac_f32_e32 v6, v14, v11
	v_fmac_f32_e32 v6, v15, v12
	v_fmac_f32_e32 v6, v188, v8
	v_max_f32_e32 v7, v22, v22
	v_max_f32_e64 v6, |v6|, v7
	v_div_scale_f32 v7, s[18:19], v6, v6, 1.0
	v_rcp_f32_e32 v8, v7
	v_mul_f32_e32 v200, v13, v10
	v_mul_f32_e32 v199, v14, v11
	v_mul_f32_e32 v198, v15, v12
	v_fma_f32 v10, -v7, v8, 1.0
	v_fmac_f32_e32 v8, v10, v8
	v_div_scale_f32 v10, vcc, 1.0, v6, 1.0
	v_mul_f32_e32 v11, v10, v8
	v_fma_f32 v12, -v7, v11, v10
	v_fmac_f32_e32 v11, v12, v8
	v_fmac_f32_e32 v2, v147, v3
	v_fma_f32 v7, -v7, v11, v10
	v_fmac_f32_e32 v2, v148, v4
	v_div_fmas_f32 v7, v7, v8, v11
	v_fmac_f32_e32 v2, v149, v5
	v_div_fixup_f32 v202, v7, v6, 1.0
	v_fmac_f32_e32 v2, v144, v9
	v_max_f32_e32 v6, v23, v23
	v_max_f32_e64 v2, |v2|, v6
	v_div_scale_f32 v6, s[18:19], v2, v2, 1.0
	v_rcp_f32_e32 v7, v6
	v_mul_f32_e32 v205, v147, v3
	v_mul_f32_e32 v204, v148, v4
	v_mul_f32_e32 v203, v149, v5
	v_fma_f32 v3, -v6, v7, 1.0
	v_fmac_f32_e32 v7, v3, v7
	v_div_scale_f32 v3, vcc, 1.0, v2, 1.0
	v_mul_f32_e32 v4, v3, v7
	v_fma_f32 v5, -v6, v4, v3
	v_fmac_f32_e32 v4, v5, v7
	v_fma_f32 v3, -v6, v4, v3
	v_div_fmas_f32 v3, v3, v7, v4
	v_div_fixup_f32 v206, v3, v2, 1.0
	v_lshl_add_u64 v[2:3], v[0:1], 0, v[126:127]
	v_lshl_add_u64 v[4:5], v[0:1], 0, v[128:129]
	global_load_dwordx4 v[80:83], v[2:3], off nt
	global_load_dwordx4 v[72:75], v[4:5], off nt
	v_lshl_add_u64 v[2:3], v[0:1], 0, v[130:131]
	v_lshl_add_u64 v[4:5], v[0:1], 0, v[132:133]
	global_load_dwordx4 v[64:67], v[2:3], off nt
	global_load_dwordx4 v[56:59], v[4:5], off nt
	v_lshl_add_u64 v[2:3], v[0:1], 0, v[134:135]
	v_lshl_add_u64 v[4:5], v[0:1], 0, v[136:137]
	global_load_dwordx4 v[48:51], v[2:3], off nt
	global_load_dwordx4 v[40:43], v[4:5], off nt
	v_lshl_add_u64 v[2:3], v[0:1], 0, v[138:139]
	v_lshl_add_u64 v[0:1], v[0:1], 0, v[140:141]
	global_load_dwordx4 v[36:39], v[2:3], off nt
	global_load_dwordx4 v[8:11], v[0:1], off nt
	ds_read_b128 v[32:35], v168
	ds_read_b128 v[24:27], v168 offset:512
	ds_read_b128 v[28:31], v168 offset:2048
	ds_read_b128 v[20:23], v168 offset:2560
	ds_read_b128 v[16:19], v168 offset:1024
	ds_read_b128 v[12:15], v168 offset:1536
	ds_read_b128 v[4:7], v168 offset:3072
	ds_read_b128 v[0:3], v168 offset:3584
	ds_read2st64_b32 v[152:153], v169 offset0:16 offset1:20
	s_waitcnt lgkmcnt(8)
	v_mul_f32_e32 v145, v93, v33
	v_mul_f32_e32 v154, v95, v35
	v_fmac_f32_e32 v145, v92, v32
	v_fmac_f32_e32 v154, v94, v34
	v_add_f32_e32 v145, v145, v154
	s_waitcnt lgkmcnt(0)
	v_mul_f32_e32 v154, v146, v152
	v_pk_mul_f32 v[208:209], v[30:31], v[154:155] op_sel_hi:[1,0]
	v_pk_mul_f32 v[154:155], v[28:29], v[154:155] op_sel_hi:[1,0]
	v_mul_f32_e32 v207, v93, v25
	v_pk_fma_f32 v[154:155], v[92:93], v[144:145], v[154:155] op_sel_hi:[1,0,1]
	v_mul_f32_e32 v212, v93, v17
	v_mul_f32_e32 v93, v93, v13
	v_fmac_f32_e32 v207, v92, v24
	v_mul_f32_e32 v210, v95, v27
	v_fmac_f32_e32 v212, v92, v16
	v_mul_f32_e32 v213, v95, v19
	v_fmac_f32_e32 v93, v92, v12
	v_mul_f32_e32 v92, v95, v15
	v_fmac_f32_e32 v210, v94, v26
	v_fmac_f32_e32 v213, v94, v18
	v_fmac_f32_e32 v92, v94, v14
	v_pk_fma_f32 v[208:209], v[94:95], v[144:145], v[208:209] op_sel_hi:[1,0,1]
	v_add_f32_e32 v207, v207, v210
	v_mul_f32_e32 v210, v147, v153
	v_add_f32_e32 v213, v212, v213
	v_add_f32_e32 v92, v93, v92
	v_pk_fma_f32 v[208:209], v[22:23], v[210:211], v[208:209] op_sel_hi:[1,0,1]
	v_pk_fma_f32 v[210:211], v[20:21], v[210:211], v[154:155] op_sel_hi:[1,0,1]
	ds_read2st64_b32 v[154:155], v169 offset0:24 offset1:28
	ds_bpermute_b32 v93, v105, v145
	ds_bpermute_b32 v94, v105, v207
	ds_bpermute_b32 v95, v105, v213
	ds_bpermute_b32 v214, v105, v92
	s_waitcnt lgkmcnt(4)
	v_mul_f32_e32 v212, v148, v154
	s_waitcnt lgkmcnt(3)
	v_add_f32_e32 v145, v145, v93
	s_waitcnt lgkmcnt(2)
	v_add_f32_e32 v94, v207, v94
	s_waitcnt lgkmcnt(1)
	v_add_f32_e32 v95, v213, v95
	s_waitcnt lgkmcnt(0)
	v_add_f32_e32 v207, v92, v214
	v_pk_fma_f32 v[216:217], v[4:5], v[212:213], v[210:211] op_sel_hi:[1,0,1]
	ds_bpermute_b32 v210, v156, v145
	ds_bpermute_b32 v211, v156, v94
	ds_bpermute_b32 v213, v156, v95
	ds_bpermute_b32 v214, v156, v207
	v_lshl_add_u64 v[150:151], v[150:151], 2, s[68:69]
	s_waitcnt lgkmcnt(3)
	v_add_f32_e32 v145, v145, v210
	s_waitcnt lgkmcnt(2)
	v_add_f32_e32 v94, v94, v211
	s_waitcnt lgkmcnt(1)
	v_add_f32_e32 v95, v95, v213
	s_waitcnt lgkmcnt(0)
	v_add_f32_e32 v207, v207, v214
	v_pk_fma_f32 v[92:93], v[6:7], v[212:213], v[208:209] op_sel_hi:[1,0,1]
	ds_bpermute_b32 v208, v157, v145
	ds_bpermute_b32 v209, v157, v94
	ds_bpermute_b32 v210, v157, v95
	ds_bpermute_b32 v211, v157, v207
	v_mul_f32_e32 v212, v149, v155
	s_waitcnt lgkmcnt(3)
	v_add_f32_e32 v145, v145, v208
	s_waitcnt lgkmcnt(2)
	v_add_f32_e32 v94, v94, v209
	s_waitcnt lgkmcnt(1)
	v_add_f32_e32 v95, v95, v210
	s_waitcnt lgkmcnt(0)
	v_add_f32_e32 v207, v207, v211
	ds_bpermute_b32 v208, v158, v145
	ds_bpermute_b32 v209, v158, v94
	ds_bpermute_b32 v210, v158, v95
	ds_bpermute_b32 v211, v158, v207
	v_pk_fma_f32 v[214:215], v[2:3], v[212:213], v[92:93] op_sel_hi:[1,0,1]
	s_waitcnt lgkmcnt(3)
	v_add_f32_e32 v92, v145, v208
	s_waitcnt lgkmcnt(2)
	v_add_f32_e32 v93, v94, v209
	s_waitcnt lgkmcnt(1)
	v_add_f32_e32 v94, v95, v210
	s_waitcnt lgkmcnt(0)
	v_add_f32_e32 v145, v207, v211
	ds_bpermute_b32 v95, v159, v92
	ds_bpermute_b32 v208, v159, v93
	ds_bpermute_b32 v209, v159, v94
	ds_bpermute_b32 v210, v159, v145
	v_pk_fma_f32 v[212:213], v[0:1], v[212:213], v[216:217] op_sel_hi:[1,0,1]
	v_lshl_add_u64 v[216:217], v[150:151], 0, v[108:109]
	v_add_u32_e32 v207, 0x50, v169
	global_store_dwordx4 v[216:217], v[212:215], off nt
	s_and_saveexec_b64 s[18:19], s[10:11]
	s_cbranch_execz .LBB0_551
	s_waitcnt lgkmcnt(2)
	v_add_f32_e32 v93, v93, v208
	v_add_f32_e32 v92, v92, v95
	v_mul_f32_e32 v92, v190, v92
	v_mul_f32_e32 v93, v189, v93
	v_fmac_f32_e32 v92, v191, v152
	v_fmac_f32_e32 v93, v195, v152
	v_fmac_f32_e32 v92, 0, v153
	v_fmac_f32_e32 v93, v194, v153
	v_fmac_f32_e32 v92, 0, v154
	v_fmac_f32_e32 v93, 0, v154
	v_fmac_f32_e32 v92, 0, v155
	v_fmac_f32_e32 v93, 0, v155
	s_waitcnt lgkmcnt(0)
	v_add_f32_e32 v145, v145, v210
	v_add_f32_e32 v94, v94, v209
	v_mul_f32_e32 v92, v196, v92
	v_mul_f32_e32 v93, v197, v93
	ds_write2st64_b32 v207, v92, v93 offset0:32 offset1:36
	v_mul_f32_e32 v92, v188, v94
	v_mul_f32_e32 v93, v144, v145
	v_fmac_f32_e32 v92, v200, v152
	v_fmac_f32_e32 v93, v201, v152
	v_fmac_f32_e32 v92, v199, v153
	v_fmac_f32_e32 v93, v205, v153
	v_fmac_f32_e32 v92, v198, v154
	v_fmac_f32_e32 v93, v204, v154
	v_fmac_f32_e32 v92, 0, v155
	v_fmac_f32_e32 v93, v203, v155
	v_mul_f32_e32 v92, v202, v92
	v_mul_f32_e32 v93, v206, v93
	ds_write2st64_b32 v207, v92, v93 offset0:40 offset1:44
.LBB0_551:
	s_or_b64 exec, exec, s[18:19]
	v_add_u32_e32 v155, 64, v169
	s_waitcnt lgkmcnt(3)
	ds_read2st64_b32 v[94:95], v155 offset0:16 offset1:20
	v_mul_f32_e32 v92, v89, v33
	v_mul_f32_e32 v93, v91, v35
	v_fmac_f32_e32 v92, v88, v32
	v_fmac_f32_e32 v93, v90, v34
	v_add_f32_e32 v214, v92, v93
	s_waitcnt lgkmcnt(0)
	v_mul_f32_e32 v92, v146, v94
	v_mul_f32_e32 v154, v89, v25
	v_mul_f32_e32 v210, v91, v27
	v_mov_b32_e32 v145, v144
	v_pk_mul_f32 v[152:153], v[30:31], v[92:93] op_sel_hi:[1,0]
	v_pk_mul_f32 v[208:209], v[28:29], v[92:93] op_sel_hi:[1,0]
	v_mov_b32_e32 v92, v144
	v_mov_b32_e32 v93, v144
	v_fmac_f32_e32 v154, v88, v24
	v_fmac_f32_e32 v210, v90, v26
	v_pk_fma_f32 v[152:153], v[90:91], v[92:93], v[152:153]
	v_pk_fma_f32 v[208:209], v[88:89], v[144:145], v[208:209]
	v_add_f32_e32 v215, v154, v210
	v_mul_f32_e32 v154, v147, v95
	v_pk_fma_f32 v[210:211], v[22:23], v[154:155], v[152:153] op_sel_hi:[1,0,1]
	v_pk_fma_f32 v[208:209], v[20:21], v[154:155], v[208:209] op_sel_hi:[1,0,1]
	v_mul_f32_e32 v154, v89, v17
	v_mul_f32_e32 v89, v89, v13
	v_fmac_f32_e32 v154, v88, v16
	v_mul_f32_e32 v212, v91, v19
	v_fmac_f32_e32 v89, v88, v12
	v_mul_f32_e32 v88, v91, v15
	v_fmac_f32_e32 v212, v90, v18
	v_fmac_f32_e32 v88, v90, v14
	ds_read2st64_b32 v[152:153], v155 offset0:24 offset1:28
	v_add_f32_e32 v216, v154, v212
	v_add_f32_e32 v88, v89, v88
	ds_bpermute_b32 v89, v105, v214
	ds_bpermute_b32 v90, v105, v215
	ds_bpermute_b32 v91, v105, v216
	ds_bpermute_b32 v217, v105, v88
	s_waitcnt lgkmcnt(4)
	v_mul_f32_e32 v154, v148, v152
	v_pk_fma_f32 v[212:213], v[4:5], v[154:155], v[208:209] op_sel_hi:[1,0,1]
	s_waitcnt lgkmcnt(3)
	v_add_f32_e32 v208, v214, v89
	s_waitcnt lgkmcnt(2)
	v_add_f32_e32 v90, v215, v90
	s_waitcnt lgkmcnt(1)
	v_add_f32_e32 v91, v216, v91
	s_waitcnt lgkmcnt(0)
	v_add_f32_e32 v209, v88, v217
	ds_bpermute_b32 v214, v156, v208
	ds_bpermute_b32 v215, v156, v90
	ds_bpermute_b32 v216, v156, v91
	ds_bpermute_b32 v217, v156, v209
	v_pk_fma_f32 v[88:89], v[6:7], v[154:155], v[210:211] op_sel_hi:[1,0,1]
	s_waitcnt lgkmcnt(3)
	v_add_f32_e32 v208, v208, v214
	s_waitcnt lgkmcnt(2)
	v_add_f32_e32 v90, v90, v215
	s_waitcnt lgkmcnt(1)
	v_add_f32_e32 v91, v91, v216
	s_waitcnt lgkmcnt(0)
	v_add_f32_e32 v209, v209, v217
	ds_bpermute_b32 v210, v157, v208
	ds_bpermute_b32 v211, v157, v90
	ds_bpermute_b32 v214, v157, v91
	ds_bpermute_b32 v215, v157, v209
	v_mul_f32_e32 v154, v149, v153
	s_waitcnt lgkmcnt(3)
	v_add_f32_e32 v208, v208, v210
	s_waitcnt lgkmcnt(2)
	v_add_f32_e32 v90, v90, v211
	s_waitcnt lgkmcnt(1)
	v_add_f32_e32 v91, v91, v214
	s_waitcnt lgkmcnt(0)
	v_add_f32_e32 v209, v209, v215
	ds_bpermute_b32 v210, v158, v208
	ds_bpermute_b32 v211, v158, v90
	ds_bpermute_b32 v216, v158, v91
	ds_bpermute_b32 v217, v158, v209
	v_pk_fma_f32 v[214:215], v[2:3], v[154:155], v[88:89] op_sel_hi:[1,0,1]
	s_waitcnt lgkmcnt(3)
	v_add_f32_e32 v88, v208, v210
	s_waitcnt lgkmcnt(2)
	v_add_f32_e32 v89, v90, v211
	s_waitcnt lgkmcnt(1)
	v_add_f32_e32 v90, v91, v216
	s_waitcnt lgkmcnt(0)
	v_add_f32_e32 v208, v209, v217
	ds_bpermute_b32 v91, v159, v88
	ds_bpermute_b32 v209, v159, v89
	ds_bpermute_b32 v210, v159, v90
	ds_bpermute_b32 v211, v159, v208
	v_pk_fma_f32 v[212:213], v[0:1], v[154:155], v[212:213] op_sel_hi:[1,0,1]
	v_lshl_add_u64 v[216:217], v[150:151], 0, v[110:111]
	v_add_u32_e32 v154, 0x90, v169
	global_store_dwordx4 v[216:217], v[212:215], off nt
	s_and_saveexec_b64 s[18:19], s[10:11]
	s_cbranch_execz .LBB0_553
	s_waitcnt lgkmcnt(2)
	v_add_f32_e32 v89, v89, v209
	v_add_f32_e32 v88, v88, v91
	v_mul_f32_e32 v88, v190, v88
	v_mul_f32_e32 v89, v189, v89
	v_fmac_f32_e32 v88, v191, v94
	v_fmac_f32_e32 v89, v195, v94
	v_fmac_f32_e32 v88, 0, v95
	v_fmac_f32_e32 v89, v194, v95
	v_fmac_f32_e32 v88, 0, v152
	v_fmac_f32_e32 v89, 0, v152
	v_fmac_f32_e32 v88, 0, v153
	v_fmac_f32_e32 v89, 0, v153
	s_waitcnt lgkmcnt(0)
	v_add_f32_e32 v208, v208, v211
	v_add_f32_e32 v90, v90, v210
	v_mul_f32_e32 v88, v196, v88
	v_mul_f32_e32 v89, v197, v89
	ds_write2st64_b32 v154, v88, v89 offset0:32 offset1:36
	v_mul_f32_e32 v88, v188, v90
	v_mul_f32_e32 v89, v144, v208
	v_fmac_f32_e32 v88, v200, v94
	v_fmac_f32_e32 v89, v201, v94
	v_fmac_f32_e32 v88, v199, v95
	v_fmac_f32_e32 v89, v205, v95
	v_fmac_f32_e32 v88, v198, v152
	v_fmac_f32_e32 v89, v204, v152
	v_fmac_f32_e32 v88, 0, v153
	v_fmac_f32_e32 v89, v203, v153
	v_mul_f32_e32 v88, v202, v88
	v_mul_f32_e32 v89, v206, v89
	ds_write2st64_b32 v154, v88, v89 offset0:40 offset1:44
.LBB0_553:
	s_or_b64 exec, exec, s[18:19]
	v_add_u32_e32 v94, 0x80, v169
	ds_read2st64_b32 v[88:89], v94 offset0:16 offset1:20
	v_mul_f32_e32 v90, v85, v33
	s_waitcnt lgkmcnt(4)
	v_mul_f32_e32 v91, v87, v35
	v_fmac_f32_e32 v90, v84, v32
	v_fmac_f32_e32 v91, v86, v34
	v_add_f32_e32 v95, v90, v91
	s_waitcnt lgkmcnt(0)
	v_mul_f32_e32 v90, v146, v88
	v_pk_mul_f32 v[152:153], v[30:31], v[90:91] op_sel_hi:[1,0]
	v_pk_mul_f32 v[90:91], v[28:29], v[90:91] op_sel_hi:[1,0]
	v_pk_fma_f32 v[92:93], v[86:87], v[92:93], v[152:153]
	v_pk_fma_f32 v[90:91], v[84:85], v[144:145], v[90:91]
	v_mul_f32_e32 v152, v85, v25
	v_mul_f32_e32 v153, v87, v27
	v_mul_f32_e32 v208, v85, v17
	v_mul_f32_e32 v85, v85, v13
	v_fmac_f32_e32 v152, v84, v24
	v_fmac_f32_e32 v153, v86, v26
	v_fmac_f32_e32 v208, v84, v16
	v_mul_f32_e32 v210, v87, v19
	v_fmac_f32_e32 v85, v84, v12
	v_mul_f32_e32 v84, v87, v15
	v_add_f32_e32 v209, v152, v153
	v_mul_f32_e32 v152, v147, v89
	v_fmac_f32_e32 v210, v86, v18
	v_fmac_f32_e32 v84, v86, v14
	v_pk_fma_f32 v[92:93], v[22:23], v[152:153], v[92:93] op_sel_hi:[1,0,1]
	v_pk_fma_f32 v[152:153], v[20:21], v[152:153], v[90:91] op_sel_hi:[1,0,1]
	ds_read2st64_b32 v[90:91], v94 offset0:24 offset1:28
	v_add_f32_e32 v210, v208, v210
	v_add_f32_e32 v84, v85, v84
	ds_bpermute_b32 v85, v105, v95
	ds_bpermute_b32 v86, v105, v209
	ds_bpermute_b32 v87, v105, v210
	ds_bpermute_b32 v211, v105, v84
	s_waitcnt lgkmcnt(4)
	v_mul_f32_e32 v208, v148, v90
	v_pk_fma_f32 v[212:213], v[4:5], v[208:209], v[152:153] op_sel_hi:[1,0,1]
	s_waitcnt lgkmcnt(3)
	v_add_f32_e32 v95, v95, v85
	s_waitcnt lgkmcnt(2)
	v_add_f32_e32 v86, v209, v86
	s_waitcnt lgkmcnt(1)
	v_add_f32_e32 v87, v210, v87
	s_waitcnt lgkmcnt(0)
	v_add_f32_e32 v152, v84, v211
	ds_bpermute_b32 v153, v156, v95
	ds_bpermute_b32 v209, v156, v86
	ds_bpermute_b32 v210, v156, v87
	ds_bpermute_b32 v211, v156, v152
	s_waitcnt lgkmcnt(2)
	v_pk_fma_f32 v[84:85], v[6:7], v[208:209], v[92:93] op_sel_hi:[1,0,1]
	v_add_f32_e32 v93, v95, v153
	v_add_f32_e32 v86, v86, v209
	s_waitcnt lgkmcnt(1)
	v_add_f32_e32 v87, v87, v210
	s_waitcnt lgkmcnt(0)
	v_add_f32_e32 v95, v152, v211
	ds_bpermute_b32 v152, v157, v93
	ds_bpermute_b32 v153, v157, v86
	ds_bpermute_b32 v208, v157, v87
	ds_bpermute_b32 v209, v157, v95
	v_mul_f32_e32 v92, v149, v91
	s_waitcnt lgkmcnt(3)
	v_add_f32_e32 v93, v93, v152
	s_waitcnt lgkmcnt(2)
	v_add_f32_e32 v86, v86, v153
	s_waitcnt lgkmcnt(1)
	v_add_f32_e32 v87, v87, v208
	s_waitcnt lgkmcnt(0)
	v_add_f32_e32 v95, v95, v209
	ds_bpermute_b32 v152, v158, v93
	ds_bpermute_b32 v153, v158, v86
	ds_bpermute_b32 v208, v158, v87
	ds_bpermute_b32 v209, v158, v95
	v_pk_fma_f32 v[210:211], v[2:3], v[92:93], v[84:85] op_sel_hi:[1,0,1]
	s_waitcnt lgkmcnt(3)
	v_add_f32_e32 v84, v93, v152
	s_waitcnt lgkmcnt(2)
	v_add_f32_e32 v85, v86, v153
	s_waitcnt lgkmcnt(1)
	v_add_f32_e32 v86, v87, v208
	s_waitcnt lgkmcnt(0)
	v_add_f32_e32 v93, v95, v209
	ds_bpermute_b32 v87, v159, v84
	ds_bpermute_b32 v95, v159, v85
	ds_bpermute_b32 v152, v159, v86
	ds_bpermute_b32 v153, v159, v93
	v_pk_fma_f32 v[208:209], v[0:1], v[92:93], v[212:213] op_sel_hi:[1,0,1]
	v_lshl_add_u64 v[212:213], v[150:151], 0, v[112:113]
	v_add_u32_e32 v92, 0xd0, v169
	global_store_dwordx4 v[212:213], v[208:211], off nt
	s_and_saveexec_b64 s[18:19], s[10:11]
	s_cbranch_execz .LBB0_555
	s_waitcnt lgkmcnt(2)
	v_add_f32_e32 v85, v85, v95
	v_add_f32_e32 v84, v84, v87
	v_mul_f32_e32 v84, v190, v84
	v_mul_f32_e32 v85, v189, v85
	v_fmac_f32_e32 v84, v191, v88
	v_fmac_f32_e32 v85, v195, v88
	v_fmac_f32_e32 v84, 0, v89
	v_fmac_f32_e32 v85, v194, v89
	v_fmac_f32_e32 v84, 0, v90
	v_fmac_f32_e32 v85, 0, v90
	v_fmac_f32_e32 v84, 0, v91
	v_fmac_f32_e32 v85, 0, v91
	s_waitcnt lgkmcnt(0)
	v_add_f32_e32 v93, v93, v153
	v_add_f32_e32 v86, v86, v152
	v_mul_f32_e32 v84, v196, v84
	v_mul_f32_e32 v85, v197, v85
	ds_write2st64_b32 v92, v84, v85 offset0:32 offset1:36
	v_mul_f32_e32 v84, v188, v86
	v_mul_f32_e32 v85, v144, v93
	v_fmac_f32_e32 v84, v200, v88
	v_fmac_f32_e32 v85, v201, v88
	v_fmac_f32_e32 v84, v199, v89
	v_fmac_f32_e32 v85, v205, v89
	v_fmac_f32_e32 v84, v198, v90
	v_fmac_f32_e32 v85, v204, v90
	v_fmac_f32_e32 v84, 0, v91
	v_fmac_f32_e32 v85, v203, v91
	v_mul_f32_e32 v84, v202, v84
	v_mul_f32_e32 v85, v206, v85
	ds_write2st64_b32 v92, v84, v85 offset0:40 offset1:44
.LBB0_555:
	s_or_b64 exec, exec, s[18:19]
	v_add_u32_e32 v91, 0xc0, v169
	s_waitcnt lgkmcnt(3)
	ds_read2st64_b32 v[86:87], v91 offset0:16 offset1:20
	v_mul_f32_e32 v84, v77, v33
	v_mul_f32_e32 v85, v79, v35
	v_fmac_f32_e32 v84, v76, v32
	v_fmac_f32_e32 v85, v78, v34
	v_add_f32_e32 v93, v84, v85
	s_waitcnt lgkmcnt(0)
	v_mul_f32_e32 v84, v146, v86
	v_mul_f32_e32 v90, v77, v25
	v_mul_f32_e32 v95, v79, v27
	v_pk_mul_f32 v[88:89], v[30:31], v[84:85] op_sel_hi:[1,0]
	v_pk_mul_f32 v[152:153], v[28:29], v[84:85] op_sel_hi:[1,0]
	v_mov_b32_e32 v84, v144
	v_mov_b32_e32 v85, v144
	v_fmac_f32_e32 v90, v76, v24
	v_fmac_f32_e32 v95, v78, v26
	v_pk_fma_f32 v[88:89], v[78:79], v[84:85], v[88:89]
	v_pk_fma_f32 v[152:153], v[76:77], v[144:145], v[152:153]
	v_add_f32_e32 v95, v90, v95
	v_mul_f32_e32 v90, v147, v87
	v_pk_fma_f32 v[208:209], v[22:23], v[90:91], v[88:89] op_sel_hi:[1,0,1]
	v_pk_fma_f32 v[152:153], v[20:21], v[90:91], v[152:153] op_sel_hi:[1,0,1]
	v_mul_f32_e32 v90, v77, v17
	v_mul_f32_e32 v77, v77, v13
	v_fmac_f32_e32 v90, v76, v16
	v_mul_f32_e32 v210, v79, v19
	v_fmac_f32_e32 v77, v76, v12
	v_mul_f32_e32 v76, v79, v15
	v_fmac_f32_e32 v210, v78, v18
	v_fmac_f32_e32 v76, v78, v14
	v_add_f32_e32 v210, v90, v210
	v_add_f32_e32 v76, v77, v76
	ds_read2st64_b32 v[88:89], v91 offset0:24 offset1:28
	ds_bpermute_b32 v77, v105, v93
	ds_bpermute_b32 v78, v105, v95
	ds_bpermute_b32 v79, v105, v210
	ds_bpermute_b32 v211, v105, v76
	s_waitcnt lgkmcnt(4)
	v_mul_f32_e32 v90, v148, v88
	s_waitcnt lgkmcnt(3)
	v_add_f32_e32 v93, v93, v77
	s_waitcnt lgkmcnt(2)
	v_add_f32_e32 v78, v95, v78
	s_waitcnt lgkmcnt(1)
	v_add_f32_e32 v79, v210, v79
	s_waitcnt lgkmcnt(0)
	v_add_f32_e32 v95, v76, v211
	v_pk_fma_f32 v[212:213], v[4:5], v[90:91], v[152:153] op_sel_hi:[1,0,1]
	ds_bpermute_b32 v152, v156, v93
	ds_bpermute_b32 v153, v156, v78
	ds_bpermute_b32 v210, v156, v79
	ds_bpermute_b32 v211, v156, v95
	v_pk_fma_f32 v[76:77], v[6:7], v[90:91], v[208:209] op_sel_hi:[1,0,1]
	s_waitcnt lgkmcnt(3)
	v_add_f32_e32 v93, v93, v152
	s_waitcnt lgkmcnt(2)
	v_add_f32_e32 v78, v78, v153
	s_waitcnt lgkmcnt(1)
	v_add_f32_e32 v79, v79, v210
	s_waitcnt lgkmcnt(0)
	v_add_f32_e32 v95, v95, v211
	ds_bpermute_b32 v152, v157, v93
	ds_bpermute_b32 v153, v157, v78
	ds_bpermute_b32 v208, v157, v79
	ds_bpermute_b32 v209, v157, v95
	v_mul_f32_e32 v90, v149, v89
	s_waitcnt lgkmcnt(3)
	v_add_f32_e32 v93, v93, v152
	s_waitcnt lgkmcnt(2)
	v_add_f32_e32 v78, v78, v153
	s_waitcnt lgkmcnt(1)
	v_add_f32_e32 v79, v79, v208
	s_waitcnt lgkmcnt(0)
	v_add_f32_e32 v95, v95, v209
	ds_bpermute_b32 v152, v158, v93
	ds_bpermute_b32 v153, v158, v78
	ds_bpermute_b32 v208, v158, v79
	ds_bpermute_b32 v209, v158, v95
	v_pk_fma_f32 v[210:211], v[2:3], v[90:91], v[76:77] op_sel_hi:[1,0,1]
	s_waitcnt lgkmcnt(3)
	v_add_f32_e32 v76, v93, v152
	s_waitcnt lgkmcnt(2)
	v_add_f32_e32 v77, v78, v153
	s_waitcnt lgkmcnt(1)
	v_add_f32_e32 v78, v79, v208
	s_waitcnt lgkmcnt(0)
	v_add_f32_e32 v93, v95, v209
	ds_bpermute_b32 v79, v159, v76
	ds_bpermute_b32 v95, v159, v77
	ds_bpermute_b32 v152, v159, v78
	ds_bpermute_b32 v153, v159, v93
	v_pk_fma_f32 v[208:209], v[0:1], v[90:91], v[212:213] op_sel_hi:[1,0,1]
	v_lshl_add_u64 v[212:213], v[150:151], 0, v[114:115]
	v_add_u32_e32 v90, 16, v169
	global_store_dwordx4 v[212:213], v[208:211], off nt
	s_and_saveexec_b64 s[18:19], s[10:11]
	s_cbranch_execz .LBB0_557
	s_waitcnt lgkmcnt(2)
	v_add_f32_e32 v77, v77, v95
	v_add_f32_e32 v76, v76, v79
	v_mul_f32_e32 v76, v190, v76
	v_mul_f32_e32 v77, v189, v77
	v_fmac_f32_e32 v76, v191, v86
	v_fmac_f32_e32 v77, v195, v86
	v_fmac_f32_e32 v76, 0, v87
	v_fmac_f32_e32 v77, v194, v87
	v_fmac_f32_e32 v76, 0, v88
	v_fmac_f32_e32 v77, 0, v88
	v_fmac_f32_e32 v76, 0, v89
	v_fmac_f32_e32 v77, 0, v89
	s_waitcnt lgkmcnt(0)
	v_add_f32_e32 v93, v93, v153
	v_add_f32_e32 v78, v78, v152
	v_mul_f32_e32 v76, v196, v76
	v_mul_f32_e32 v77, v197, v77
	ds_write2st64_b32 v90, v76, v77 offset0:33 offset1:37
	v_mul_f32_e32 v76, v188, v78
	v_mul_f32_e32 v77, v144, v93
	v_fmac_f32_e32 v76, v200, v86
	v_fmac_f32_e32 v77, v201, v86
	v_fmac_f32_e32 v76, v199, v87
	v_fmac_f32_e32 v77, v205, v87
	v_fmac_f32_e32 v76, v198, v88
	v_fmac_f32_e32 v77, v204, v88
	v_fmac_f32_e32 v76, 0, v89
	v_fmac_f32_e32 v77, v203, v89
	v_mul_f32_e32 v76, v202, v76
	v_mul_f32_e32 v77, v206, v77
	ds_write2st64_b32 v90, v76, v77 offset0:41 offset1:45
.LBB0_557:
	s_or_b64 exec, exec, s[18:19]
	ds_read2st64_b32 v[76:77], v169 offset0:17 offset1:21
	v_mul_f32_e32 v78, v69, v33
	s_waitcnt lgkmcnt(4)
	v_mul_f32_e32 v79, v71, v35
	v_fmac_f32_e32 v78, v68, v32
	v_fmac_f32_e32 v79, v70, v34
	v_add_f32_e32 v88, v78, v79
	s_waitcnt lgkmcnt(0)
	v_mul_f32_e32 v78, v146, v76
	v_pk_mul_f32 v[86:87], v[30:31], v[78:79] op_sel_hi:[1,0]
	v_pk_mul_f32 v[78:79], v[28:29], v[78:79] op_sel_hi:[1,0]
	v_pk_fma_f32 v[84:85], v[70:71], v[84:85], v[86:87]
	v_mul_f32_e32 v86, v69, v25
	v_mul_f32_e32 v87, v71, v27
	v_fmac_f32_e32 v86, v68, v24
	v_fmac_f32_e32 v87, v70, v26
	v_pk_fma_f32 v[78:79], v[68:69], v[144:145], v[78:79]
	v_add_f32_e32 v89, v86, v87
	v_mul_f32_e32 v86, v147, v77
	v_pk_fma_f32 v[84:85], v[22:23], v[86:87], v[84:85] op_sel_hi:[1,0,1]
	v_pk_fma_f32 v[86:87], v[20:21], v[86:87], v[78:79] op_sel_hi:[1,0,1]
	v_mul_f32_e32 v78, v69, v17
	v_mul_f32_e32 v69, v69, v13
	v_fmac_f32_e32 v78, v68, v16
	v_mul_f32_e32 v79, v71, v19
	v_fmac_f32_e32 v69, v68, v12
	v_mul_f32_e32 v68, v71, v15
	v_fmac_f32_e32 v79, v70, v18
	v_fmac_f32_e32 v68, v70, v14
	v_add_f32_e32 v93, v78, v79
	v_add_f32_e32 v69, v69, v68
	ds_bpermute_b32 v70, v105, v88
	ds_bpermute_b32 v71, v105, v89
	ds_bpermute_b32 v95, v105, v93
	ds_bpermute_b32 v152, v105, v69
	ds_read2st64_b32 v[78:79], v169 offset0:25 offset1:29
	s_waitcnt lgkmcnt(4)
	v_add_f32_e32 v70, v88, v70
	s_waitcnt lgkmcnt(3)
	v_add_f32_e32 v71, v89, v71
	s_waitcnt lgkmcnt(2)
	v_add_f32_e32 v93, v93, v95
	s_waitcnt lgkmcnt(1)
	v_add_f32_e32 v69, v69, v152
	ds_bpermute_b32 v95, v156, v70
	ds_bpermute_b32 v152, v156, v71
	ds_bpermute_b32 v153, v156, v93
	ds_bpermute_b32 v208, v156, v69
	s_waitcnt lgkmcnt(4)
	v_mul_f32_e32 v68, v148, v78
	v_pk_fma_f32 v[88:89], v[4:5], v[68:69], v[86:87] op_sel_hi:[1,0,1]
	s_waitcnt lgkmcnt(3)
	v_add_f32_e32 v70, v70, v95
	s_waitcnt lgkmcnt(2)
	v_add_f32_e32 v71, v71, v152
	s_waitcnt lgkmcnt(1)
	v_add_f32_e32 v86, v93, v153
	s_waitcnt lgkmcnt(0)
	v_add_f32_e32 v69, v69, v208
	ds_bpermute_b32 v87, v157, v70
	ds_bpermute_b32 v93, v157, v71
	ds_bpermute_b32 v95, v157, v86
	ds_bpermute_b32 v208, v157, v69
	v_pk_fma_f32 v[152:153], v[6:7], v[68:69], v[84:85] op_sel_hi:[1,0,1]
	s_waitcnt lgkmcnt(3)
	v_add_f32_e32 v68, v70, v87
	s_waitcnt lgkmcnt(2)
	v_add_f32_e32 v70, v71, v93
	s_waitcnt lgkmcnt(1)
	v_add_f32_e32 v71, v86, v95
	s_waitcnt lgkmcnt(0)
	v_add_f32_e32 v84, v69, v208
	ds_bpermute_b32 v69, v158, v68
	ds_bpermute_b32 v85, v158, v70
	ds_bpermute_b32 v86, v158, v71
	ds_bpermute_b32 v87, v158, v84
	v_mul_f32_e32 v208, v149, v79
	s_waitcnt lgkmcnt(3)
	v_add_f32_e32 v68, v68, v69
	s_waitcnt lgkmcnt(2)
	v_add_f32_e32 v69, v70, v85
	s_waitcnt lgkmcnt(1)
	v_add_f32_e32 v70, v71, v86
	s_waitcnt lgkmcnt(0)
	v_add_f32_e32 v84, v84, v87
	ds_bpermute_b32 v71, v159, v68
	ds_bpermute_b32 v85, v159, v69
	ds_bpermute_b32 v86, v159, v70
	ds_bpermute_b32 v87, v159, v84
	v_pk_fma_f32 v[210:211], v[2:3], v[208:209], v[152:153] op_sel_hi:[1,0,1]
	v_pk_fma_f32 v[208:209], v[0:1], v[208:209], v[88:89] op_sel_hi:[1,0,1]
	v_lshl_add_u64 v[88:89], v[150:151], 0, v[116:117]
	global_store_dwordx4 v[88:89], v[208:211], off nt
	s_and_saveexec_b64 s[18:19], s[10:11]
	s_cbranch_execz .LBB0_559
	s_waitcnt lgkmcnt(2)
	v_add_f32_e32 v69, v69, v85
	v_add_f32_e32 v68, v68, v71
	v_mul_f32_e32 v68, v190, v68
	v_mul_f32_e32 v69, v189, v69
	v_fmac_f32_e32 v68, v191, v76
	v_fmac_f32_e32 v69, v195, v76
	v_fmac_f32_e32 v68, 0, v77
	v_fmac_f32_e32 v69, v194, v77
	v_fmac_f32_e32 v68, 0, v78
	v_fmac_f32_e32 v69, 0, v78
	v_fmac_f32_e32 v68, 0, v79
	v_fmac_f32_e32 v69, 0, v79
	s_waitcnt lgkmcnt(0)
	v_add_f32_e32 v84, v84, v87
	v_add_f32_e32 v70, v70, v86
	v_mul_f32_e32 v68, v196, v68
	v_mul_f32_e32 v69, v197, v69
	ds_write2st64_b32 v207, v68, v69 offset0:33 offset1:37
	v_mul_f32_e32 v68, v188, v70
	v_mul_f32_e32 v69, v144, v84
	v_fmac_f32_e32 v68, v200, v76
	v_fmac_f32_e32 v69, v201, v76
	v_fmac_f32_e32 v68, v199, v77
	v_fmac_f32_e32 v69, v205, v77
	v_fmac_f32_e32 v68, v198, v78
	v_fmac_f32_e32 v69, v204, v78
	v_fmac_f32_e32 v68, 0, v79
	v_fmac_f32_e32 v69, v203, v79
	v_mul_f32_e32 v68, v202, v68
	v_mul_f32_e32 v69, v206, v69
	ds_write2st64_b32 v207, v68, v69 offset0:41 offset1:45
.LBB0_559:
	s_or_b64 exec, exec, s[18:19]
	s_waitcnt lgkmcnt(3)
	ds_read2st64_b32 v[70:71], v155 offset0:17 offset1:21
	v_mul_f32_e32 v68, v61, v33
	v_mul_f32_e32 v69, v63, v35
	v_fmac_f32_e32 v68, v60, v32
	v_fmac_f32_e32 v69, v62, v34
	s_waitcnt lgkmcnt(3)
	v_add_f32_e32 v85, v68, v69
	s_waitcnt lgkmcnt(0)
	v_mul_f32_e32 v68, v146, v70
	v_mul_f32_e32 v84, v61, v25
	v_mul_f32_e32 v86, v63, v27
	v_pk_mul_f32 v[76:77], v[30:31], v[68:69] op_sel_hi:[1,0]
	v_pk_mul_f32 v[78:79], v[28:29], v[68:69] op_sel_hi:[1,0]
	v_mov_b32_e32 v68, v144
	v_mov_b32_e32 v69, v144
	v_fmac_f32_e32 v84, v60, v24
	v_fmac_f32_e32 v86, v62, v26
	v_pk_fma_f32 v[76:77], v[62:63], v[68:69], v[76:77]
	v_add_f32_e32 v88, v84, v86
	v_mul_f32_e32 v84, v147, v71
	v_pk_fma_f32 v[78:79], v[60:61], v[144:145], v[78:79]
	v_pk_fma_f32 v[86:87], v[22:23], v[84:85], v[76:77] op_sel_hi:[1,0,1]
	v_mul_f32_e32 v76, v61, v17
	v_mul_f32_e32 v61, v61, v13
	v_fmac_f32_e32 v76, v60, v16
	v_mul_f32_e32 v77, v63, v19
	v_fmac_f32_e32 v61, v60, v12
	v_mul_f32_e32 v60, v63, v15
	v_fmac_f32_e32 v77, v62, v18
	v_fmac_f32_e32 v60, v62, v14
	v_pk_fma_f32 v[78:79], v[20:21], v[84:85], v[78:79] op_sel_hi:[1,0,1]
	v_add_f32_e32 v84, v76, v77
	v_add_f32_e32 v61, v61, v60
	ds_bpermute_b32 v62, v105, v85
	ds_bpermute_b32 v63, v105, v88
	ds_bpermute_b32 v89, v105, v84
	ds_bpermute_b32 v93, v105, v61
	ds_read2st64_b32 v[76:77], v155 offset0:25 offset1:29
	s_waitcnt lgkmcnt(4)
	v_add_f32_e32 v62, v85, v62
	s_waitcnt lgkmcnt(3)
	v_add_f32_e32 v63, v88, v63
	s_waitcnt lgkmcnt(2)
	v_add_f32_e32 v84, v84, v89
	s_waitcnt lgkmcnt(1)
	v_add_f32_e32 v61, v61, v93
	ds_bpermute_b32 v85, v156, v62
	ds_bpermute_b32 v88, v156, v63
	ds_bpermute_b32 v89, v156, v84
	ds_bpermute_b32 v93, v156, v61
	s_waitcnt lgkmcnt(4)
	v_mul_f32_e32 v60, v148, v76
	v_pk_fma_f32 v[152:153], v[4:5], v[60:61], v[78:79] op_sel_hi:[1,0,1]
	s_waitcnt lgkmcnt(3)
	v_add_f32_e32 v62, v62, v85
	s_waitcnt lgkmcnt(2)
	v_add_f32_e32 v63, v63, v88
	s_waitcnt lgkmcnt(1)
	v_add_f32_e32 v78, v84, v89
	s_waitcnt lgkmcnt(0)
	v_add_f32_e32 v61, v61, v93
	ds_bpermute_b32 v79, v157, v62
	ds_bpermute_b32 v84, v157, v63
	ds_bpermute_b32 v85, v157, v78
	ds_bpermute_b32 v88, v157, v61
	v_pk_fma_f32 v[86:87], v[6:7], v[60:61], v[86:87] op_sel_hi:[1,0,1]
	s_waitcnt lgkmcnt(3)
	v_add_f32_e32 v60, v62, v79
	s_waitcnt lgkmcnt(2)
	v_add_f32_e32 v62, v63, v84
	s_waitcnt lgkmcnt(1)
	v_add_f32_e32 v63, v78, v85
	s_waitcnt lgkmcnt(0)
	v_add_f32_e32 v78, v61, v88
	ds_bpermute_b32 v61, v158, v60
	ds_bpermute_b32 v79, v158, v62
	ds_bpermute_b32 v84, v158, v63
	ds_bpermute_b32 v85, v158, v78
	v_mul_f32_e32 v208, v149, v77
	s_waitcnt lgkmcnt(3)
	v_add_f32_e32 v60, v60, v61
	s_waitcnt lgkmcnt(2)
	v_add_f32_e32 v61, v62, v79
	s_waitcnt lgkmcnt(1)
	v_add_f32_e32 v62, v63, v84
	s_waitcnt lgkmcnt(0)
	v_add_f32_e32 v78, v78, v85
	ds_bpermute_b32 v63, v159, v60
	ds_bpermute_b32 v79, v159, v61
	ds_bpermute_b32 v84, v159, v62
	ds_bpermute_b32 v85, v159, v78
	v_pk_fma_f32 v[88:89], v[2:3], v[208:209], v[86:87] op_sel_hi:[1,0,1]
	v_pk_fma_f32 v[86:87], v[0:1], v[208:209], v[152:153] op_sel_hi:[1,0,1]
	v_lshl_add_u64 v[152:153], v[150:151], 0, v[118:119]
	global_store_dwordx4 v[152:153], v[86:89], off nt
	s_and_saveexec_b64 s[18:19], s[10:11]
	s_cbranch_execz .LBB0_561
	s_waitcnt lgkmcnt(2)
	v_add_f32_e32 v61, v61, v79
	v_add_f32_e32 v60, v60, v63
	v_mul_f32_e32 v60, v190, v60
	v_mul_f32_e32 v61, v189, v61
	v_fmac_f32_e32 v60, v191, v70
	v_fmac_f32_e32 v61, v195, v70
	v_fmac_f32_e32 v60, 0, v71
	v_fmac_f32_e32 v61, v194, v71
	v_fmac_f32_e32 v60, 0, v76
	v_fmac_f32_e32 v61, 0, v76
	v_fmac_f32_e32 v60, 0, v77
	v_fmac_f32_e32 v61, 0, v77
	s_waitcnt lgkmcnt(0)
	v_add_f32_e32 v78, v78, v85
	v_add_f32_e32 v62, v62, v84
	v_mul_f32_e32 v60, v196, v60
	v_mul_f32_e32 v61, v197, v61
	ds_write2st64_b32 v154, v60, v61 offset0:33 offset1:37
	v_mul_f32_e32 v60, v188, v62
	v_mul_f32_e32 v61, v144, v78
	v_fmac_f32_e32 v60, v200, v70
	v_fmac_f32_e32 v61, v201, v70
	v_fmac_f32_e32 v60, v199, v71
	v_fmac_f32_e32 v61, v205, v71
	v_fmac_f32_e32 v60, v198, v76
	v_fmac_f32_e32 v61, v204, v76
	v_fmac_f32_e32 v60, 0, v77
	v_fmac_f32_e32 v61, v203, v77
	v_mul_f32_e32 v60, v202, v60
	v_mul_f32_e32 v61, v206, v61
	ds_write2st64_b32 v154, v60, v61 offset0:41 offset1:45
.LBB0_561:
	s_or_b64 exec, exec, s[18:19]
	ds_read2st64_b32 v[60:61], v94 offset0:17 offset1:21
	v_mul_f32_e32 v62, v53, v33
	s_waitcnt lgkmcnt(4)
	v_mul_f32_e32 v63, v55, v35
	v_fmac_f32_e32 v62, v52, v32
	v_fmac_f32_e32 v63, v54, v34
	v_add_f32_e32 v76, v62, v63
	s_waitcnt lgkmcnt(0)
	v_mul_f32_e32 v62, v146, v60
	v_pk_mul_f32 v[70:71], v[30:31], v[62:63] op_sel_hi:[1,0]
	v_pk_mul_f32 v[62:63], v[28:29], v[62:63] op_sel_hi:[1,0]
	v_pk_fma_f32 v[68:69], v[54:55], v[68:69], v[70:71]
	v_mul_f32_e32 v70, v53, v25
	v_mul_f32_e32 v71, v55, v27
	v_fmac_f32_e32 v70, v52, v24
	v_fmac_f32_e32 v71, v54, v26
	v_pk_fma_f32 v[62:63], v[52:53], v[144:145], v[62:63]
	v_add_f32_e32 v77, v70, v71
	v_mul_f32_e32 v70, v147, v61
	v_pk_fma_f32 v[68:69], v[22:23], v[70:71], v[68:69] op_sel_hi:[1,0,1]
	v_pk_fma_f32 v[70:71], v[20:21], v[70:71], v[62:63] op_sel_hi:[1,0,1]
	v_mul_f32_e32 v62, v53, v17
	v_mul_f32_e32 v53, v53, v13
	v_fmac_f32_e32 v62, v52, v16
	v_mul_f32_e32 v63, v55, v19
	v_fmac_f32_e32 v53, v52, v12
	v_mul_f32_e32 v52, v55, v15
	v_fmac_f32_e32 v63, v54, v18
	v_fmac_f32_e32 v52, v54, v14
	v_add_f32_e32 v78, v62, v63
	v_add_f32_e32 v53, v53, v52
	ds_bpermute_b32 v54, v105, v76
	ds_bpermute_b32 v55, v105, v77
	ds_bpermute_b32 v79, v105, v78
	ds_bpermute_b32 v84, v105, v53
	ds_read2st64_b32 v[62:63], v94 offset0:25 offset1:29
	s_waitcnt lgkmcnt(4)
	v_add_f32_e32 v54, v76, v54
	s_waitcnt lgkmcnt(3)
	v_add_f32_e32 v55, v77, v55
	s_waitcnt lgkmcnt(2)
	v_add_f32_e32 v78, v78, v79
	s_waitcnt lgkmcnt(1)
	v_add_f32_e32 v53, v53, v84
	ds_bpermute_b32 v79, v156, v54
	ds_bpermute_b32 v84, v156, v55
	ds_bpermute_b32 v85, v156, v78
	ds_bpermute_b32 v86, v156, v53
	s_waitcnt lgkmcnt(4)
	v_mul_f32_e32 v52, v148, v62
	v_pk_fma_f32 v[76:77], v[4:5], v[52:53], v[70:71] op_sel_hi:[1,0,1]
	s_waitcnt lgkmcnt(3)
	v_add_f32_e32 v54, v54, v79
	s_waitcnt lgkmcnt(2)
	v_add_f32_e32 v55, v55, v84
	s_waitcnt lgkmcnt(1)
	v_add_f32_e32 v70, v78, v85
	s_waitcnt lgkmcnt(0)
	v_add_f32_e32 v53, v53, v86
	ds_bpermute_b32 v71, v157, v54
	ds_bpermute_b32 v84, v157, v55
	ds_bpermute_b32 v85, v157, v70
	ds_bpermute_b32 v86, v157, v53
	v_pk_fma_f32 v[78:79], v[6:7], v[52:53], v[68:69] op_sel_hi:[1,0,1]
	s_waitcnt lgkmcnt(3)
	v_add_f32_e32 v52, v54, v71
	s_waitcnt lgkmcnt(2)
	v_add_f32_e32 v54, v55, v84
	s_waitcnt lgkmcnt(1)
	v_add_f32_e32 v55, v70, v85
	s_waitcnt lgkmcnt(0)
	v_add_f32_e32 v68, v53, v86
	ds_bpermute_b32 v53, v158, v52
	ds_bpermute_b32 v69, v158, v54
	ds_bpermute_b32 v70, v158, v55
	ds_bpermute_b32 v71, v158, v68
	v_mul_f32_e32 v84, v149, v63
	s_waitcnt lgkmcnt(3)
	v_add_f32_e32 v52, v52, v53
	s_waitcnt lgkmcnt(2)
	v_add_f32_e32 v53, v54, v69
	s_waitcnt lgkmcnt(1)
	v_add_f32_e32 v54, v55, v70
	s_waitcnt lgkmcnt(0)
	v_add_f32_e32 v68, v68, v71
	ds_bpermute_b32 v55, v159, v52
	ds_bpermute_b32 v69, v159, v53
	ds_bpermute_b32 v70, v159, v54
	ds_bpermute_b32 v71, v159, v68
	v_pk_fma_f32 v[78:79], v[2:3], v[84:85], v[78:79] op_sel_hi:[1,0,1]
	v_pk_fma_f32 v[76:77], v[0:1], v[84:85], v[76:77] op_sel_hi:[1,0,1]
	v_lshl_add_u64 v[84:85], v[150:151], 0, v[120:121]
	global_store_dwordx4 v[84:85], v[76:79], off nt
	s_and_saveexec_b64 s[18:19], s[10:11]
	s_cbranch_execz .LBB0_563
	s_waitcnt lgkmcnt(2)
	v_add_f32_e32 v53, v53, v69
	v_add_f32_e32 v52, v52, v55
	v_mul_f32_e32 v52, v190, v52
	v_mul_f32_e32 v53, v189, v53
	v_fmac_f32_e32 v52, v191, v60
	v_fmac_f32_e32 v53, v195, v60
	v_fmac_f32_e32 v52, 0, v61
	v_fmac_f32_e32 v53, v194, v61
	v_fmac_f32_e32 v52, 0, v62
	v_fmac_f32_e32 v53, 0, v62
	v_fmac_f32_e32 v52, 0, v63
	v_fmac_f32_e32 v53, 0, v63
	s_waitcnt lgkmcnt(0)
	v_add_f32_e32 v68, v68, v71
	v_add_f32_e32 v54, v54, v70
	v_mul_f32_e32 v52, v196, v52
	v_mul_f32_e32 v53, v197, v53
	ds_write2st64_b32 v92, v52, v53 offset0:33 offset1:37
	v_mul_f32_e32 v52, v188, v54
	v_mul_f32_e32 v53, v144, v68
	v_fmac_f32_e32 v52, v200, v60
	v_fmac_f32_e32 v53, v201, v60
	v_fmac_f32_e32 v52, v199, v61
	v_fmac_f32_e32 v53, v205, v61
	v_fmac_f32_e32 v52, v198, v62
	v_fmac_f32_e32 v53, v204, v62
	v_fmac_f32_e32 v52, 0, v63
	v_fmac_f32_e32 v53, v203, v63
	v_mul_f32_e32 v52, v202, v52
	v_mul_f32_e32 v53, v206, v53
	ds_write2st64_b32 v92, v52, v53 offset0:41 offset1:45
.LBB0_563:
	s_or_b64 exec, exec, s[18:19]
	s_waitcnt lgkmcnt(3)
	ds_read2st64_b32 v[54:55], v91 offset0:17 offset1:21
	v_mul_f32_e32 v52, v45, v33
	v_mul_f32_e32 v53, v47, v35
	v_fmac_f32_e32 v52, v44, v32
	v_fmac_f32_e32 v53, v46, v34
	s_waitcnt lgkmcnt(3)
	v_add_f32_e32 v69, v52, v53
	s_waitcnt lgkmcnt(0)
	v_mul_f32_e32 v52, v146, v54
	v_mul_f32_e32 v68, v45, v25
	v_mul_f32_e32 v70, v47, v27
	v_pk_mul_f32 v[60:61], v[30:31], v[52:53] op_sel_hi:[1,0]
	v_pk_mul_f32 v[62:63], v[28:29], v[52:53] op_sel_hi:[1,0]
	v_mov_b32_e32 v52, v144
	v_mov_b32_e32 v53, v144
	v_fmac_f32_e32 v68, v44, v24
	v_fmac_f32_e32 v70, v46, v26
	v_pk_fma_f32 v[60:61], v[46:47], v[52:53], v[60:61]
	v_add_f32_e32 v76, v68, v70
	v_mul_f32_e32 v68, v147, v55
	v_pk_fma_f32 v[62:63], v[44:45], v[144:145], v[62:63]
	v_pk_fma_f32 v[70:71], v[22:23], v[68:69], v[60:61] op_sel_hi:[1,0,1]
	v_mul_f32_e32 v60, v45, v17
	v_mul_f32_e32 v45, v45, v13
	v_fmac_f32_e32 v60, v44, v16
	v_mul_f32_e32 v61, v47, v19
	v_fmac_f32_e32 v45, v44, v12
	v_mul_f32_e32 v44, v47, v15
	v_fmac_f32_e32 v61, v46, v18
	v_fmac_f32_e32 v44, v46, v14
	v_pk_fma_f32 v[62:63], v[20:21], v[68:69], v[62:63] op_sel_hi:[1,0,1]
	v_add_f32_e32 v68, v60, v61
	v_add_f32_e32 v45, v45, v44
	ds_bpermute_b32 v46, v105, v69
	ds_bpermute_b32 v47, v105, v76
	ds_bpermute_b32 v77, v105, v68
	ds_bpermute_b32 v78, v105, v45
	ds_read2st64_b32 v[60:61], v91 offset0:25 offset1:29
	s_waitcnt lgkmcnt(4)
	v_add_f32_e32 v46, v69, v46
	s_waitcnt lgkmcnt(3)
	v_add_f32_e32 v47, v76, v47
	s_waitcnt lgkmcnt(2)
	v_add_f32_e32 v68, v68, v77
	s_waitcnt lgkmcnt(1)
	v_add_f32_e32 v45, v45, v78
	ds_bpermute_b32 v69, v156, v46
	ds_bpermute_b32 v78, v156, v47
	ds_bpermute_b32 v79, v156, v68
	ds_bpermute_b32 v84, v156, v45
	s_waitcnt lgkmcnt(4)
	v_mul_f32_e32 v44, v148, v60
	v_pk_fma_f32 v[76:77], v[4:5], v[44:45], v[62:63] op_sel_hi:[1,0,1]
	s_waitcnt lgkmcnt(3)
	v_add_f32_e32 v46, v46, v69
	s_waitcnt lgkmcnt(2)
	v_add_f32_e32 v47, v47, v78
	s_waitcnt lgkmcnt(1)
	v_add_f32_e32 v62, v68, v79
	s_waitcnt lgkmcnt(0)
	v_add_f32_e32 v45, v45, v84
	ds_bpermute_b32 v63, v157, v46
	ds_bpermute_b32 v68, v157, v47
	ds_bpermute_b32 v69, v157, v62
	ds_bpermute_b32 v78, v157, v45
	v_pk_fma_f32 v[70:71], v[6:7], v[44:45], v[70:71] op_sel_hi:[1,0,1]
	s_waitcnt lgkmcnt(3)
	v_add_f32_e32 v44, v46, v63
	s_waitcnt lgkmcnt(2)
	v_add_f32_e32 v46, v47, v68
	s_waitcnt lgkmcnt(1)
	v_add_f32_e32 v47, v62, v69
	s_waitcnt lgkmcnt(0)
	v_add_f32_e32 v62, v45, v78
	ds_bpermute_b32 v45, v158, v44
	ds_bpermute_b32 v63, v158, v46
	ds_bpermute_b32 v68, v158, v47
	ds_bpermute_b32 v69, v158, v62
	v_mul_f32_e32 v84, v149, v61
	s_waitcnt lgkmcnt(3)
	v_add_f32_e32 v44, v44, v45
	s_waitcnt lgkmcnt(2)
	v_add_f32_e32 v45, v46, v63
	s_waitcnt lgkmcnt(1)
	v_add_f32_e32 v46, v47, v68
	s_waitcnt lgkmcnt(0)
	v_add_f32_e32 v62, v62, v69
	ds_bpermute_b32 v47, v159, v44
	ds_bpermute_b32 v63, v159, v45
	ds_bpermute_b32 v68, v159, v46
	ds_bpermute_b32 v69, v159, v62
	v_pk_fma_f32 v[78:79], v[2:3], v[84:85], v[70:71] op_sel_hi:[1,0,1]
	v_pk_fma_f32 v[76:77], v[0:1], v[84:85], v[76:77] op_sel_hi:[1,0,1]
	v_lshl_add_u64 v[70:71], v[150:151], 0, v[122:123]
	global_store_dwordx4 v[70:71], v[76:79], off nt
	s_and_saveexec_b64 s[18:19], s[10:11]
	s_cbranch_execz .LBB0_565
	s_waitcnt lgkmcnt(2)
	v_add_f32_e32 v45, v45, v63
	v_add_f32_e32 v44, v44, v47
	v_mul_f32_e32 v44, v190, v44
	v_mul_f32_e32 v45, v189, v45
	v_fmac_f32_e32 v44, v191, v54
	v_fmac_f32_e32 v45, v195, v54
	v_fmac_f32_e32 v44, 0, v55
	v_fmac_f32_e32 v45, v194, v55
	v_fmac_f32_e32 v44, 0, v60
	v_fmac_f32_e32 v45, 0, v60
	v_fmac_f32_e32 v44, 0, v61
	v_fmac_f32_e32 v45, 0, v61
	s_waitcnt lgkmcnt(0)
	v_add_f32_e32 v62, v62, v69
	v_add_f32_e32 v46, v46, v68
	v_mul_f32_e32 v44, v196, v44
	v_mul_f32_e32 v45, v197, v45
	ds_write2st64_b32 v90, v44, v45 offset0:34 offset1:38
	v_mul_f32_e32 v44, v188, v46
	v_mul_f32_e32 v45, v144, v62
	v_fmac_f32_e32 v44, v200, v54
	v_fmac_f32_e32 v45, v201, v54
	v_fmac_f32_e32 v44, v199, v55
	v_fmac_f32_e32 v45, v205, v55
	v_fmac_f32_e32 v44, v198, v60
	v_fmac_f32_e32 v45, v204, v60
	v_fmac_f32_e32 v44, 0, v61
	v_fmac_f32_e32 v45, v203, v61
	v_mul_f32_e32 v44, v202, v44
	v_mul_f32_e32 v45, v206, v45
	ds_write2st64_b32 v90, v44, v45 offset0:42 offset1:46
.LBB0_565:
	s_or_b64 exec, exec, s[18:19]
	ds_read2st64_b32 v[44:45], v169 offset0:18 offset1:22
	s_waitcnt vmcnt(15)
	v_mul_f32_e32 v46, v81, v33
	s_waitcnt lgkmcnt(4)
	v_mul_f32_e32 v47, v83, v35
	v_fmac_f32_e32 v46, v80, v32
	v_fmac_f32_e32 v47, v82, v34
	v_add_f32_e32 v61, v46, v47
	s_waitcnt lgkmcnt(0)
	v_mul_f32_e32 v46, v146, v44
	v_pk_mul_f32 v[54:55], v[30:31], v[46:47] op_sel_hi:[1,0]
	v_pk_mul_f32 v[46:47], v[28:29], v[46:47] op_sel_hi:[1,0]
	v_pk_fma_f32 v[52:53], v[52:53], v[82:83], v[54:55]
	v_mul_f32_e32 v54, v81, v25
	v_mul_f32_e32 v55, v83, v27
	v_fmac_f32_e32 v54, v80, v24
	v_fmac_f32_e32 v55, v82, v26
	v_pk_fma_f32 v[46:47], v[144:145], v[80:81], v[46:47]
	v_add_f32_e32 v62, v54, v55
	v_mul_f32_e32 v54, v147, v45
	v_pk_fma_f32 v[52:53], v[22:23], v[54:55], v[52:53] op_sel_hi:[1,0,1]
	v_pk_fma_f32 v[54:55], v[20:21], v[54:55], v[46:47] op_sel_hi:[1,0,1]
	v_mul_f32_e32 v46, v81, v17
	v_mul_f32_e32 v47, v83, v19
	v_mul_f32_e32 v60, v81, v13
	v_mul_f32_e32 v68, v83, v15
	v_fmac_f32_e32 v46, v80, v16
	v_fmac_f32_e32 v47, v82, v18
	v_fmac_f32_e32 v60, v80, v12
	v_fmac_f32_e32 v68, v82, v14
	v_add_f32_e32 v63, v46, v47
	v_add_f32_e32 v68, v60, v68
	ds_bpermute_b32 v69, v105, v61
	ds_bpermute_b32 v70, v105, v62
	ds_bpermute_b32 v71, v105, v63
	ds_bpermute_b32 v76, v105, v68
	ds_read2st64_b32 v[46:47], v169 offset0:26 offset1:30
	s_waitcnt lgkmcnt(4)
	v_add_f32_e32 v61, v61, v69
	s_waitcnt lgkmcnt(3)
	v_add_f32_e32 v62, v62, v70
	s_waitcnt lgkmcnt(2)
	v_add_f32_e32 v63, v63, v71
	s_waitcnt lgkmcnt(1)
	v_add_f32_e32 v70, v68, v76
	ds_bpermute_b32 v71, v156, v61
	ds_bpermute_b32 v76, v156, v62
	ds_bpermute_b32 v77, v156, v63
	ds_bpermute_b32 v78, v156, v70
	s_waitcnt lgkmcnt(4)
	v_mul_f32_e32 v60, v148, v46
	v_pk_fma_f32 v[68:69], v[4:5], v[60:61], v[54:55] op_sel_hi:[1,0,1]
	s_waitcnt lgkmcnt(3)
	v_add_f32_e32 v54, v61, v71
	s_waitcnt lgkmcnt(2)
	v_add_f32_e32 v55, v62, v76
	s_waitcnt lgkmcnt(1)
	v_add_f32_e32 v61, v63, v77
	s_waitcnt lgkmcnt(0)
	v_add_f32_e32 v62, v70, v78
	ds_bpermute_b32 v63, v157, v54
	ds_bpermute_b32 v76, v157, v55
	ds_bpermute_b32 v77, v157, v61
	ds_bpermute_b32 v78, v157, v62
	v_pk_fma_f32 v[70:71], v[6:7], v[60:61], v[52:53] op_sel_hi:[1,0,1]
	s_waitcnt lgkmcnt(3)
	v_add_f32_e32 v52, v54, v63
	s_waitcnt lgkmcnt(2)
	v_add_f32_e32 v53, v55, v76
	s_waitcnt lgkmcnt(1)
	v_add_f32_e32 v54, v61, v77
	s_waitcnt lgkmcnt(0)
	v_add_f32_e32 v55, v62, v78
	ds_bpermute_b32 v60, v158, v52
	ds_bpermute_b32 v61, v158, v53
	ds_bpermute_b32 v62, v158, v54
	ds_bpermute_b32 v63, v158, v55
	v_mul_f32_e32 v76, v149, v47
	s_waitcnt lgkmcnt(3)
	v_add_f32_e32 v52, v52, v60
	s_waitcnt lgkmcnt(2)
	v_add_f32_e32 v53, v53, v61
	s_waitcnt lgkmcnt(1)
	v_add_f32_e32 v54, v54, v62
	s_waitcnt lgkmcnt(0)
	v_add_f32_e32 v60, v55, v63
	ds_bpermute_b32 v55, v159, v52
	ds_bpermute_b32 v61, v159, v53
	ds_bpermute_b32 v62, v159, v54
	ds_bpermute_b32 v63, v159, v60
	v_pk_fma_f32 v[70:71], v[2:3], v[76:77], v[70:71] op_sel_hi:[1,0,1]
	v_pk_fma_f32 v[68:69], v[0:1], v[76:77], v[68:69] op_sel_hi:[1,0,1]
	v_lshl_add_u64 v[76:77], v[150:151], 0, v[126:127]
	global_store_dwordx4 v[76:77], v[68:71], off nt
	s_and_saveexec_b64 s[18:19], s[10:11]
	s_cbranch_execz .LBB0_567
	s_waitcnt lgkmcnt(2)
	v_add_f32_e32 v53, v53, v61
	v_add_f32_e32 v52, v52, v55
	v_mul_f32_e32 v52, v190, v52
	v_mul_f32_e32 v53, v189, v53
	v_fmac_f32_e32 v52, v191, v44
	v_fmac_f32_e32 v53, v195, v44
	v_fmac_f32_e32 v52, 0, v45
	v_fmac_f32_e32 v53, v194, v45
	v_fmac_f32_e32 v52, 0, v46
	v_fmac_f32_e32 v53, 0, v46
	v_fmac_f32_e32 v52, 0, v47
	v_fmac_f32_e32 v53, 0, v47
	s_waitcnt lgkmcnt(0)
	v_add_f32_e32 v60, v60, v63
	v_add_f32_e32 v54, v54, v62
	v_mul_f32_e32 v52, v196, v52
	v_mul_f32_e32 v53, v197, v53
	ds_write2st64_b32 v207, v52, v53 offset0:34 offset1:38
	v_mul_f32_e32 v52, v188, v54
	v_mul_f32_e32 v53, v144, v60
	v_fmac_f32_e32 v52, v200, v44
	v_fmac_f32_e32 v53, v201, v44
	v_fmac_f32_e32 v52, v199, v45
	v_fmac_f32_e32 v53, v205, v45
	v_fmac_f32_e32 v52, v198, v46
	v_fmac_f32_e32 v53, v204, v46
	v_fmac_f32_e32 v52, 0, v47
	v_fmac_f32_e32 v53, v203, v47
	v_mul_f32_e32 v52, v202, v52
	v_mul_f32_e32 v44, v206, v53
	ds_write2st64_b32 v207, v52, v44 offset0:42 offset1:46
.LBB0_567:
	s_or_b64 exec, exec, s[18:19]
	ds_read2st64_b32 v[46:47], v155 offset0:18 offset1:22
	s_waitcnt vmcnt(15)
	v_mul_f32_e32 v44, v73, v33
	v_mul_f32_e32 v45, v75, v35
	v_fmac_f32_e32 v44, v72, v32
	v_fmac_f32_e32 v45, v74, v34
	s_waitcnt lgkmcnt(3)
	v_add_f32_e32 v61, v44, v45
	s_waitcnt lgkmcnt(0)
	v_mul_f32_e32 v44, v146, v46
	v_mul_f32_e32 v60, v73, v25
	v_mul_f32_e32 v62, v75, v27
	v_pk_mul_f32 v[52:53], v[30:31], v[44:45] op_sel_hi:[1,0]
	v_pk_mul_f32 v[54:55], v[28:29], v[44:45] op_sel_hi:[1,0]
	v_mov_b32_e32 v44, v144
	v_mov_b32_e32 v45, v144
	v_fmac_f32_e32 v60, v72, v24
	v_fmac_f32_e32 v62, v74, v26
	v_pk_fma_f32 v[52:53], v[44:45], v[74:75], v[52:53]
	v_pk_fma_f32 v[54:55], v[144:145], v[72:73], v[54:55]
	v_add_f32_e32 v68, v60, v62
	v_mul_f32_e32 v60, v147, v47
	v_pk_fma_f32 v[62:63], v[22:23], v[60:61], v[52:53] op_sel_hi:[1,0,1]
	v_pk_fma_f32 v[54:55], v[20:21], v[60:61], v[54:55] op_sel_hi:[1,0,1]
	v_mul_f32_e32 v52, v73, v17
	v_mul_f32_e32 v53, v75, v19
	v_mul_f32_e32 v60, v73, v13
	v_mul_f32_e32 v70, v75, v15
	v_fmac_f32_e32 v52, v72, v16
	v_fmac_f32_e32 v53, v74, v18
	v_fmac_f32_e32 v60, v72, v12
	v_fmac_f32_e32 v70, v74, v14
	v_add_f32_e32 v69, v52, v53
	v_add_f32_e32 v70, v60, v70
	ds_bpermute_b32 v71, v105, v61
	ds_bpermute_b32 v72, v105, v68
	ds_bpermute_b32 v73, v105, v69
	ds_bpermute_b32 v74, v105, v70
	ds_read2st64_b32 v[52:53], v155 offset0:26 offset1:30
	s_waitcnt lgkmcnt(4)
	v_add_f32_e32 v61, v61, v71
	s_waitcnt lgkmcnt(3)
	v_add_f32_e32 v68, v68, v72
	s_waitcnt lgkmcnt(2)
	v_add_f32_e32 v69, v69, v73
	s_waitcnt lgkmcnt(1)
	v_add_f32_e32 v72, v70, v74
	ds_bpermute_b32 v73, v156, v61
	ds_bpermute_b32 v74, v156, v68
	ds_bpermute_b32 v75, v156, v69
	ds_bpermute_b32 v76, v156, v72
	s_waitcnt lgkmcnt(4)
	v_mul_f32_e32 v60, v148, v52
	v_pk_fma_f32 v[70:71], v[4:5], v[60:61], v[54:55] op_sel_hi:[1,0,1]
	s_waitcnt lgkmcnt(3)
	v_add_f32_e32 v54, v61, v73
	s_waitcnt lgkmcnt(2)
	v_add_f32_e32 v55, v68, v74
	s_waitcnt lgkmcnt(1)
	v_add_f32_e32 v61, v69, v75
	s_waitcnt lgkmcnt(0)
	v_add_f32_e32 v68, v72, v76
	ds_bpermute_b32 v69, v157, v54
	ds_bpermute_b32 v74, v157, v55
	ds_bpermute_b32 v75, v157, v61
	ds_bpermute_b32 v76, v157, v68
	v_pk_fma_f32 v[72:73], v[6:7], v[60:61], v[62:63] op_sel_hi:[1,0,1]
	s_waitcnt lgkmcnt(3)
	v_add_f32_e32 v54, v54, v69
	s_waitcnt lgkmcnt(2)
	v_add_f32_e32 v55, v55, v74
	s_waitcnt lgkmcnt(1)
	v_add_f32_e32 v60, v61, v75
	s_waitcnt lgkmcnt(0)
	v_add_f32_e32 v61, v68, v76
	ds_bpermute_b32 v62, v158, v54
	ds_bpermute_b32 v63, v158, v55
	ds_bpermute_b32 v68, v158, v60
	ds_bpermute_b32 v69, v158, v61
	v_mul_f32_e32 v74, v149, v53
	s_waitcnt lgkmcnt(3)
	v_add_f32_e32 v54, v54, v62
	s_waitcnt lgkmcnt(2)
	v_add_f32_e32 v55, v55, v63
	s_waitcnt lgkmcnt(1)
	v_add_f32_e32 v60, v60, v68
	s_waitcnt lgkmcnt(0)
	v_add_f32_e32 v62, v61, v69
	ds_bpermute_b32 v61, v159, v54
	ds_bpermute_b32 v63, v159, v55
	ds_bpermute_b32 v68, v159, v60
	ds_bpermute_b32 v69, v159, v62
	v_pk_fma_f32 v[72:73], v[2:3], v[74:75], v[72:73] op_sel_hi:[1,0,1]
	v_pk_fma_f32 v[70:71], v[0:1], v[74:75], v[70:71] op_sel_hi:[1,0,1]
	v_lshl_add_u64 v[74:75], v[150:151], 0, v[128:129]
	global_store_dwordx4 v[74:75], v[70:73], off nt
	s_and_saveexec_b64 s[18:19], s[10:11]
	s_cbranch_execz .LBB0_569
	s_waitcnt lgkmcnt(2)
	v_add_f32_e32 v55, v55, v63
	v_add_f32_e32 v54, v54, v61
	v_mul_f32_e32 v54, v190, v54
	v_mul_f32_e32 v55, v189, v55
	v_fmac_f32_e32 v54, v191, v46
	v_fmac_f32_e32 v55, v195, v46
	v_fmac_f32_e32 v54, 0, v47
	v_fmac_f32_e32 v55, v194, v47
	v_fmac_f32_e32 v54, 0, v52
	v_fmac_f32_e32 v55, 0, v52
	v_fmac_f32_e32 v54, 0, v53
	v_fmac_f32_e32 v55, 0, v53
	s_waitcnt lgkmcnt(0)
	v_add_f32_e32 v62, v62, v69
	v_add_f32_e32 v60, v60, v68
	v_mul_f32_e32 v54, v196, v54
	v_mul_f32_e32 v55, v197, v55
	ds_write2st64_b32 v154, v54, v55 offset0:34 offset1:38
	v_mul_f32_e32 v54, v188, v60
	v_mul_f32_e32 v55, v144, v62
	v_fmac_f32_e32 v54, v200, v46
	v_fmac_f32_e32 v55, v201, v46
	v_fmac_f32_e32 v54, v199, v47
	v_fmac_f32_e32 v55, v205, v47
	v_fmac_f32_e32 v54, v198, v52
	v_fmac_f32_e32 v55, v204, v52
	v_fmac_f32_e32 v54, 0, v53
	v_fmac_f32_e32 v55, v203, v53
	v_mul_f32_e32 v54, v202, v54
	v_mul_f32_e32 v46, v206, v55
	ds_write2st64_b32 v154, v54, v46 offset0:42 offset1:46
.LBB0_569:
	s_or_b64 exec, exec, s[18:19]
	ds_read2st64_b32 v[46:47], v94 offset0:18 offset1:22
	s_waitcnt vmcnt(15)
	v_mul_f32_e32 v52, v65, v33
	v_mul_f32_e32 v53, v67, v35
	v_fmac_f32_e32 v52, v64, v32
	v_fmac_f32_e32 v53, v66, v34
	v_add_f32_e32 v62, v52, v53
	s_waitcnt lgkmcnt(0)
	v_mul_f32_e32 v52, v146, v46
	v_pk_mul_f32 v[54:55], v[30:31], v[52:53] op_sel_hi:[1,0]
	v_pk_mul_f32 v[52:53], v[28:29], v[52:53] op_sel_hi:[1,0]
	v_pk_fma_f32 v[44:45], v[44:45], v[66:67], v[54:55]
	v_mul_f32_e32 v54, v65, v25
	v_mul_f32_e32 v55, v67, v27
	v_fmac_f32_e32 v54, v64, v24
	v_fmac_f32_e32 v55, v66, v26
	v_pk_fma_f32 v[52:53], v[144:145], v[64:65], v[52:53]
	v_add_f32_e32 v55, v54, v55
	v_mul_f32_e32 v54, v147, v47
	v_pk_fma_f32 v[60:61], v[22:23], v[54:55], v[44:45] op_sel_hi:[1,0,1]
	v_pk_fma_f32 v[52:53], v[20:21], v[54:55], v[52:53] op_sel_hi:[1,0,1]
	v_mul_f32_e32 v44, v65, v17
	v_mul_f32_e32 v54, v65, v13
	v_fmac_f32_e32 v44, v64, v16
	v_mul_f32_e32 v45, v67, v19
	v_fmac_f32_e32 v54, v64, v12
	v_mul_f32_e32 v64, v67, v15
	v_fmac_f32_e32 v45, v66, v18
	v_fmac_f32_e32 v64, v66, v14
	v_add_f32_e32 v63, v44, v45
	v_add_f32_e32 v64, v54, v64
	ds_bpermute_b32 v65, v105, v62
	ds_bpermute_b32 v66, v105, v55
	ds_bpermute_b32 v67, v105, v63
	ds_bpermute_b32 v68, v105, v64
	ds_read2st64_b32 v[44:45], v94 offset0:26 offset1:30
	s_waitcnt lgkmcnt(4)
	v_add_f32_e32 v62, v62, v65
	s_waitcnt lgkmcnt(3)
	v_add_f32_e32 v55, v55, v66
	s_waitcnt lgkmcnt(2)
	v_add_f32_e32 v63, v63, v67
	s_waitcnt lgkmcnt(1)
	v_add_f32_e32 v66, v64, v68
	ds_bpermute_b32 v67, v156, v62
	ds_bpermute_b32 v68, v156, v55
	ds_bpermute_b32 v69, v156, v63
	ds_bpermute_b32 v70, v156, v66
	s_waitcnt lgkmcnt(4)
	v_mul_f32_e32 v54, v148, v44
	v_pk_fma_f32 v[64:65], v[4:5], v[54:55], v[52:53] op_sel_hi:[1,0,1]
	s_waitcnt lgkmcnt(3)
	v_add_f32_e32 v52, v62, v67
	s_waitcnt lgkmcnt(2)
	v_add_f32_e32 v53, v55, v68
	s_waitcnt lgkmcnt(1)
	v_add_f32_e32 v55, v63, v69
	s_waitcnt lgkmcnt(0)
	v_add_f32_e32 v62, v66, v70
	ds_bpermute_b32 v63, v157, v52
	ds_bpermute_b32 v68, v157, v53
	ds_bpermute_b32 v69, v157, v55
	ds_bpermute_b32 v70, v157, v62
	v_pk_fma_f32 v[66:67], v[6:7], v[54:55], v[60:61] op_sel_hi:[1,0,1]
	s_waitcnt lgkmcnt(3)
	v_add_f32_e32 v52, v52, v63
	s_waitcnt lgkmcnt(2)
	v_add_f32_e32 v53, v53, v68
	s_waitcnt lgkmcnt(1)
	v_add_f32_e32 v54, v55, v69
	s_waitcnt lgkmcnt(0)
	v_add_f32_e32 v55, v62, v70
	ds_bpermute_b32 v60, v158, v52
	ds_bpermute_b32 v61, v158, v53
	ds_bpermute_b32 v62, v158, v54
	ds_bpermute_b32 v63, v158, v55
	v_mul_f32_e32 v68, v149, v45
	s_waitcnt lgkmcnt(3)
	v_add_f32_e32 v52, v52, v60
	s_waitcnt lgkmcnt(2)
	v_add_f32_e32 v53, v53, v61
	s_waitcnt lgkmcnt(1)
	v_add_f32_e32 v54, v54, v62
	s_waitcnt lgkmcnt(0)
	v_add_f32_e32 v60, v55, v63
	ds_bpermute_b32 v55, v159, v52
	ds_bpermute_b32 v61, v159, v53
	ds_bpermute_b32 v62, v159, v54
	ds_bpermute_b32 v63, v159, v60
	v_pk_fma_f32 v[66:67], v[2:3], v[68:69], v[66:67] op_sel_hi:[1,0,1]
	v_pk_fma_f32 v[64:65], v[0:1], v[68:69], v[64:65] op_sel_hi:[1,0,1]
	v_lshl_add_u64 v[68:69], v[150:151], 0, v[130:131]
	global_store_dwordx4 v[68:69], v[64:67], off nt
	s_and_saveexec_b64 s[18:19], s[10:11]
	s_cbranch_execz .LBB0_571
	s_waitcnt lgkmcnt(2)
	v_add_f32_e32 v53, v53, v61
	v_add_f32_e32 v52, v52, v55
	v_mul_f32_e32 v52, v190, v52
	v_mul_f32_e32 v53, v189, v53
	v_fmac_f32_e32 v52, v191, v46
	v_fmac_f32_e32 v53, v195, v46
	v_fmac_f32_e32 v52, 0, v47
	v_fmac_f32_e32 v53, v194, v47
	v_fmac_f32_e32 v52, 0, v44
	v_fmac_f32_e32 v53, 0, v44
	v_fmac_f32_e32 v52, 0, v45
	v_fmac_f32_e32 v53, 0, v45
	s_waitcnt lgkmcnt(0)
	v_add_f32_e32 v60, v60, v63
	v_add_f32_e32 v54, v54, v62
	v_mul_f32_e32 v52, v196, v52
	v_mul_f32_e32 v53, v197, v53
	ds_write2st64_b32 v92, v52, v53 offset0:34 offset1:38
	v_mul_f32_e32 v52, v188, v54
	v_mul_f32_e32 v53, v144, v60
	v_fmac_f32_e32 v52, v200, v46
	v_fmac_f32_e32 v53, v201, v46
	v_fmac_f32_e32 v52, v199, v47
	v_fmac_f32_e32 v53, v205, v47
	v_fmac_f32_e32 v52, v198, v44
	v_fmac_f32_e32 v53, v204, v44
	v_fmac_f32_e32 v52, 0, v45
	v_fmac_f32_e32 v53, v203, v45
	v_mul_f32_e32 v52, v202, v52
	v_mul_f32_e32 v44, v206, v53
	ds_write2st64_b32 v92, v52, v44 offset0:42 offset1:46
.LBB0_571:
	s_or_b64 exec, exec, s[18:19]
	ds_read2st64_b32 v[46:47], v91 offset0:18 offset1:22
	s_waitcnt vmcnt(15)
	v_mul_f32_e32 v44, v57, v33
	v_mul_f32_e32 v45, v59, v35
	v_fmac_f32_e32 v44, v56, v32
	v_fmac_f32_e32 v45, v58, v34
	s_waitcnt lgkmcnt(3)
	v_add_f32_e32 v61, v44, v45
	s_waitcnt lgkmcnt(0)
	v_mul_f32_e32 v44, v146, v46
	v_mul_f32_e32 v60, v57, v25
	v_mul_f32_e32 v62, v59, v27
	v_pk_mul_f32 v[52:53], v[30:31], v[44:45] op_sel_hi:[1,0]
	v_pk_mul_f32 v[54:55], v[28:29], v[44:45] op_sel_hi:[1,0]
	v_mov_b32_e32 v44, v144
	v_mov_b32_e32 v45, v144
	v_fmac_f32_e32 v60, v56, v24
	v_fmac_f32_e32 v62, v58, v26
	v_pk_fma_f32 v[52:53], v[44:45], v[58:59], v[52:53]
	v_add_f32_e32 v64, v60, v62
	v_mul_f32_e32 v60, v147, v47
	v_pk_fma_f32 v[54:55], v[144:145], v[56:57], v[54:55]
	v_pk_fma_f32 v[62:63], v[22:23], v[60:61], v[52:53] op_sel_hi:[1,0,1]
	v_mul_f32_e32 v52, v57, v17
	v_mul_f32_e32 v57, v57, v13
	v_fmac_f32_e32 v52, v56, v16
	v_mul_f32_e32 v53, v59, v19
	v_fmac_f32_e32 v57, v56, v12
	v_mul_f32_e32 v56, v59, v15
	v_fmac_f32_e32 v53, v58, v18
	v_fmac_f32_e32 v56, v58, v14
	v_pk_fma_f32 v[54:55], v[20:21], v[60:61], v[54:55] op_sel_hi:[1,0,1]
	v_add_f32_e32 v60, v52, v53
	v_add_f32_e32 v57, v57, v56
	ds_bpermute_b32 v58, v105, v61
	ds_bpermute_b32 v59, v105, v64
	ds_bpermute_b32 v65, v105, v60
	ds_bpermute_b32 v66, v105, v57
	ds_read2st64_b32 v[52:53], v91 offset0:26 offset1:30
	s_waitcnt lgkmcnt(4)
	v_add_f32_e32 v58, v61, v58
	s_waitcnt lgkmcnt(3)
	v_add_f32_e32 v59, v64, v59
	s_waitcnt lgkmcnt(2)
	v_add_f32_e32 v60, v60, v65
	s_waitcnt lgkmcnt(1)
	v_add_f32_e32 v57, v57, v66
	ds_bpermute_b32 v61, v156, v58
	ds_bpermute_b32 v64, v156, v59
	ds_bpermute_b32 v65, v156, v60
	ds_bpermute_b32 v68, v156, v57
	s_waitcnt lgkmcnt(4)
	v_mul_f32_e32 v56, v148, v52
	v_pk_fma_f32 v[66:67], v[4:5], v[56:57], v[54:55] op_sel_hi:[1,0,1]
	s_waitcnt lgkmcnt(3)
	v_add_f32_e32 v54, v58, v61
	s_waitcnt lgkmcnt(2)
	v_add_f32_e32 v55, v59, v64
	s_waitcnt lgkmcnt(1)
	v_add_f32_e32 v58, v60, v65
	s_waitcnt lgkmcnt(0)
	v_add_f32_e32 v57, v57, v68
	ds_bpermute_b32 v59, v157, v54
	ds_bpermute_b32 v60, v157, v55
	ds_bpermute_b32 v61, v157, v58
	ds_bpermute_b32 v64, v157, v57
	v_pk_fma_f32 v[62:63], v[6:7], v[56:57], v[62:63] op_sel_hi:[1,0,1]
	s_waitcnt lgkmcnt(3)
	v_add_f32_e32 v54, v54, v59
	s_waitcnt lgkmcnt(2)
	v_add_f32_e32 v55, v55, v60
	s_waitcnt lgkmcnt(1)
	v_add_f32_e32 v56, v58, v61
	s_waitcnt lgkmcnt(0)
	v_add_f32_e32 v57, v57, v64
	ds_bpermute_b32 v58, v158, v54
	ds_bpermute_b32 v59, v158, v55
	ds_bpermute_b32 v60, v158, v56
	ds_bpermute_b32 v61, v158, v57
	v_mul_f32_e32 v68, v149, v53
	s_waitcnt lgkmcnt(3)
	v_add_f32_e32 v54, v54, v58
	s_waitcnt lgkmcnt(2)
	v_add_f32_e32 v55, v55, v59
	s_waitcnt lgkmcnt(1)
	v_add_f32_e32 v56, v56, v60
	s_waitcnt lgkmcnt(0)
	v_add_f32_e32 v58, v57, v61
	ds_bpermute_b32 v57, v159, v54
	ds_bpermute_b32 v59, v159, v55
	ds_bpermute_b32 v60, v159, v56
	ds_bpermute_b32 v61, v159, v58
	v_pk_fma_f32 v[64:65], v[2:3], v[68:69], v[62:63] op_sel_hi:[1,0,1]
	v_pk_fma_f32 v[62:63], v[0:1], v[68:69], v[66:67] op_sel_hi:[1,0,1]
	v_lshl_add_u64 v[66:67], v[150:151], 0, v[132:133]
	global_store_dwordx4 v[66:67], v[62:65], off nt
	s_and_saveexec_b64 s[18:19], s[10:11]
	s_cbranch_execz .LBB0_573
	s_waitcnt lgkmcnt(2)
	v_add_f32_e32 v55, v55, v59
	v_add_f32_e32 v54, v54, v57
	v_mul_f32_e32 v54, v190, v54
	v_mul_f32_e32 v55, v189, v55
	v_fmac_f32_e32 v54, v191, v46
	v_fmac_f32_e32 v55, v195, v46
	v_fmac_f32_e32 v54, 0, v47
	v_fmac_f32_e32 v55, v194, v47
	v_fmac_f32_e32 v54, 0, v52
	v_fmac_f32_e32 v55, 0, v52
	v_fmac_f32_e32 v54, 0, v53
	v_fmac_f32_e32 v55, 0, v53
	s_waitcnt lgkmcnt(0)
	v_add_f32_e32 v58, v58, v61
	v_add_f32_e32 v56, v56, v60
	v_mul_f32_e32 v54, v196, v54
	v_mul_f32_e32 v55, v197, v55
	ds_write2st64_b32 v90, v54, v55 offset0:35 offset1:39
	v_mul_f32_e32 v54, v188, v56
	v_mul_f32_e32 v55, v144, v58
	v_fmac_f32_e32 v54, v200, v46
	v_fmac_f32_e32 v55, v201, v46
	v_fmac_f32_e32 v54, v199, v47
	v_fmac_f32_e32 v55, v205, v47
	v_fmac_f32_e32 v54, v198, v52
	v_fmac_f32_e32 v55, v204, v52
	v_fmac_f32_e32 v54, 0, v53
	v_fmac_f32_e32 v55, v203, v53
	v_mul_f32_e32 v54, v202, v54
	v_mul_f32_e32 v46, v206, v55
	ds_write2st64_b32 v90, v54, v46 offset0:43 offset1:47
.LBB0_573:
	s_or_b64 exec, exec, s[18:19]
	ds_read2st64_b32 v[46:47], v169 offset0:19 offset1:23
	s_waitcnt vmcnt(15)
	v_mul_f32_e32 v52, v49, v33
	v_mul_f32_e32 v53, v51, v35
	v_fmac_f32_e32 v52, v48, v32
	v_fmac_f32_e32 v53, v50, v34
	v_add_f32_e32 v58, v52, v53
	s_waitcnt lgkmcnt(0)
	v_mul_f32_e32 v52, v146, v46
	v_pk_mul_f32 v[54:55], v[30:31], v[52:53] op_sel_hi:[1,0]
	v_pk_mul_f32 v[52:53], v[28:29], v[52:53] op_sel_hi:[1,0]
	v_pk_fma_f32 v[44:45], v[44:45], v[50:51], v[54:55]
	v_mul_f32_e32 v54, v49, v25
	v_mul_f32_e32 v55, v51, v27
	v_fmac_f32_e32 v54, v48, v24
	v_fmac_f32_e32 v55, v50, v26
	v_add_f32_e32 v55, v54, v55
	v_mul_f32_e32 v54, v147, v47
	v_pk_fma_f32 v[52:53], v[144:145], v[48:49], v[52:53]
	v_pk_fma_f32 v[56:57], v[22:23], v[54:55], v[44:45] op_sel_hi:[1,0,1]
	v_mul_f32_e32 v44, v49, v17
	v_mul_f32_e32 v49, v49, v13
	v_fmac_f32_e32 v44, v48, v16
	v_mul_f32_e32 v45, v51, v19
	v_fmac_f32_e32 v49, v48, v12
	v_mul_f32_e32 v48, v51, v15
	v_fmac_f32_e32 v45, v50, v18
	v_fmac_f32_e32 v48, v50, v14
	v_pk_fma_f32 v[52:53], v[20:21], v[54:55], v[52:53] op_sel_hi:[1,0,1]
	v_add_f32_e32 v54, v44, v45
	v_add_f32_e32 v49, v49, v48
	ds_bpermute_b32 v50, v105, v58
	ds_bpermute_b32 v51, v105, v55
	ds_bpermute_b32 v59, v105, v54
	ds_bpermute_b32 v60, v105, v49
	ds_read2st64_b32 v[44:45], v169 offset0:27 offset1:31
	s_waitcnt lgkmcnt(4)
	v_add_f32_e32 v50, v58, v50
	s_waitcnt lgkmcnt(3)
	v_add_f32_e32 v51, v55, v51
	s_waitcnt lgkmcnt(2)
	v_add_f32_e32 v54, v54, v59
	s_waitcnt lgkmcnt(1)
	v_add_f32_e32 v49, v49, v60
	ds_bpermute_b32 v55, v156, v50
	ds_bpermute_b32 v58, v156, v51
	ds_bpermute_b32 v59, v156, v54
	ds_bpermute_b32 v62, v156, v49
	s_waitcnt lgkmcnt(4)
	v_mul_f32_e32 v48, v148, v44
	v_pk_fma_f32 v[60:61], v[4:5], v[48:49], v[52:53] op_sel_hi:[1,0,1]
	s_waitcnt lgkmcnt(3)
	v_add_f32_e32 v50, v50, v55
	s_waitcnt lgkmcnt(2)
	v_add_f32_e32 v51, v51, v58
	s_waitcnt lgkmcnt(1)
	v_add_f32_e32 v52, v54, v59
	s_waitcnt lgkmcnt(0)
	v_add_f32_e32 v49, v49, v62
	ds_bpermute_b32 v53, v157, v50
	ds_bpermute_b32 v54, v157, v51
	ds_bpermute_b32 v55, v157, v52
	ds_bpermute_b32 v58, v157, v49
	v_pk_fma_f32 v[56:57], v[6:7], v[48:49], v[56:57] op_sel_hi:[1,0,1]
	s_waitcnt lgkmcnt(3)
	v_add_f32_e32 v48, v50, v53
	s_waitcnt lgkmcnt(2)
	v_add_f32_e32 v50, v51, v54
	s_waitcnt lgkmcnt(1)
	v_add_f32_e32 v51, v52, v55
	s_waitcnt lgkmcnt(0)
	v_add_f32_e32 v52, v49, v58
	ds_bpermute_b32 v49, v158, v48
	ds_bpermute_b32 v53, v158, v50
	ds_bpermute_b32 v54, v158, v51
	ds_bpermute_b32 v55, v158, v52
	v_mul_f32_e32 v62, v149, v45
	s_waitcnt lgkmcnt(3)
	v_add_f32_e32 v48, v48, v49
	s_waitcnt lgkmcnt(2)
	v_add_f32_e32 v49, v50, v53
	s_waitcnt lgkmcnt(1)
	v_add_f32_e32 v50, v51, v54
	s_waitcnt lgkmcnt(0)
	v_add_f32_e32 v52, v52, v55
	ds_bpermute_b32 v51, v159, v48
	ds_bpermute_b32 v53, v159, v49
	ds_bpermute_b32 v54, v159, v50
	ds_bpermute_b32 v55, v159, v52
	v_pk_fma_f32 v[58:59], v[2:3], v[62:63], v[56:57] op_sel_hi:[1,0,1]
	v_pk_fma_f32 v[56:57], v[0:1], v[62:63], v[60:61] op_sel_hi:[1,0,1]
	v_lshl_add_u64 v[60:61], v[150:151], 0, v[134:135]
	global_store_dwordx4 v[60:61], v[56:59], off nt
	s_and_saveexec_b64 s[18:19], s[10:11]
	s_cbranch_execz .LBB0_575
	s_waitcnt lgkmcnt(2)
	v_add_f32_e32 v49, v49, v53
	v_add_f32_e32 v48, v48, v51
	v_mul_f32_e32 v48, v190, v48
	v_mul_f32_e32 v49, v189, v49
	v_fmac_f32_e32 v48, v191, v46
	v_fmac_f32_e32 v49, v195, v46
	v_fmac_f32_e32 v48, 0, v47
	v_fmac_f32_e32 v49, v194, v47
	v_fmac_f32_e32 v48, 0, v44
	v_fmac_f32_e32 v49, 0, v44
	v_fmac_f32_e32 v48, 0, v45
	v_fmac_f32_e32 v49, 0, v45
	s_waitcnt lgkmcnt(0)
	v_add_f32_e32 v52, v52, v55
	v_add_f32_e32 v50, v50, v54
	v_mul_f32_e32 v48, v196, v48
	v_mul_f32_e32 v49, v197, v49
	ds_write2st64_b32 v207, v48, v49 offset0:35 offset1:39
	v_mul_f32_e32 v48, v188, v50
	v_mul_f32_e32 v49, v144, v52
	v_fmac_f32_e32 v48, v200, v46
	v_fmac_f32_e32 v49, v201, v46
	v_fmac_f32_e32 v48, v199, v47
	v_fmac_f32_e32 v49, v205, v47
	v_fmac_f32_e32 v48, v198, v44
	v_fmac_f32_e32 v49, v204, v44
	v_fmac_f32_e32 v48, 0, v45
	v_fmac_f32_e32 v49, v203, v45
	v_mul_f32_e32 v48, v202, v48
	v_mul_f32_e32 v44, v206, v49
	ds_write2st64_b32 v207, v48, v44 offset0:43 offset1:47
.LBB0_575:
	s_or_b64 exec, exec, s[18:19]
	ds_read2st64_b32 v[46:47], v155 offset0:19 offset1:23
	s_waitcnt vmcnt(15)
	v_mul_f32_e32 v44, v41, v33
	v_mul_f32_e32 v45, v43, v35
	v_fmac_f32_e32 v44, v40, v32
	v_fmac_f32_e32 v45, v42, v34
	s_waitcnt lgkmcnt(3)
	v_add_f32_e32 v53, v44, v45
	s_waitcnt lgkmcnt(0)
	v_mul_f32_e32 v44, v146, v46
	v_mul_f32_e32 v52, v41, v25
	v_mul_f32_e32 v54, v43, v27
	v_pk_mul_f32 v[48:49], v[30:31], v[44:45] op_sel_hi:[1,0]
	v_pk_mul_f32 v[50:51], v[28:29], v[44:45] op_sel_hi:[1,0]
	v_mov_b32_e32 v44, v144
	v_mov_b32_e32 v45, v144
	v_fmac_f32_e32 v52, v40, v24
	v_fmac_f32_e32 v54, v42, v26
	v_pk_fma_f32 v[48:49], v[44:45], v[42:43], v[48:49]
	v_add_f32_e32 v56, v52, v54
	v_mul_f32_e32 v52, v147, v47
	v_pk_fma_f32 v[50:51], v[144:145], v[40:41], v[50:51]
	v_pk_fma_f32 v[54:55], v[22:23], v[52:53], v[48:49] op_sel_hi:[1,0,1]
	v_mul_f32_e32 v48, v41, v17
	v_mul_f32_e32 v41, v41, v13
	v_fmac_f32_e32 v48, v40, v16
	v_mul_f32_e32 v49, v43, v19
	v_fmac_f32_e32 v41, v40, v12
	v_mul_f32_e32 v40, v43, v15
	v_fmac_f32_e32 v49, v42, v18
	v_fmac_f32_e32 v40, v42, v14
	v_pk_fma_f32 v[50:51], v[20:21], v[52:53], v[50:51] op_sel_hi:[1,0,1]
	v_add_f32_e32 v52, v48, v49
	v_add_f32_e32 v41, v41, v40
	ds_bpermute_b32 v42, v105, v53
	ds_bpermute_b32 v43, v105, v56
	ds_bpermute_b32 v57, v105, v52
	ds_bpermute_b32 v58, v105, v41
	ds_read2st64_b32 v[48:49], v155 offset0:27 offset1:31
	s_waitcnt lgkmcnt(4)
	v_add_f32_e32 v42, v53, v42
	s_waitcnt lgkmcnt(3)
	v_add_f32_e32 v43, v56, v43
	s_waitcnt lgkmcnt(2)
	v_add_f32_e32 v52, v52, v57
	s_waitcnt lgkmcnt(1)
	v_add_f32_e32 v41, v41, v58
	ds_bpermute_b32 v53, v156, v42
	ds_bpermute_b32 v56, v156, v43
	ds_bpermute_b32 v57, v156, v52
	ds_bpermute_b32 v60, v156, v41
	s_waitcnt lgkmcnt(4)
	v_mul_f32_e32 v40, v148, v48
	v_pk_fma_f32 v[58:59], v[4:5], v[40:41], v[50:51] op_sel_hi:[1,0,1]
	s_waitcnt lgkmcnt(3)
	v_add_f32_e32 v42, v42, v53
	s_waitcnt lgkmcnt(2)
	v_add_f32_e32 v43, v43, v56
	s_waitcnt lgkmcnt(1)
	v_add_f32_e32 v50, v52, v57
	s_waitcnt lgkmcnt(0)
	v_add_f32_e32 v41, v41, v60
	ds_bpermute_b32 v51, v157, v42
	ds_bpermute_b32 v52, v157, v43
	ds_bpermute_b32 v53, v157, v50
	ds_bpermute_b32 v56, v157, v41
	v_pk_fma_f32 v[54:55], v[6:7], v[40:41], v[54:55] op_sel_hi:[1,0,1]
	s_waitcnt lgkmcnt(3)
	v_add_f32_e32 v40, v42, v51
	s_waitcnt lgkmcnt(2)
	v_add_f32_e32 v42, v43, v52
	s_waitcnt lgkmcnt(1)
	v_add_f32_e32 v43, v50, v53
	s_waitcnt lgkmcnt(0)
	v_add_f32_e32 v50, v41, v56
	ds_bpermute_b32 v41, v158, v40
	ds_bpermute_b32 v51, v158, v42
	ds_bpermute_b32 v52, v158, v43
	ds_bpermute_b32 v53, v158, v50
	v_mul_f32_e32 v60, v149, v49
	s_waitcnt lgkmcnt(3)
	v_add_f32_e32 v40, v40, v41
	s_waitcnt lgkmcnt(2)
	v_add_f32_e32 v41, v42, v51
	s_waitcnt lgkmcnt(1)
	v_add_f32_e32 v42, v43, v52
	s_waitcnt lgkmcnt(0)
	v_add_f32_e32 v50, v50, v53
	ds_bpermute_b32 v43, v159, v40
	ds_bpermute_b32 v51, v159, v41
	ds_bpermute_b32 v52, v159, v42
	ds_bpermute_b32 v53, v159, v50
	v_pk_fma_f32 v[56:57], v[2:3], v[60:61], v[54:55] op_sel_hi:[1,0,1]
	v_pk_fma_f32 v[54:55], v[0:1], v[60:61], v[58:59] op_sel_hi:[1,0,1]
	v_lshl_add_u64 v[58:59], v[150:151], 0, v[136:137]
	global_store_dwordx4 v[58:59], v[54:57], off nt
	s_and_saveexec_b64 s[18:19], s[10:11]
	s_cbranch_execz .LBB0_577
	s_waitcnt lgkmcnt(2)
	v_add_f32_e32 v41, v41, v51
	v_add_f32_e32 v40, v40, v43
	v_mul_f32_e32 v40, v190, v40
	v_mul_f32_e32 v41, v189, v41
	v_fmac_f32_e32 v40, v191, v46
	v_fmac_f32_e32 v41, v195, v46
	v_fmac_f32_e32 v40, 0, v47
	v_fmac_f32_e32 v41, v194, v47
	v_fmac_f32_e32 v40, 0, v48
	v_fmac_f32_e32 v41, 0, v48
	v_fmac_f32_e32 v40, 0, v49
	v_fmac_f32_e32 v41, 0, v49
	s_waitcnt lgkmcnt(0)
	v_add_f32_e32 v50, v50, v53
	v_add_f32_e32 v42, v42, v52
	v_mul_f32_e32 v40, v196, v40
	v_mul_f32_e32 v41, v197, v41
	ds_write2st64_b32 v154, v40, v41 offset0:35 offset1:39
	v_mul_f32_e32 v40, v188, v42
	v_mul_f32_e32 v41, v144, v50
	v_fmac_f32_e32 v40, v200, v46
	v_fmac_f32_e32 v41, v201, v46
	v_fmac_f32_e32 v40, v199, v47
	v_fmac_f32_e32 v41, v205, v47
	v_fmac_f32_e32 v40, v198, v48
	v_fmac_f32_e32 v41, v204, v48
	v_fmac_f32_e32 v40, 0, v49
	v_fmac_f32_e32 v41, v203, v49
	v_mul_f32_e32 v40, v202, v40
	v_mul_f32_e32 v41, v206, v41
	ds_write2st64_b32 v154, v40, v41 offset0:43 offset1:47
.LBB0_577:
	s_or_b64 exec, exec, s[18:19]
	ds_read2st64_b32 v[40:41], v94 offset0:19 offset1:23
	s_waitcnt vmcnt(15)
	v_mul_f32_e32 v42, v37, v33
	s_waitcnt lgkmcnt(4)
	v_mul_f32_e32 v43, v39, v35
	v_fmac_f32_e32 v42, v36, v32
	v_fmac_f32_e32 v43, v38, v34
	v_add_f32_e32 v48, v42, v43
	s_waitcnt lgkmcnt(0)
	v_mul_f32_e32 v42, v146, v40
	v_pk_mul_f32 v[46:47], v[30:31], v[42:43] op_sel_hi:[1,0]
	v_pk_mul_f32 v[42:43], v[28:29], v[42:43] op_sel_hi:[1,0]
	v_pk_fma_f32 v[44:45], v[44:45], v[38:39], v[46:47]
	v_mul_f32_e32 v46, v37, v25
	v_mul_f32_e32 v47, v39, v27
	v_fmac_f32_e32 v46, v36, v24
	v_fmac_f32_e32 v47, v38, v26
	v_pk_fma_f32 v[42:43], v[144:145], v[36:37], v[42:43]
	v_add_f32_e32 v49, v46, v47
	v_mul_f32_e32 v46, v147, v41
	v_pk_fma_f32 v[44:45], v[22:23], v[46:47], v[44:45] op_sel_hi:[1,0,1]
	v_pk_fma_f32 v[46:47], v[20:21], v[46:47], v[42:43] op_sel_hi:[1,0,1]
	v_mul_f32_e32 v42, v37, v17
	v_mul_f32_e32 v37, v37, v13
	v_fmac_f32_e32 v42, v36, v16
	v_mul_f32_e32 v43, v39, v19
	v_fmac_f32_e32 v37, v36, v12
	v_mul_f32_e32 v36, v39, v15
	v_fmac_f32_e32 v43, v38, v18
	v_fmac_f32_e32 v36, v38, v14
	v_add_f32_e32 v50, v42, v43
	v_add_f32_e32 v37, v37, v36
	ds_bpermute_b32 v38, v105, v48
	ds_bpermute_b32 v39, v105, v49
	ds_bpermute_b32 v51, v105, v50
	ds_bpermute_b32 v52, v105, v37
	ds_read2st64_b32 v[42:43], v94 offset0:27 offset1:31
	s_waitcnt lgkmcnt(4)
	v_add_f32_e32 v38, v48, v38
	s_waitcnt lgkmcnt(3)
	v_add_f32_e32 v39, v49, v39
	s_waitcnt lgkmcnt(2)
	v_add_f32_e32 v50, v50, v51
	s_waitcnt lgkmcnt(1)
	v_add_f32_e32 v37, v37, v52
	ds_bpermute_b32 v51, v156, v38
	ds_bpermute_b32 v52, v156, v39
	ds_bpermute_b32 v53, v156, v50
	ds_bpermute_b32 v54, v156, v37
	s_waitcnt lgkmcnt(4)
	v_mul_f32_e32 v36, v148, v42
	v_pk_fma_f32 v[48:49], v[4:5], v[36:37], v[46:47] op_sel_hi:[1,0,1]
	s_waitcnt lgkmcnt(3)
	v_add_f32_e32 v38, v38, v51
	s_waitcnt lgkmcnt(2)
	v_add_f32_e32 v39, v39, v52
	s_waitcnt lgkmcnt(1)
	v_add_f32_e32 v46, v50, v53
	s_waitcnt lgkmcnt(0)
	v_add_f32_e32 v37, v37, v54
	ds_bpermute_b32 v47, v157, v38
	ds_bpermute_b32 v52, v157, v39
	ds_bpermute_b32 v53, v157, v46
	ds_bpermute_b32 v54, v157, v37
	v_pk_fma_f32 v[50:51], v[6:7], v[36:37], v[44:45] op_sel_hi:[1,0,1]
	s_waitcnt lgkmcnt(3)
	v_add_f32_e32 v36, v38, v47
	s_waitcnt lgkmcnt(2)
	v_add_f32_e32 v38, v39, v52
	s_waitcnt lgkmcnt(1)
	v_add_f32_e32 v39, v46, v53
	s_waitcnt lgkmcnt(0)
	v_add_f32_e32 v44, v37, v54
	ds_bpermute_b32 v37, v158, v36
	ds_bpermute_b32 v45, v158, v38
	ds_bpermute_b32 v46, v158, v39
	ds_bpermute_b32 v47, v158, v44
	v_mul_f32_e32 v52, v149, v43
	s_waitcnt lgkmcnt(3)
	v_add_f32_e32 v36, v36, v37
	s_waitcnt lgkmcnt(2)
	v_add_f32_e32 v37, v38, v45
	s_waitcnt lgkmcnt(1)
	v_add_f32_e32 v38, v39, v46
	s_waitcnt lgkmcnt(0)
	v_add_f32_e32 v44, v44, v47
	ds_bpermute_b32 v39, v159, v36
	ds_bpermute_b32 v45, v159, v37
	ds_bpermute_b32 v46, v159, v38
	ds_bpermute_b32 v47, v159, v44
	v_pk_fma_f32 v[50:51], v[2:3], v[52:53], v[50:51] op_sel_hi:[1,0,1]
	v_pk_fma_f32 v[48:49], v[0:1], v[52:53], v[48:49] op_sel_hi:[1,0,1]
	v_lshl_add_u64 v[52:53], v[150:151], 0, v[138:139]
	global_store_dwordx4 v[52:53], v[48:51], off nt
	s_and_saveexec_b64 s[18:19], s[10:11]
	s_cbranch_execz .LBB0_579
	s_waitcnt lgkmcnt(2)
	v_add_f32_e32 v37, v37, v45
	v_add_f32_e32 v36, v36, v39
	v_mul_f32_e32 v36, v190, v36
	v_mul_f32_e32 v37, v189, v37
	v_fmac_f32_e32 v36, v191, v40
	v_fmac_f32_e32 v37, v195, v40
	v_fmac_f32_e32 v36, 0, v41
	v_fmac_f32_e32 v37, v194, v41
	v_fmac_f32_e32 v36, 0, v42
	v_fmac_f32_e32 v37, 0, v42
	v_fmac_f32_e32 v36, 0, v43
	v_fmac_f32_e32 v37, 0, v43
	s_waitcnt lgkmcnt(0)
	v_add_f32_e32 v44, v44, v47
	v_add_f32_e32 v38, v38, v46
	v_mul_f32_e32 v36, v196, v36
	v_mul_f32_e32 v37, v197, v37
	ds_write2st64_b32 v92, v36, v37 offset0:35 offset1:39
	v_mul_f32_e32 v36, v188, v38
	v_mul_f32_e32 v37, v144, v44
	v_fmac_f32_e32 v36, v200, v40
	v_fmac_f32_e32 v37, v201, v40
	v_fmac_f32_e32 v36, v199, v41
	v_fmac_f32_e32 v37, v205, v41
	v_fmac_f32_e32 v36, v198, v42
	v_fmac_f32_e32 v37, v204, v42
	v_fmac_f32_e32 v36, 0, v43
	v_fmac_f32_e32 v37, v203, v43
	v_mul_f32_e32 v36, v202, v36
	v_mul_f32_e32 v37, v206, v37
	ds_write2st64_b32 v92, v36, v37 offset0:43 offset1:47
.LBB0_579:
	s_or_b64 exec, exec, s[18:19]
	ds_read2st64_b32 v[36:37], v91 offset0:19 offset1:23
	s_waitcnt vmcnt(15)
	v_mul_f32_e32 v33, v9, v33
	v_fmac_f32_e32 v33, v8, v32
	v_mul_f32_e32 v32, v11, v35
	v_fmac_f32_e32 v32, v10, v34
	v_add_f32_e32 v34, v33, v32
	s_waitcnt lgkmcnt(0)
	v_mul_f32_e32 v32, v146, v36
	v_pk_mul_f32 v[28:29], v[28:29], v[32:33] op_sel_hi:[1,0]
	v_mul_f32_e32 v25, v9, v25
	v_pk_fma_f32 v[28:29], v[144:145], v[8:9], v[28:29]
	v_mul_f32_e32 v17, v9, v17
	v_mul_f32_e32 v9, v9, v13
	v_fmac_f32_e32 v25, v8, v24
	v_mul_f32_e32 v24, v11, v27
	v_fmac_f32_e32 v17, v8, v16
	v_mul_f32_e32 v16, v11, v19
	v_fmac_f32_e32 v9, v8, v12
	v_mul_f32_e32 v8, v11, v15
	v_fmac_f32_e32 v24, v10, v26
	v_fmac_f32_e32 v16, v10, v18
	v_fmac_f32_e32 v8, v10, v14
	v_pk_mul_f32 v[30:31], v[30:31], v[32:33] op_sel_hi:[1,0]
	v_mov_b32_e32 v32, v144
	v_mov_b32_e32 v33, v144
	v_add_f32_e32 v25, v25, v24
	v_add_f32_e32 v18, v17, v16
	v_add_f32_e32 v9, v9, v8
	v_pk_fma_f32 v[30:31], v[32:33], v[10:11], v[30:31]
	ds_bpermute_b32 v10, v105, v34
	ds_bpermute_b32 v11, v105, v25
	ds_bpermute_b32 v12, v105, v18
	ds_bpermute_b32 v13, v105, v9
	v_mul_f32_e32 v24, v147, v37
	ds_read2st64_b32 v[16:17], v91 offset0:27 offset1:31
	s_waitcnt lgkmcnt(4)
	v_add_f32_e32 v10, v34, v10
	s_waitcnt lgkmcnt(3)
	v_add_f32_e32 v11, v25, v11
	s_waitcnt lgkmcnt(2)
	v_add_f32_e32 v14, v18, v12
	s_waitcnt lgkmcnt(1)
	v_add_f32_e32 v9, v9, v13
	v_pk_fma_f32 v[22:23], v[22:23], v[24:25], v[30:31] op_sel_hi:[1,0,1]
	v_pk_fma_f32 v[20:21], v[20:21], v[24:25], v[28:29] op_sel_hi:[1,0,1]
	ds_bpermute_b32 v15, v156, v10
	ds_bpermute_b32 v18, v156, v11
	ds_bpermute_b32 v19, v156, v14
	ds_bpermute_b32 v24, v156, v9
	s_waitcnt lgkmcnt(4)
	v_mul_f32_e32 v8, v148, v16
	v_pk_fma_f32 v[12:13], v[4:5], v[8:9], v[20:21] op_sel_hi:[1,0,1]
	s_waitcnt lgkmcnt(3)
	v_add_f32_e32 v4, v10, v15
	s_waitcnt lgkmcnt(2)
	v_add_f32_e32 v5, v11, v18
	s_waitcnt lgkmcnt(1)
	v_add_f32_e32 v10, v14, v19
	s_waitcnt lgkmcnt(0)
	v_add_f32_e32 v9, v9, v24
	ds_bpermute_b32 v11, v157, v4
	ds_bpermute_b32 v18, v157, v5
	ds_bpermute_b32 v19, v157, v10
	ds_bpermute_b32 v20, v157, v9
	v_pk_fma_f32 v[14:15], v[6:7], v[8:9], v[22:23] op_sel_hi:[1,0,1]
	s_waitcnt lgkmcnt(3)
	v_add_f32_e32 v4, v4, v11
	s_waitcnt lgkmcnt(2)
	v_add_f32_e32 v5, v5, v18
	s_waitcnt lgkmcnt(1)
	v_add_f32_e32 v6, v10, v19
	s_waitcnt lgkmcnt(0)
	v_add_f32_e32 v7, v9, v20
	ds_bpermute_b32 v8, v158, v4
	ds_bpermute_b32 v9, v158, v5
	ds_bpermute_b32 v10, v158, v6
	ds_bpermute_b32 v11, v158, v7
	v_mul_f32_e32 v18, v149, v17
	s_waitcnt lgkmcnt(3)
	v_add_f32_e32 v4, v4, v8
	s_waitcnt lgkmcnt(2)
	v_add_f32_e32 v5, v5, v9
	s_waitcnt lgkmcnt(1)
	v_add_f32_e32 v6, v6, v10
	s_waitcnt lgkmcnt(0)
	v_add_f32_e32 v8, v7, v11
	ds_bpermute_b32 v7, v159, v4
	ds_bpermute_b32 v9, v159, v5
	ds_bpermute_b32 v10, v159, v6
	ds_bpermute_b32 v11, v159, v8
	v_pk_fma_f32 v[2:3], v[2:3], v[18:19], v[14:15] op_sel_hi:[1,0,1]
	v_pk_fma_f32 v[0:1], v[0:1], v[18:19], v[12:13] op_sel_hi:[1,0,1]
	v_lshl_add_u64 v[12:13], v[150:151], 0, v[140:141]
	global_store_dwordx4 v[12:13], v[0:3], off nt
	s_and_saveexec_b64 s[18:19], s[10:11]
	s_cbranch_execnz .LBB0_585
	s_or_b64 exec, exec, s[18:19]
	s_and_saveexec_b64 s[18:19], s[12:13]
	s_cbranch_execnz .LBB0_586

.LBB0_589:
	s_lshl_b32 s40, s51, 5
	s_and_b32 s38, s51, 3
	s_and_b32 s28, s40, 0xffffff80
	s_lshl_b32 s39, s38, 6
	v_add_u32_e32 v0, s28, v49
	v_or_b32_e32 v40, s39, v48
	v_ashrrev_i32_e32 v1, 31, v0
	v_lshlrev_b64 v[0:1], 10, v[0:1]
	v_lshlrev_b32_e32 v6, 2, v40
	v_or_b32_e32 v0, v0, v6
	s_waitcnt lgkmcnt(0)
	v_lshl_add_u64 v[2:3], s[24:25], 0, v[0:1]
	v_lshl_add_u64 v[0:1], s[26:27], 0, v[0:1]
	global_load_dwordx4 v[28:31], v[0:1], off nt
	v_add_u32_e32 v0, s28, v50
	v_ashrrev_i32_e32 v1, 31, v0
	v_lshlrev_b64 v[0:1], 10, v[0:1]
	v_or_b32_e32 v0, v0, v6
	global_load_dwordx4 v[24:27], v[2:3], off nt
	v_lshl_add_u64 v[2:3], s[24:25], 0, v[0:1]
	v_lshl_add_u64 v[0:1], s[26:27], 0, v[0:1]
	global_load_dwordx4 v[20:23], v[0:1], off nt
	v_add_u32_e32 v0, s28, v51
	v_ashrrev_i32_e32 v1, 31, v0
	v_lshlrev_b64 v[0:1], 10, v[0:1]
	v_or_b32_e32 v0, v0, v6
	global_load_dwordx4 v[16:19], v[2:3], off nt
	v_lshl_add_u64 v[2:3], s[24:25], 0, v[0:1]
	v_lshl_add_u64 v[0:1], s[26:27], 0, v[0:1]
	global_load_dwordx4 v[12:15], v[0:1], off nt
	v_add_u32_e32 v0, s28, v52
	v_ashrrev_i32_e32 v1, 31, v0
	v_lshlrev_b64 v[4:5], 10, v[0:1]
	v_or_b32_e32 v4, v4, v6
	v_lshl_add_u64 v[0:1], s[24:25], 0, v[4:5]
	v_lshl_add_u64 v[4:5], s[26:27], 0, v[4:5]
	global_load_dwordx4 v[8:11], v[2:3], off nt
	s_add_i32 s28, s28, -4
	global_load_dwordx4 v[0:3], v[0:1], off nt
	s_nop 0
	global_load_dwordx4 v[4:7], v[4:5], off nt
	s_waitcnt vmcnt(6)
	ds_write_b128 v32, v[24:27]
	ds_write_b128 v32, v[28:31] offset:35904
	s_and_saveexec_b64 s[36:37], s[8:9]
	s_cbranch_execz .LBB0_591
	v_add_u32_e32 v62, s28, v49
	v_ashrrev_i32_e32 v63, 31, v62
	v_lshlrev_b64 v[62:63], 10, v[62:63]
	v_lshl_or_b32 v62, v40, 2, v62
	v_lshl_add_u64 v[64:65], s[30:31], 0, v[62:63]
	global_store_dwordx4 v[64:65], v[24:27], off nt
	s_nop 1
	v_lshl_add_u64 v[24:25], s[34:35], 0, v[62:63]
	global_store_dwordx4 v[24:25], v[28:31], off nt
.LBB0_591:
	s_or_b64 exec, exec, s[36:37]
	s_waitcnt vmcnt(4)
	ds_write_b128 v34, v[16:19]
	ds_write_b128 v34, v[20:23] offset:35904
	s_and_saveexec_b64 s[36:37], s[10:11]
	s_cbranch_execz .LBB0_593
	v_add_u32_e32 v24, s28, v50
	v_ashrrev_i32_e32 v25, 31, v24
	v_lshlrev_b64 v[24:25], 10, v[24:25]
	v_lshl_or_b32 v24, v40, 2, v24
	v_lshl_add_u64 v[26:27], s[30:31], 0, v[24:25]
	global_store_dwordx4 v[26:27], v[16:19], off nt
	s_nop 1
	v_lshl_add_u64 v[16:17], s[34:35], 0, v[24:25]
	global_store_dwordx4 v[16:17], v[20:23], off nt
.LBB0_593:
	s_or_b64 exec, exec, s[36:37]
	s_waitcnt vmcnt(2)
	ds_write_b128 v36, v[8:11]
	ds_write_b128 v36, v[12:15] offset:35904
	s_and_saveexec_b64 s[36:37], s[12:13]
	s_cbranch_execz .LBB0_595
	v_add_u32_e32 v16, s28, v51
	v_ashrrev_i32_e32 v17, 31, v16
	v_lshlrev_b64 v[16:17], 10, v[16:17]
	v_lshl_or_b32 v16, v40, 2, v16
	v_lshl_add_u64 v[18:19], s[30:31], 0, v[16:17]
	global_store_dwordx4 v[18:19], v[8:11], off nt
	s_nop 1
	v_lshl_add_u64 v[8:9], s[34:35], 0, v[16:17]
	global_store_dwordx4 v[8:9], v[12:15], off nt
.LBB0_595:
	s_or_b64 exec, exec, s[36:37]
	s_waitcnt vmcnt(1)
	ds_write_b128 v38, v[0:3]
	s_waitcnt vmcnt(0)
	ds_write_b128 v38, v[4:7] offset:35904
	s_and_saveexec_b64 s[36:37], s[14:15]
	s_cbranch_execz .LBB0_597
	v_add_u32_e32 v8, s28, v52
	v_ashrrev_i32_e32 v9, 31, v8
	v_lshlrev_b64 v[8:9], 10, v[8:9]
	v_lshl_or_b32 v8, v40, 2, v8
	v_lshl_add_u64 v[10:11], s[30:31], 0, v[8:9]
	global_store_dwordx4 v[10:11], v[0:3], off nt
	s_nop 1
	v_lshl_add_u64 v[0:1], s[34:35], 0, v[8:9]
	global_store_dwordx4 v[0:1], v[4:7], off nt
